# new SwiGLU epilogue (6 VALU/output, interleaved, no hazard pads) + accumulator zeroing removed by peeling k-tile 0 with SrcC=0 in 6 GEMM loops
# speedup vs baseline: 1.0205x; 1.0070x over previous
; #define PG8_STAGE(bufoff, gbase, voff) do { _Pragma("unroll") for (int _i = 0; _i < 2; ++_i) \
;         __builtin_amdgcn_global_load_lds((const unsigned*)((const char*)(gbase) + (voff)[_i]), (PG8_LAS unsigned*)(lds + (bufoff) + ldsw + _i * 8192), 16, 0, 0); } while (0)
; #define PG8_LDA(dst, b, h) do { _Pragma("unroll") for (int m = 0; m < 4; ++m) _Pragma("unroll") for (int k = 0; k < 2; ++k) dst[m][k] = *(const PG8_LAS bf16x8*)(lds + PG8_SA(b, h) + aoff + m * 2048 + k * 1024); } while (0)
; #define PG8_LDB(dst, b, h) do { _Pragma("unroll") for (int n = 0; n < 2; ++n) _Pragma("unroll") for (int k = 0; k < 2; ++k) dst[n][k] = *(const PG8_LAS bf16x8*)(lds + PG8_SB(b, h) + boff + n * 2048 + k * 1024); } while (0)
; #define PG8_MMA(ai, bj, At, Bt) do { __builtin_amdgcn_s_setprio(1); _Pragma("unroll") for (int m = 0; m < 4; ++m) _Pragma("unroll") for (int n = 0; n < 2; ++n) _Pragma("unroll") for (int k = 0; k < 2; ++k) \
;         acc[ai][bj][m][n] = __builtin_amdgcn_mfma_f32_16x16x32_bf16(Bt[n][k], At[m][k], acc[ai][bj][m][n], 0, 0, 0); __builtin_amdgcn_s_setprio(0); } while (0)
; #define PG8_WAIT_V(n) asm volatile("s_waitcnt vmcnt(" #n ")" ::: "memory")
; #define PG8_WAIT_L(n) asm volatile("s_waitcnt lgkmcnt(" #n ")" ::: "memory")
; #define PG8_BAR __builtin_amdgcn_s_barrier()
; #define PG8_SCHED __builtin_amdgcn_sched_barrier(0)
; template <class Epi, class Sched>
; __device__ __forceinline__ void gemm_phase(PG8_LAS unsigned char* lds, const Gemm g, const Sched& S, const Epi& E) {
;     ...
;             const bool last = (t == nt - 2);
;             const char* a1 = cA + (size_t)(t + 1) * kstep;
;             const char* a2 = last ? nA : cA + (size_t)(t + 2) * kstep; const char* b2 = last ? nB : cB + (size_t)(t + 2) * kstep;
;             const char* a3 = a2 + kstep; const char* b3 = b2 + kstep;
;             PG8_LDB(B0, 0, 0); PG8_LDB(B1, 0, 1); PG8_SCHED; PG8_LDA(At, 0, 0); PG8_STAGE(PG8_SA(1, 1), a1 + hstepA, voffA);
;             PG8_WAIT_V(8); PG8_WAIT_L(0); PG8_BAR; PG8_MMA(0, 0, At, B0); PG8_MMA(0, 1, At, B1); PG8_BAR; PG8_SCHED;
.LBB0_161:
	s_ashr_i32 s17, s16, 31
	s_lshl_b64 s[18:19], s[16:17], 19
	s_add_u32 s18, s36, s18
	s_addc_u32 s19, s37, s19
	s_and_b64 s[20:21], s[4:5], exec
	s_cselect_b32 s33, s19, s23
	s_cselect_b32 s61, s18, s22
	s_ashr_i32 s15, s14, 31
	s_lshl_b64 s[20:21], s[14:15], 19
	v_readlane_b32 s15, v254, 56
	s_add_u32 s20, s15, s20
	v_readlane_b32 s15, v254, 57
	s_addc_u32 s21, s15, s21
	s_and_b64 s[26:27], s[4:5], exec
	s_cselect_b32 s15, s21, s25
	s_cselect_b32 s70, s20, s24
	s_add_u32 s22, s22, 0x40080
	s_addc_u32 s23, s23, 0
	s_add_u32 s71, s24, 0x100
	v_mov_b32_e32 v2, 0
	s_addc_u32 s75, s25, 0
	s_mov_b32 s64, -2
	s_waitcnt vmcnt(0)
	s_add_u32 s24, s22, 0xfffc0080
	s_addc_u32 s25, s23, -1
	s_add_i32 s65, 0, 0x10000
	s_cmp_eq_u32 s64, 12
	s_cselect_b32 s27, s33, s25
	s_cselect_b32 s26, s61, s24
	v_add_u32_e32 v151, s65, v166
	s_cselect_b32 s25, s15, s75
	s_cselect_b32 s24, s70, s71
	s_add_i32 s74, 0, 0x14000
	ds_read_b128 v[122:125], v151
	s_waitcnt lgkmcnt(0)
	ds_read_b128 v[152:155], v151 offset:1024
	ds_read_b128 v[156:159], v151 offset:2048
	ds_read_b128 v[160:163], v151 offset:3072
	v_add_u32_e32 v151, s74, v166
	ds_read_b128 v[172:175], v151
	ds_read_b128 v[176:179], v151 offset:1024
	ds_read_b128 v[180:183], v151 offset:2048
	ds_read_b128 v[184:187], v151 offset:3072
	v_lshl_add_u64 v[164:165], s[22:23], 0, v[146:147]
	s_add_i32 m0, s29, 0xc000
	ds_read_b128 v[188:191], v171
	ds_read_b128 v[192:195], v171 offset:1024
	ds_read_b128 v[196:199], v171 offset:2048
	ds_read_b128 v[200:203], v171 offset:3072
	ds_read_b128 v[204:207], v171 offset:4096
	ds_read_b128 v[214:217], v171 offset:5120
	ds_read_b128 v[218:221], v171 offset:6144
	ds_read_b128 v[222:225], v171 offset:7168
	global_load_lds_dwordx4 v[164:165], off
	v_lshl_add_u64 v[164:165], s[22:23], 0, v[148:149]
	s_add_i32 m0, s29, 0xe000
	s_nop 0
	global_load_lds_dwordx4 v[164:165], off
	s_waitcnt vmcnt(8)
	s_waitcnt lgkmcnt(0)
	s_barrier
	s_setprio 1
	s_waitcnt lgkmcnt(0)
	v_mfma_f32_16x16x32_bf16 v[130:133], v[122:125], v[188:191], 0
	v_mfma_f32_16x16x32_bf16 v[126:129], v[156:159], v[188:191], 0
	v_mfma_f32_16x16x32_bf16 v[110:113], v[122:125], v[196:199], 0
	v_mfma_f32_16x16x32_bf16 v[106:109], v[156:159], v[196:199], 0
	v_mfma_f32_16x16x32_bf16 v[94:97], v[122:125], v[204:207], 0
	v_mfma_f32_16x16x32_bf16 v[90:93], v[156:159], v[204:207], 0
	v_mfma_f32_16x16x32_bf16 v[78:81], v[122:125], v[218:221], 0
	v_mfma_f32_16x16x32_bf16 v[74:77], v[156:159], v[218:221], 0
	v_mfma_f32_16x16x32_bf16 v[130:133], v[152:155], v[192:195], v[130:133]
	v_mfma_f32_16x16x32_bf16 v[126:129], v[160:163], v[192:195], v[126:129]
	v_mfma_f32_16x16x32_bf16 v[110:113], v[152:155], v[200:203], v[110:113]
	v_mfma_f32_16x16x32_bf16 v[106:109], v[160:163], v[200:203], v[106:109]
	v_mfma_f32_16x16x32_bf16 v[94:97], v[152:155], v[214:217], v[94:97]
	v_mfma_f32_16x16x32_bf16 v[90:93], v[160:163], v[214:217], v[90:93]
	v_mfma_f32_16x16x32_bf16 v[78:81], v[152:155], v[222:225], v[78:81]
	v_mfma_f32_16x16x32_bf16 v[74:77], v[160:163], v[222:225], v[74:77]
	s_setprio 0
	s_setprio 1
	v_mfma_f32_16x16x32_bf16 v[118:121], v[172:175], v[188:191], 0
	v_mfma_f32_16x16x32_bf16 v[114:117], v[180:183], v[188:191], 0
	v_mfma_f32_16x16x32_bf16 v[102:105], v[172:175], v[196:199], 0
	v_mfma_f32_16x16x32_bf16 v[98:101], v[180:183], v[196:199], 0
	v_mfma_f32_16x16x32_bf16 v[86:89], v[172:175], v[204:207], 0
	v_mfma_f32_16x16x32_bf16 v[82:85], v[180:183], v[204:207], 0
	v_mfma_f32_16x16x32_bf16 v[70:73], v[172:175], v[218:221], 0
	v_mfma_f32_16x16x32_bf16 v[66:69], v[180:183], v[218:221], 0
	v_mfma_f32_16x16x32_bf16 v[118:121], v[176:179], v[192:195], v[118:121]
	v_mfma_f32_16x16x32_bf16 v[114:117], v[184:187], v[192:195], v[114:117]
	v_mfma_f32_16x16x32_bf16 v[102:105], v[176:179], v[200:203], v[102:105]
	v_mfma_f32_16x16x32_bf16 v[98:101], v[184:187], v[200:203], v[98:101]
	v_mfma_f32_16x16x32_bf16 v[86:89], v[176:179], v[214:217], v[86:89]
	v_mfma_f32_16x16x32_bf16 v[82:85], v[184:187], v[214:217], v[82:85]
	v_mfma_f32_16x16x32_bf16 v[70:73], v[176:179], v[222:225], v[70:73]
	v_mfma_f32_16x16x32_bf16 v[66:69], v[184:187], v[222:225], v[66:69]
	s_setprio 0
	s_barrier
; #define PG8_STAGE(bufoff, gbase, voff) do { _Pragma("unroll") for (int _i = 0; _i < 2; ++_i) \
;         __builtin_amdgcn_global_load_lds((const unsigned*)((const char*)(gbase) + (voff)[_i]), (PG8_LAS unsigned*)(lds + (bufoff) + ldsw + _i * 8192), 16, 0, 0); } while (0)
; #define PG8_LDA(dst, b, h) do { _Pragma("unroll") for (int m = 0; m < 4; ++m) _Pragma("unroll") for (int k = 0; k < 2; ++k) dst[m][k] = *(const PG8_LAS bf16x8*)(lds + PG8_SA(b, h) + aoff + m * 2048 + k * 1024); } while (0)
; #define PG8_MMA(ai, bj, At, Bt) do { __builtin_amdgcn_s_setprio(1); _Pragma("unroll") for (int m = 0; m < 4; ++m) _Pragma("unroll") for (int n = 0; n < 2; ++n) _Pragma("unroll") for (int k = 0; k < 2; ++k) \
;         acc[ai][bj][m][n] = __builtin_amdgcn_mfma_f32_16x16x32_bf16(Bt[n][k], At[m][k], acc[ai][bj][m][n], 0, 0, 0); __builtin_amdgcn_s_setprio(0); } while (0)
; #define PG8_WAIT_V(n) asm volatile("s_waitcnt vmcnt(" #n ")" ::: "memory")
; #define PG8_WAIT_L(n) asm volatile("s_waitcnt lgkmcnt(" #n ")" ::: "memory")
; #define PG8_BAR __builtin_amdgcn_s_barrier()
; #define PG8_SCHED __builtin_amdgcn_sched_barrier(0)
; template <class Epi, class Sched>
; __device__ __forceinline__ void gemm_phase(PG8_LAS unsigned char* lds, const Gemm g, const Sched& S, const Epi& E) {
;     ...
;             PG8_LDA(At, 0, 1); PG8_STAGE(PG8_SB(0, 0), b2, voffB); PG8_STAGE(PG8_SB(0, 1), b2 + hstepB, voffB); PG8_STAGE(PG8_SA(0, 0), a2, voffA);
;             PG8_WAIT_V(8); PG8_WAIT_L(0); PG8_BAR; PG8_MMA(1, 0, At, B0); PG8_MMA(1, 1, At, B1); PG8_BAR; PG8_SCHED;
	s_add_i32 s65, s65, s28
	v_lshl_add_u64 v[164:165], s[24:25], 0, v[136:137]
	s_mov_b32 m0, s65
	ds_read_b128 v[188:191], v171 offset:16384
	ds_read_b128 v[192:195], v171 offset:17408
	ds_read_b128 v[196:199], v171 offset:18432
	ds_read_b128 v[200:203], v171 offset:19456
	ds_read_b128 v[204:207], v171 offset:20480
	ds_read_b128 v[214:217], v171 offset:21504
	ds_read_b128 v[218:221], v171 offset:22528
	ds_read_b128 v[222:225], v171 offset:23552
	global_load_lds_dwordx4 v[164:165], off
	s_add_i32 m0, s65, 0x2000
	s_add_u32 s66, s24, 0x40000
	v_lshl_add_u64 v[208:209], s[24:25], 0, v[140:141]
	s_addc_u32 s67, s25, 0
	s_add_i32 s65, s74, s28
	global_load_lds_dwordx4 v[208:209], off
	v_lshl_add_u64 v[210:211], s[66:67], 0, v[136:137]
	s_mov_b32 m0, s65
	v_lshl_add_u64 v[226:227], s[26:27], 0, v[138:139]
	global_load_lds_dwordx4 v[210:211], off
	v_lshl_add_u64 v[210:211], s[66:67], 0, v[140:141]
	s_add_i32 m0, s65, 0x2000
	s_nop 0
	global_load_lds_dwordx4 v[210:211], off
	v_lshl_add_u64 v[210:211], s[26:27], 0, v[134:135]
	s_mov_b32 m0, s29
	s_nop 0
	global_load_lds_dwordx4 v[210:211], off
	s_mov_b32 m0, s30
	s_nop 0
	global_load_lds_dwordx4 v[226:227], off
	s_waitcnt vmcnt(8)
	s_waitcnt lgkmcnt(0)
	s_barrier
	s_setprio 1
	s_waitcnt lgkmcnt(0)
	v_mfma_f32_16x16x32_bf16 v[62:65], v[122:125], v[188:191], 0
	v_mfma_f32_16x16x32_bf16 v[58:61], v[156:159], v[188:191], 0
	v_mfma_f32_16x16x32_bf16 v[46:49], v[122:125], v[196:199], 0
	v_mfma_f32_16x16x32_bf16 v[42:45], v[156:159], v[196:199], 0
	v_mfma_f32_16x16x32_bf16 v[30:33], v[122:125], v[204:207], 0
	v_mfma_f32_16x16x32_bf16 v[26:29], v[156:159], v[204:207], 0
	v_mfma_f32_16x16x32_bf16 v[14:17], v[122:125], v[218:221], 0
	v_mfma_f32_16x16x32_bf16 v[10:13], v[156:159], v[218:221], 0
	v_mfma_f32_16x16x32_bf16 v[62:65], v[152:155], v[192:195], v[62:65]
	v_mfma_f32_16x16x32_bf16 v[58:61], v[160:163], v[192:195], v[58:61]
	v_mfma_f32_16x16x32_bf16 v[46:49], v[152:155], v[200:203], v[46:49]
	v_mfma_f32_16x16x32_bf16 v[42:45], v[160:163], v[200:203], v[42:45]
	v_mfma_f32_16x16x32_bf16 v[30:33], v[152:155], v[214:217], v[30:33]
	v_mfma_f32_16x16x32_bf16 v[26:29], v[160:163], v[214:217], v[26:29]
	v_mfma_f32_16x16x32_bf16 v[14:17], v[152:155], v[222:225], v[14:17]
	v_mfma_f32_16x16x32_bf16 v[10:13], v[160:163], v[222:225], v[10:13]
	s_setprio 0
	s_setprio 1
	v_mfma_f32_16x16x32_bf16 v[54:57], v[172:175], v[188:191], 0
	v_mfma_f32_16x16x32_bf16 v[50:53], v[180:183], v[188:191], 0
	v_mfma_f32_16x16x32_bf16 v[38:41], v[172:175], v[196:199], 0
	v_mfma_f32_16x16x32_bf16 v[34:37], v[180:183], v[196:199], 0
	v_mfma_f32_16x16x32_bf16 v[22:25], v[172:175], v[204:207], 0
	v_mfma_f32_16x16x32_bf16 v[18:21], v[180:183], v[204:207], 0
	v_mfma_f32_16x16x32_bf16 v[6:9], v[172:175], v[218:221], 0
	v_mfma_f32_16x16x32_bf16 v[2:5], v[180:183], v[218:221], 0
	v_mfma_f32_16x16x32_bf16 v[54:57], v[176:179], v[192:195], v[54:57]
	v_mfma_f32_16x16x32_bf16 v[50:53], v[184:187], v[192:195], v[50:53]
	v_mfma_f32_16x16x32_bf16 v[38:41], v[176:179], v[200:203], v[38:41]
	v_mfma_f32_16x16x32_bf16 v[34:37], v[184:187], v[200:203], v[34:37]
	v_mfma_f32_16x16x32_bf16 v[22:25], v[176:179], v[214:217], v[22:25]
	v_mfma_f32_16x16x32_bf16 v[18:21], v[184:187], v[214:217], v[18:21]
	v_mfma_f32_16x16x32_bf16 v[6:9], v[176:179], v[222:225], v[6:9]
	v_mfma_f32_16x16x32_bf16 v[2:5], v[184:187], v[222:225], v[2:5]
	s_setprio 0
	s_barrier
	s_branch .Lpeel_mid_162

; #define PG8_STAGE(bufoff, gbase, voff) do { _Pragma("unroll") for (int _i = 0; _i < 2; ++_i) \
;         __builtin_amdgcn_global_load_lds((const unsigned*)((const char*)(gbase) + (voff)[_i]), (PG8_LAS unsigned*)(lds + (bufoff) + ldsw + _i * 8192), 16, 0, 0); } while (0)
; #define PG8_LDA(dst, b, h) do { _Pragma("unroll") for (int m = 0; m < 4; ++m) _Pragma("unroll") for (int k = 0; k < 2; ++k) dst[m][k] = *(const PG8_LAS bf16x8*)(lds + PG8_SA(b, h) + aoff + m * 2048 + k * 1024); } while (0)
; #define PG8_LDB(dst, b, h) do { _Pragma("unroll") for (int n = 0; n < 2; ++n) _Pragma("unroll") for (int k = 0; k < 2; ++k) dst[n][k] = *(const PG8_LAS bf16x8*)(lds + PG8_SB(b, h) + boff + n * 2048 + k * 1024); } while (0)
; #define PG8_MMA(ai, bj, At, Bt) do { __builtin_amdgcn_s_setprio(1); _Pragma("unroll") for (int m = 0; m < 4; ++m) _Pragma("unroll") for (int n = 0; n < 2; ++n) _Pragma("unroll") for (int k = 0; k < 2; ++k) \
;         acc[ai][bj][m][n] = __builtin_amdgcn_mfma_f32_16x16x32_bf16(Bt[n][k], At[m][k], acc[ai][bj][m][n], 0, 0, 0); __builtin_amdgcn_s_setprio(0); } while (0)
; #define PG8_WAIT_V(n) asm volatile("s_waitcnt vmcnt(" #n ")" ::: "memory")
; #define PG8_WAIT_L(n) asm volatile("s_waitcnt lgkmcnt(" #n ")" ::: "memory")
; #define PG8_BAR __builtin_amdgcn_s_barrier()
; #define PG8_SCHED __builtin_amdgcn_sched_barrier(0)
; template <class Epi, class Sched>
; __device__ __forceinline__ void gemm_phase(PG8_LAS unsigned char* lds, const Gemm g, const Sched& S, const Epi& E) {
;     ...
;             PG8_LDB(B0, 1, 0); PG8_LDB(B1, 1, 1); PG8_SCHED; PG8_LDA(At, 1, 0); PG8_STAGE(PG8_SA(0, 1), a2 + hstepA, voffA);
;             PG8_WAIT_V(8); PG8_WAIT_L(0); PG8_BAR; PG8_MMA(0, 0, At, B0); PG8_MMA(0, 1, At, B1); PG8_BAR; PG8_SCHED;
.Lpeel_mid_162:
	s_add_i32 s65, 0, 0x18000
	v_add_u32_e32 v151, s65, v166
	s_add_i32 s66, 0, 0x1c000
	ds_read_b128 v[122:125], v151
	ds_read_b128 v[152:155], v151 offset:1024
	ds_read_b128 v[156:159], v151 offset:2048
	ds_read_b128 v[160:163], v151 offset:3072
	v_add_u32_e32 v151, s66, v166
	ds_read_b128 v[172:175], v151
	ds_read_b128 v[176:179], v151 offset:1024
	ds_read_b128 v[180:183], v151 offset:2048
	ds_read_b128 v[184:187], v151 offset:3072
	s_add_u32 s26, s26, 0x40000
	s_addc_u32 s27, s27, 0
	s_mov_b32 m0, s31
	v_lshl_add_u64 v[228:229], s[26:27], 0, v[134:135]
	ds_read_b128 v[188:191], v171 offset:32768
	ds_read_b128 v[192:195], v171 offset:33792
	ds_read_b128 v[196:199], v171 offset:34816
	ds_read_b128 v[200:203], v171 offset:35840
	ds_read_b128 v[204:207], v171 offset:36864
	ds_read_b128 v[214:217], v171 offset:37888
	ds_read_b128 v[218:221], v171 offset:38912
	ds_read_b128 v[222:225], v171 offset:39936
	global_load_lds_dwordx4 v[228:229], off
	v_lshl_add_u64 v[228:229], s[26:27], 0, v[138:139]
	s_mov_b32 m0, s46
	s_nop 0
	global_load_lds_dwordx4 v[228:229], off
	s_waitcnt vmcnt(8)
	s_waitcnt lgkmcnt(0)
	s_barrier
	s_setprio 1
	s_waitcnt lgkmcnt(0)
	v_mfma_f32_16x16x32_bf16 v[130:133], v[122:125], v[188:191], v[130:133]
	v_mfma_f32_16x16x32_bf16 v[126:129], v[156:159], v[188:191], v[126:129]
	v_mfma_f32_16x16x32_bf16 v[110:113], v[122:125], v[196:199], v[110:113]
	v_mfma_f32_16x16x32_bf16 v[106:109], v[156:159], v[196:199], v[106:109]
	v_mfma_f32_16x16x32_bf16 v[94:97], v[122:125], v[204:207], v[94:97]
	v_mfma_f32_16x16x32_bf16 v[90:93], v[156:159], v[204:207], v[90:93]
	v_mfma_f32_16x16x32_bf16 v[78:81], v[122:125], v[218:221], v[78:81]
	v_mfma_f32_16x16x32_bf16 v[74:77], v[156:159], v[218:221], v[74:77]
	v_mfma_f32_16x16x32_bf16 v[130:133], v[152:155], v[192:195], v[130:133]
	v_mfma_f32_16x16x32_bf16 v[126:129], v[160:163], v[192:195], v[126:129]
	v_mfma_f32_16x16x32_bf16 v[110:113], v[152:155], v[200:203], v[110:113]
	v_mfma_f32_16x16x32_bf16 v[106:109], v[160:163], v[200:203], v[106:109]
	v_mfma_f32_16x16x32_bf16 v[94:97], v[152:155], v[214:217], v[94:97]
	v_mfma_f32_16x16x32_bf16 v[90:93], v[160:163], v[214:217], v[90:93]
	v_mfma_f32_16x16x32_bf16 v[78:81], v[152:155], v[222:225], v[78:81]
	v_mfma_f32_16x16x32_bf16 v[74:77], v[160:163], v[222:225], v[74:77]
	s_setprio 0
	s_setprio 1
	v_mfma_f32_16x16x32_bf16 v[118:121], v[172:175], v[188:191], v[118:121]
	v_mfma_f32_16x16x32_bf16 v[114:117], v[180:183], v[188:191], v[114:117]
	v_mfma_f32_16x16x32_bf16 v[102:105], v[172:175], v[196:199], v[102:105]
	v_mfma_f32_16x16x32_bf16 v[98:101], v[180:183], v[196:199], v[98:101]
	v_mfma_f32_16x16x32_bf16 v[86:89], v[172:175], v[204:207], v[86:89]
	v_mfma_f32_16x16x32_bf16 v[82:85], v[180:183], v[204:207], v[82:85]
	v_mfma_f32_16x16x32_bf16 v[70:73], v[172:175], v[218:221], v[70:73]
	v_mfma_f32_16x16x32_bf16 v[66:69], v[180:183], v[218:221], v[66:69]
	v_mfma_f32_16x16x32_bf16 v[118:121], v[176:179], v[192:195], v[118:121]
	v_mfma_f32_16x16x32_bf16 v[114:117], v[184:187], v[192:195], v[114:117]
	v_mfma_f32_16x16x32_bf16 v[102:105], v[176:179], v[200:203], v[102:105]
	v_mfma_f32_16x16x32_bf16 v[98:101], v[184:187], v[200:203], v[98:101]
	v_mfma_f32_16x16x32_bf16 v[86:89], v[176:179], v[214:217], v[86:89]
	v_mfma_f32_16x16x32_bf16 v[82:85], v[184:187], v[214:217], v[82:85]
	v_mfma_f32_16x16x32_bf16 v[70:73], v[176:179], v[222:225], v[70:73]
	v_mfma_f32_16x16x32_bf16 v[66:69], v[184:187], v[222:225], v[66:69]
	s_setprio 0
	s_barrier
; #define PG8_STAGE(bufoff, gbase, voff) do { _Pragma("unroll") for (int _i = 0; _i < 2; ++_i) \
;         __builtin_amdgcn_global_load_lds((const unsigned*)((const char*)(gbase) + (voff)[_i]), (PG8_LAS unsigned*)(lds + (bufoff) + ldsw + _i * 8192), 16, 0, 0); } while (0)
; #define PG8_LDA(dst, b, h) do { _Pragma("unroll") for (int m = 0; m < 4; ++m) _Pragma("unroll") for (int k = 0; k < 2; ++k) dst[m][k] = *(const PG8_LAS bf16x8*)(lds + PG8_SA(b, h) + aoff + m * 2048 + k * 1024); } while (0)
; #define PG8_MMA(ai, bj, At, Bt) do { __builtin_amdgcn_s_setprio(1); _Pragma("unroll") for (int m = 0; m < 4; ++m) _Pragma("unroll") for (int n = 0; n < 2; ++n) _Pragma("unroll") for (int k = 0; k < 2; ++k) \
;         acc[ai][bj][m][n] = __builtin_amdgcn_mfma_f32_16x16x32_bf16(Bt[n][k], At[m][k], acc[ai][bj][m][n], 0, 0, 0); __builtin_amdgcn_s_setprio(0); } while (0)
; #define PG8_WAIT_V(n) asm volatile("s_waitcnt vmcnt(" #n ")" ::: "memory")
; #define PG8_WAIT_L(n) asm volatile("s_waitcnt lgkmcnt(" #n ")" ::: "memory")
; #define PG8_BAR __builtin_amdgcn_s_barrier()
; #define PG8_SCHED __builtin_amdgcn_sched_barrier(0)
; template <class Epi, class Sched>
; __device__ __forceinline__ void gemm_phase(PG8_LAS unsigned char* lds, const Gemm g, const Sched& S, const Epi& E) {
;     ...
;             PG8_LDA(At, 1, 1); PG8_STAGE(PG8_SB(1, 0), b3, voffB); PG8_STAGE(PG8_SB(1, 1), b3 + hstepB, voffB); PG8_STAGE(PG8_SA(1, 0), a3, voffA);
;             PG8_WAIT_V(8); PG8_WAIT_L(0); PG8_BAR; PG8_MMA(1, 0, At, B0); PG8_MMA(1, 1, At, B1); PG8_BAR; PG8_SCHED;
;         }
	s_add_i32 s26, s65, s28
	v_lshl_add_u64 v[164:165], v[164:165], 0, s[78:79]
	s_mov_b32 m0, s26
	ds_read_b128 v[188:191], v171 offset:49152
	ds_read_b128 v[192:195], v171 offset:50176
	ds_read_b128 v[196:199], v171 offset:51200
	ds_read_b128 v[200:203], v171 offset:52224
	ds_read_b128 v[204:207], v171 offset:53248
	ds_read_b128 v[214:217], v171 offset:54272
	ds_read_b128 v[218:221], v171 offset:55296
	ds_read_b128 v[222:225], v171 offset:56320
	global_load_lds_dwordx4 v[164:165], off
	s_add_i32 m0, s26, 0x2000
	s_add_u32 s24, s24, 0x40080
	v_lshl_add_u64 v[164:165], v[208:209], 0, s[78:79]
	s_addc_u32 s25, s25, 0
	s_add_i32 s26, s66, s28
	global_load_lds_dwordx4 v[164:165], off
	v_lshl_add_u64 v[164:165], s[24:25], 0, v[136:137]
	s_mov_b32 m0, s26
	s_nop 0
	global_load_lds_dwordx4 v[164:165], off
	v_lshl_add_u64 v[164:165], s[24:25], 0, v[140:141]
	s_add_i32 m0, s26, 0x2000
	s_nop 0
	global_load_lds_dwordx4 v[164:165], off
	v_lshl_add_u64 v[164:165], v[210:211], 0, s[78:79]
	s_mov_b32 m0, s48
	s_nop 0
	global_load_lds_dwordx4 v[164:165], off
	v_lshl_add_u64 v[164:165], v[226:227], 0, s[78:79]
	s_mov_b32 m0, s49
	s_nop 0
	global_load_lds_dwordx4 v[164:165], off
	s_waitcnt vmcnt(8)
	s_waitcnt lgkmcnt(0)
	s_barrier
	s_setprio 1
	s_waitcnt lgkmcnt(0)
	v_mfma_f32_16x16x32_bf16 v[62:65], v[122:125], v[188:191], v[62:65]
	v_mfma_f32_16x16x32_bf16 v[58:61], v[156:159], v[188:191], v[58:61]
	v_mfma_f32_16x16x32_bf16 v[46:49], v[122:125], v[196:199], v[46:49]
	v_mfma_f32_16x16x32_bf16 v[42:45], v[156:159], v[196:199], v[42:45]
	v_mfma_f32_16x16x32_bf16 v[30:33], v[122:125], v[204:207], v[30:33]
	v_mfma_f32_16x16x32_bf16 v[26:29], v[156:159], v[204:207], v[26:29]
	v_mfma_f32_16x16x32_bf16 v[14:17], v[122:125], v[218:221], v[14:17]
	v_mfma_f32_16x16x32_bf16 v[10:13], v[156:159], v[218:221], v[10:13]
	v_mfma_f32_16x16x32_bf16 v[62:65], v[152:155], v[192:195], v[62:65]
	v_mfma_f32_16x16x32_bf16 v[58:61], v[160:163], v[192:195], v[58:61]
	v_mfma_f32_16x16x32_bf16 v[46:49], v[152:155], v[200:203], v[46:49]
	v_mfma_f32_16x16x32_bf16 v[42:45], v[160:163], v[200:203], v[42:45]
	v_mfma_f32_16x16x32_bf16 v[30:33], v[152:155], v[214:217], v[30:33]
	v_mfma_f32_16x16x32_bf16 v[26:29], v[160:163], v[214:217], v[26:29]
	v_mfma_f32_16x16x32_bf16 v[14:17], v[152:155], v[222:225], v[14:17]
	v_mfma_f32_16x16x32_bf16 v[10:13], v[160:163], v[222:225], v[10:13]
	s_setprio 0
	s_setprio 1
	v_mfma_f32_16x16x32_bf16 v[54:57], v[172:175], v[188:191], v[54:57]
	v_mfma_f32_16x16x32_bf16 v[50:53], v[180:183], v[188:191], v[50:53]
	v_mfma_f32_16x16x32_bf16 v[38:41], v[172:175], v[196:199], v[38:41]
	v_mfma_f32_16x16x32_bf16 v[34:37], v[180:183], v[196:199], v[34:37]
	v_mfma_f32_16x16x32_bf16 v[22:25], v[172:175], v[204:207], v[22:25]
	v_mfma_f32_16x16x32_bf16 v[18:21], v[180:183], v[204:207], v[18:21]
	v_mfma_f32_16x16x32_bf16 v[6:9], v[172:175], v[218:221], v[6:9]
	v_mfma_f32_16x16x32_bf16 v[2:5], v[180:183], v[218:221], v[2:5]
	v_mfma_f32_16x16x32_bf16 v[54:57], v[176:179], v[192:195], v[54:57]
	v_mfma_f32_16x16x32_bf16 v[50:53], v[184:187], v[192:195], v[50:53]
	v_mfma_f32_16x16x32_bf16 v[38:41], v[176:179], v[200:203], v[38:41]
	v_mfma_f32_16x16x32_bf16 v[34:37], v[184:187], v[200:203], v[34:37]
	v_mfma_f32_16x16x32_bf16 v[22:25], v[176:179], v[214:217], v[22:25]
	v_mfma_f32_16x16x32_bf16 v[18:21], v[184:187], v[214:217], v[18:21]
	v_mfma_f32_16x16x32_bf16 v[6:9], v[176:179], v[222:225], v[6:9]
	v_mfma_f32_16x16x32_bf16 v[2:5], v[184:187], v[222:225], v[2:5]
	s_setprio 0
	s_barrier
	s_add_i32 s64, s64, 2
	s_add_u32 s22, s22, 0x100
	s_addc_u32 s23, s23, 0
	s_add_u32 s71, s71, 0x100
	s_addc_u32 s75, s75, 0
	s_cmp_gt_u32 s64, 13
	s_cbranch_scc0 .LBB0_162
	s_and_b64 vcc, exec, s[12:13]
	s_cbranch_vccz .LBB0_165
	s_barrier

; #define PG8_STAGE(bufoff, gbase, voff) do { _Pragma("unroll") for (int _i = 0; _i < 2; ++_i) \
;         __builtin_amdgcn_global_load_lds((const unsigned*)((const char*)(gbase) + (voff)[_i]), (PG8_LAS unsigned*)(lds + (bufoff) + ldsw + _i * 8192), 16, 0, 0); } while (0)
; #define PG8_LDA(dst, b, h) do { _Pragma("unroll") for (int m = 0; m < 4; ++m) _Pragma("unroll") for (int k = 0; k < 2; ++k) dst[m][k] = *(const PG8_LAS bf16x8*)(lds + PG8_SA(b, h) + aoff + m * 2048 + k * 1024); } while (0)
; #define PG8_LDB(dst, b, h) do { _Pragma("unroll") for (int n = 0; n < 2; ++n) _Pragma("unroll") for (int k = 0; k < 2; ++k) dst[n][k] = *(const PG8_LAS bf16x8*)(lds + PG8_SB(b, h) + boff + n * 2048 + k * 1024); } while (0)
; #define PG8_WAIT_V(n) asm volatile("s_waitcnt vmcnt(" #n ")" ::: "memory")
; #define PG8_WAIT_L(n) asm volatile("s_waitcnt lgkmcnt(" #n ")" ::: "memory")
; #define PG8_BAR __builtin_amdgcn_s_barrier()
; #define PG8_SCHED __builtin_amdgcn_sched_barrier(0)
; template <class Epi, class Sched>
; __device__ __forceinline__ void gemm_phase(PG8_LAS unsigned char* lds, const Gemm g, const Sched& S, const Epi& E) {
;     ...
;     PG8_STAGE(PG8_SB(0, 0), cB, voffB); PG8_STAGE(PG8_SB(0, 1), cB + hstepB, voffB); PG8_STAGE(PG8_SA(0, 0), cA, voffA); PG8_STAGE(PG8_SA(0, 1), cA + hstepA, voffA);
;     if (wr == 1) PG8_BAR;
;     PG8_WAIT_V(2); PG8_BAR;
;     PG8_STAGE(PG8_SB(1, 0), cB + kstep, voffB); PG8_STAGE(PG8_SA(1, 0), cA + kstep, voffA); PG8_STAGE(PG8_SB(1, 1), cB + hstepB + kstep, voffB);
;     PG8_WAIT_V(6); PG8_BAR;
;     for (;;) {
;         const bool has_next = S.next(ui + 1, nxt);
;         const char* nA = has_next ? (const char*)g.A + (size_t)nxt.pm * tstepA : cA; const char* nB = has_next ? (const char*)g.Bt + (size_t)nxt.pn * tstepB : cB;
;         for (int t = 0; t < nt; t += 2) {
;             const bool last = (t == nt - 2);
;             const char* a1 = cA + (size_t)(t + 1) * kstep;
;             const char* a2 = last ? nA : cA + (size_t)(t + 2) * kstep; const char* b2 = last ? nB : cB + (size_t)(t + 2) * kstep;
;             const char* a3 = a2 + kstep; const char* b3 = b2 + kstep;
;             PG8_LDB(B0, 0, 0); PG8_LDB(B1, 0, 1); PG8_SCHED; PG8_LDA(At, 0, 0); PG8_STAGE(PG8_SA(1, 1), a1 + hstepA, voffA);
;             PG8_WAIT_V(8); PG8_WAIT_L(0); PG8_BAR; PG8_MMA(0, 0, At, B0); PG8_MMA(0, 1, At, B1); PG8_BAR; PG8_SCHED;
.LBB0_240:
	v_mov_b32_e32 v133, v0
	v_lshl_add_u64 v[10:11], s[86:87], 0, v[132:133]
	v_mov_b32_e32 v137, v0
	v_lshl_add_u64 v[12:13], s[86:87], 0, v[136:137]
	v_mov_b32_e32 v131, v0
	s_add_i32 m0, s12, 0x18000
	v_lshl_add_u64 v[10:11], v[10:11], 0, s[78:79]
	v_lshl_add_u64 v[14:15], s[52:53], 0, v[130:131]
	v_mov_b32_e32 v135, v0
	s_waitcnt vmcnt(2)
	s_barrier
	global_load_lds_dwordx4 v[10:11], off
	v_lshl_add_u64 v[10:11], v[12:13], 0, s[78:79]
	s_add_i32 m0, s12, 0x1a000
	s_add_i32 s33, s12, 0x8000
	v_lshl_add_u64 v[16:17], s[52:53], 0, v[134:135]
	global_load_lds_dwordx4 v[10:11], off
	v_lshl_add_u64 v[10:11], v[14:15], 0, s[78:79]
	s_mov_b32 m0, s33
	s_add_i32 s47, s12, 0xa000
	global_load_lds_dwordx4 v[10:11], off
	v_lshl_add_u64 v[10:11], v[16:17], 0, s[78:79]
	s_mov_b32 m0, s47
	v_and_b32_e32 v18, 15, v1
	global_load_lds_dwordx4 v[10:11], off
	s_add_i32 m0, s12, 0x1c000
	v_lshl_add_u64 v[10:11], s[92:93], 0, v[132:133]
	global_load_lds_dwordx4 v[10:11], off
	v_lshl_add_u64 v[10:11], s[92:93], 0, v[136:137]
	s_add_i32 m0, s12, 0x1e000
	v_and_b32_e32 v19, 48, v1
	global_load_lds_dwordx4 v[10:11], off
	s_and_b32 s46, s0, 3
	v_lshl_or_b32 v142, s1, 6, v18
	v_lshl_or_b32 v18, v18, 6, v19
	v_lshlrev_b32_e32 v19, 2, v1
	s_lshl_b32 s0, s46, 12
	v_and_b32_e32 v19, 32, v19
	v_bitop3_b32 v143, v18, s0, v19 bitop3:0xde
	s_lshl_b32 s0, s1, 13
	v_lshrrev_b32_e32 v10, 1, v2
	v_mul_lo_u32 v2, v4, s35
	s_movk_i32 s4, 0x3000
	v_bitop3_b32 v18, v18, s0, v19 bitop3:0xde
	v_mad_u64_u32 v[10:11], s[0:1], v10, s4, v[2:3]
	v_or_b32_e32 v2, v10, v3
	v_add_lshl_u32 v2, v2, v5, 1
	v_mov_b32_e32 v3, v0
	v_lshl_add_u64 v[138:139], s[72:73], 0, v[2:3]
	v_lshrrev_b32_e32 v3, 1, v6
	v_mul_lo_u32 v2, v8, s35
	v_mad_u64_u32 v[2:3], s[0:1], v3, s4, v[2:3]
	v_or_b32_e32 v2, v2, v7
	s_waitcnt vmcnt(6)
	v_add_lshl_u32 v2, v2, v9, 1
	v_mov_b32_e32 v3, v0
	v_lshl_add_u64 v[140:141], s[72:73], 0, v[2:3]
	v_mov_b32_e32 v2, 0
	s_mov_b32 s48, -2
	s_mov_b64 s[0:1], 0
	v_add_u32_e32 v144, 0, v18
	s_waitcnt vmcnt(0)
	s_barrier
	s_add_u32 s4, s76, s0
	s_addc_u32 s5, s77, s1
	s_add_u32 s4, s4, 0x2e000100
	s_addc_u32 s5, s5, 0
	s_add_u32 s17, s60, s0
	s_addc_u32 s18, s61, s1
	s_add_i32 s16, 0, 0x10000
	s_cmpk_eq_i32 s0, 0x300
	s_cselect_b32 s7, s53, s5
	s_cselect_b32 s6, s52, s4
	v_add_u32_e32 v145, s16, v143
	s_cselect_b32 s5, s87, s18
	s_cselect_b32 s4, s86, s17
	s_add_i32 s17, 0, 0x14000
	ds_read_b128 v[146:149], v145
	ds_read_b128 v[150:153], v145 offset:1024
	ds_read_b128 v[154:157], v145 offset:2048
	ds_read_b128 v[158:161], v145 offset:3072
	v_add_u32_e32 v145, s17, v143
	ds_read_b128 v[162:165], v145
	ds_read_b128 v[166:169], v145 offset:1024
	ds_read_b128 v[170:173], v145 offset:2048
	ds_read_b128 v[174:177], v145 offset:3072
	v_lshl_add_u64 v[210:211], v[138:139], 0, s[0:1]
	s_add_i32 m0, s12, 0xc000
	ds_read_b128 v[178:181], v144
	ds_read_b128 v[182:185], v144 offset:1024
	ds_read_b128 v[186:189], v144 offset:2048
	ds_read_b128 v[190:193], v144 offset:3072
	ds_read_b128 v[194:197], v144 offset:4096
	ds_read_b128 v[198:201], v144 offset:5120
	ds_read_b128 v[202:205], v144 offset:6144
	ds_read_b128 v[206:209], v144 offset:7168
	global_load_lds_dwordx4 v[210:211], off
	v_lshl_add_u64 v[210:211], v[140:141], 0, s[0:1]
	s_add_i32 m0, s12, 0xe000
	s_nop 0
	global_load_lds_dwordx4 v[210:211], off
	s_waitcnt vmcnt(8)
	s_waitcnt lgkmcnt(0)
	s_barrier
	s_setprio 1
	s_waitcnt lgkmcnt(0)
	v_mfma_f32_16x16x32_bf16 v[126:129], v[146:149], v[178:181], 0
	v_mfma_f32_16x16x32_bf16 v[122:125], v[154:157], v[178:181], 0
	v_mfma_f32_16x16x32_bf16 v[118:121], v[146:149], v[186:189], 0
	v_mfma_f32_16x16x32_bf16 v[114:117], v[154:157], v[186:189], 0
	v_mfma_f32_16x16x32_bf16 v[110:113], v[146:149], v[194:197], 0
	v_mfma_f32_16x16x32_bf16 v[106:109], v[154:157], v[194:197], 0
	v_mfma_f32_16x16x32_bf16 v[102:105], v[146:149], v[202:205], 0
	v_mfma_f32_16x16x32_bf16 v[98:101], v[154:157], v[202:205], 0
	v_mfma_f32_16x16x32_bf16 v[126:129], v[150:153], v[182:185], v[126:129]
	v_mfma_f32_16x16x32_bf16 v[122:125], v[158:161], v[182:185], v[122:125]
	v_mfma_f32_16x16x32_bf16 v[118:121], v[150:153], v[190:193], v[118:121]
	v_mfma_f32_16x16x32_bf16 v[114:117], v[158:161], v[190:193], v[114:117]
	v_mfma_f32_16x16x32_bf16 v[110:113], v[150:153], v[198:201], v[110:113]
	v_mfma_f32_16x16x32_bf16 v[106:109], v[158:161], v[198:201], v[106:109]
	v_mfma_f32_16x16x32_bf16 v[102:105], v[150:153], v[206:209], v[102:105]
	v_mfma_f32_16x16x32_bf16 v[98:101], v[158:161], v[206:209], v[98:101]
	s_setprio 0
	s_setprio 1
	v_mfma_f32_16x16x32_bf16 v[62:65], v[162:165], v[178:181], 0
	v_mfma_f32_16x16x32_bf16 v[58:61], v[170:173], v[178:181], 0
	v_mfma_f32_16x16x32_bf16 v[54:57], v[162:165], v[186:189], 0
	v_mfma_f32_16x16x32_bf16 v[50:53], v[170:173], v[186:189], 0
	v_mfma_f32_16x16x32_bf16 v[46:49], v[162:165], v[194:197], 0
	v_mfma_f32_16x16x32_bf16 v[42:45], v[170:173], v[194:197], 0
	v_mfma_f32_16x16x32_bf16 v[38:41], v[162:165], v[202:205], 0
	v_mfma_f32_16x16x32_bf16 v[34:37], v[170:173], v[202:205], 0
	v_mfma_f32_16x16x32_bf16 v[62:65], v[166:169], v[182:185], v[62:65]
	v_mfma_f32_16x16x32_bf16 v[58:61], v[174:177], v[182:185], v[58:61]
	v_mfma_f32_16x16x32_bf16 v[54:57], v[166:169], v[190:193], v[54:57]
	v_mfma_f32_16x16x32_bf16 v[50:53], v[174:177], v[190:193], v[50:53]
	v_mfma_f32_16x16x32_bf16 v[46:49], v[166:169], v[198:201], v[46:49]
	v_mfma_f32_16x16x32_bf16 v[42:45], v[174:177], v[198:201], v[42:45]
	v_mfma_f32_16x16x32_bf16 v[38:41], v[166:169], v[206:209], v[38:41]
	v_mfma_f32_16x16x32_bf16 v[34:37], v[174:177], v[206:209], v[34:37]
	s_setprio 0
	s_barrier
; #define PG8_STAGE(bufoff, gbase, voff) do { _Pragma("unroll") for (int _i = 0; _i < 2; ++_i) \
;         __builtin_amdgcn_global_load_lds((const unsigned*)((const char*)(gbase) + (voff)[_i]), (PG8_LAS unsigned*)(lds + (bufoff) + ldsw + _i * 8192), 16, 0, 0); } while (0)
; #define PG8_LDA(dst, b, h) do { _Pragma("unroll") for (int m = 0; m < 4; ++m) _Pragma("unroll") for (int k = 0; k < 2; ++k) dst[m][k] = *(const PG8_LAS bf16x8*)(lds + PG8_SA(b, h) + aoff + m * 2048 + k * 1024); } while (0)
; #define PG8_MMA(ai, bj, At, Bt) do { __builtin_amdgcn_s_setprio(1); _Pragma("unroll") for (int m = 0; m < 4; ++m) _Pragma("unroll") for (int n = 0; n < 2; ++n) _Pragma("unroll") for (int k = 0; k < 2; ++k) \
;         acc[ai][bj][m][n] = __builtin_amdgcn_mfma_f32_16x16x32_bf16(Bt[n][k], At[m][k], acc[ai][bj][m][n], 0, 0, 0); __builtin_amdgcn_s_setprio(0); } while (0)
; #define PG8_WAIT_V(n) asm volatile("s_waitcnt vmcnt(" #n ")" ::: "memory")
; #define PG8_WAIT_L(n) asm volatile("s_waitcnt lgkmcnt(" #n ")" ::: "memory")
; #define PG8_BAR __builtin_amdgcn_s_barrier()
; #define PG8_SCHED __builtin_amdgcn_sched_barrier(0)
; template <class Epi, class Sched>
; __device__ __forceinline__ void gemm_phase(PG8_LAS unsigned char* lds, const Gemm g, const Sched& S, const Epi& E) {
;     ...
;             PG8_LDA(At, 0, 1); PG8_STAGE(PG8_SB(0, 0), b2, voffB); PG8_STAGE(PG8_SB(0, 1), b2 + hstepB, voffB); PG8_STAGE(PG8_SA(0, 0), a2, voffA);
;             PG8_WAIT_V(8); PG8_WAIT_L(0); PG8_BAR; PG8_MMA(1, 0, At, B0); PG8_MMA(1, 1, At, B1); PG8_BAR; PG8_SCHED;
	s_add_i32 s18, s16, s11
	v_lshl_add_u64 v[210:211], s[4:5], 0, v[132:133]
	s_mov_b32 m0, s18
	ds_read_b128 v[178:181], v144 offset:16384
	ds_read_b128 v[182:185], v144 offset:17408
	ds_read_b128 v[186:189], v144 offset:18432
	ds_read_b128 v[190:193], v144 offset:19456
	ds_read_b128 v[194:197], v144 offset:20480
	ds_read_b128 v[198:201], v144 offset:21504
	ds_read_b128 v[202:205], v144 offset:22528
	ds_read_b128 v[206:209], v144 offset:23552
	global_load_lds_dwordx4 v[210:211], off
	s_add_i32 m0, s18, 0x2000
	s_add_u32 s18, s4, 0x20000
	v_lshl_add_u64 v[214:215], s[4:5], 0, v[136:137]
	s_addc_u32 s19, s5, 0
	s_add_i32 s49, s17, s11
	global_load_lds_dwordx4 v[214:215], off
	v_lshl_add_u64 v[216:217], s[18:19], 0, v[132:133]
	s_mov_b32 m0, s49
	v_lshl_add_u64 v[218:219], s[6:7], 0, v[134:135]
	global_load_lds_dwordx4 v[216:217], off
	v_lshl_add_u64 v[216:217], s[18:19], 0, v[136:137]
	s_add_i32 m0, s49, 0x2000
	s_nop 0
	global_load_lds_dwordx4 v[216:217], off
	v_lshl_add_u64 v[216:217], s[6:7], 0, v[130:131]
	s_mov_b32 m0, s12
	s_nop 0
	global_load_lds_dwordx4 v[216:217], off
	s_mov_b32 m0, s13
	s_nop 0
	global_load_lds_dwordx4 v[218:219], off
	s_waitcnt vmcnt(8)
	s_waitcnt lgkmcnt(0)
	s_barrier
	s_setprio 1
	s_waitcnt lgkmcnt(0)
	v_mfma_f32_16x16x32_bf16 v[94:97], v[146:149], v[178:181], 0
	v_mfma_f32_16x16x32_bf16 v[90:93], v[154:157], v[178:181], 0
	v_mfma_f32_16x16x32_bf16 v[86:89], v[146:149], v[186:189], 0
	v_mfma_f32_16x16x32_bf16 v[82:85], v[154:157], v[186:189], 0
	v_mfma_f32_16x16x32_bf16 v[78:81], v[146:149], v[194:197], 0
	v_mfma_f32_16x16x32_bf16 v[74:77], v[154:157], v[194:197], 0
	v_mfma_f32_16x16x32_bf16 v[70:73], v[146:149], v[202:205], 0
	v_mfma_f32_16x16x32_bf16 v[66:69], v[154:157], v[202:205], 0
	v_mfma_f32_16x16x32_bf16 v[94:97], v[150:153], v[182:185], v[94:97]
	v_mfma_f32_16x16x32_bf16 v[90:93], v[158:161], v[182:185], v[90:93]
	v_mfma_f32_16x16x32_bf16 v[86:89], v[150:153], v[190:193], v[86:89]
	v_mfma_f32_16x16x32_bf16 v[82:85], v[158:161], v[190:193], v[82:85]
	v_mfma_f32_16x16x32_bf16 v[78:81], v[150:153], v[198:201], v[78:81]
	v_mfma_f32_16x16x32_bf16 v[74:77], v[158:161], v[198:201], v[74:77]
	v_mfma_f32_16x16x32_bf16 v[70:73], v[150:153], v[206:209], v[70:73]
	v_mfma_f32_16x16x32_bf16 v[66:69], v[158:161], v[206:209], v[66:69]
	s_setprio 0
	s_setprio 1
	v_mfma_f32_16x16x32_bf16 v[30:33], v[162:165], v[178:181], 0
	v_mfma_f32_16x16x32_bf16 v[26:29], v[170:173], v[178:181], 0
	v_mfma_f32_16x16x32_bf16 v[22:25], v[162:165], v[186:189], 0
	v_mfma_f32_16x16x32_bf16 v[18:21], v[170:173], v[186:189], 0
	v_mfma_f32_16x16x32_bf16 v[14:17], v[162:165], v[194:197], 0
	v_mfma_f32_16x16x32_bf16 v[10:13], v[170:173], v[194:197], 0
	v_mfma_f32_16x16x32_bf16 v[6:9], v[162:165], v[202:205], 0
	v_mfma_f32_16x16x32_bf16 v[2:5], v[170:173], v[202:205], 0
	v_mfma_f32_16x16x32_bf16 v[30:33], v[166:169], v[182:185], v[30:33]
	v_mfma_f32_16x16x32_bf16 v[26:29], v[174:177], v[182:185], v[26:29]
	v_mfma_f32_16x16x32_bf16 v[22:25], v[166:169], v[190:193], v[22:25]
	v_mfma_f32_16x16x32_bf16 v[18:21], v[174:177], v[190:193], v[18:21]
	v_mfma_f32_16x16x32_bf16 v[14:17], v[166:169], v[198:201], v[14:17]
	v_mfma_f32_16x16x32_bf16 v[10:13], v[174:177], v[198:201], v[10:13]
	v_mfma_f32_16x16x32_bf16 v[6:9], v[166:169], v[206:209], v[6:9]
	v_mfma_f32_16x16x32_bf16 v[2:5], v[174:177], v[206:209], v[2:5]
	s_setprio 0
	s_barrier
	s_branch .Lpeel_mid_241

; #define PG8_STAGE(bufoff, gbase, voff) do { _Pragma("unroll") for (int _i = 0; _i < 2; ++_i) \
;         __builtin_amdgcn_global_load_lds((const unsigned*)((const char*)(gbase) + (voff)[_i]), (PG8_LAS unsigned*)(lds + (bufoff) + ldsw + _i * 8192), 16, 0, 0); } while (0)
; #define PG8_LDA(dst, b, h) do { _Pragma("unroll") for (int m = 0; m < 4; ++m) _Pragma("unroll") for (int k = 0; k < 2; ++k) dst[m][k] = *(const PG8_LAS bf16x8*)(lds + PG8_SA(b, h) + aoff + m * 2048 + k * 1024); } while (0)
; #define PG8_LDB(dst, b, h) do { _Pragma("unroll") for (int n = 0; n < 2; ++n) _Pragma("unroll") for (int k = 0; k < 2; ++k) dst[n][k] = *(const PG8_LAS bf16x8*)(lds + PG8_SB(b, h) + boff + n * 2048 + k * 1024); } while (0)
; #define PG8_MMA(ai, bj, At, Bt) do { __builtin_amdgcn_s_setprio(1); _Pragma("unroll") for (int m = 0; m < 4; ++m) _Pragma("unroll") for (int n = 0; n < 2; ++n) _Pragma("unroll") for (int k = 0; k < 2; ++k) \
;         acc[ai][bj][m][n] = __builtin_amdgcn_mfma_f32_16x16x32_bf16(Bt[n][k], At[m][k], acc[ai][bj][m][n], 0, 0, 0); __builtin_amdgcn_s_setprio(0); } while (0)
; #define PG8_WAIT_V(n) asm volatile("s_waitcnt vmcnt(" #n ")" ::: "memory")
; #define PG8_WAIT_L(n) asm volatile("s_waitcnt lgkmcnt(" #n ")" ::: "memory")
; #define PG8_BAR __builtin_amdgcn_s_barrier()
; #define PG8_SCHED __builtin_amdgcn_sched_barrier(0)
; template <class Epi, class Sched>
; __device__ __forceinline__ void gemm_phase(PG8_LAS unsigned char* lds, const Gemm g, const Sched& S, const Epi& E) {
;     ...
;             PG8_LDB(B0, 1, 0); PG8_LDB(B1, 1, 1); PG8_SCHED; PG8_LDA(At, 1, 0); PG8_STAGE(PG8_SA(0, 1), a2 + hstepA, voffA);
;             PG8_WAIT_V(8); PG8_WAIT_L(0); PG8_BAR; PG8_MMA(0, 0, At, B0); PG8_MMA(0, 1, At, B1); PG8_BAR; PG8_SCHED;
.Lpeel_mid_241:
	s_add_i32 s18, 0, 0x18000
	v_add_u32_e32 v145, s18, v143
	s_add_i32 s19, 0, 0x1c000
	ds_read_b128 v[146:149], v145
	ds_read_b128 v[150:153], v145 offset:1024
	ds_read_b128 v[154:157], v145 offset:2048
	ds_read_b128 v[158:161], v145 offset:3072
	v_add_u32_e32 v145, s19, v143
	ds_read_b128 v[162:165], v145
	ds_read_b128 v[166:169], v145 offset:1024
	ds_read_b128 v[170:173], v145 offset:2048
	ds_read_b128 v[174:177], v145 offset:3072
	s_add_u32 s6, s6, 0x30000
	s_addc_u32 s7, s7, 0
	s_mov_b32 m0, s14
	v_lshl_add_u64 v[220:221], s[6:7], 0, v[130:131]
	ds_read_b128 v[178:181], v144 offset:32768
	ds_read_b128 v[182:185], v144 offset:33792
	ds_read_b128 v[186:189], v144 offset:34816
	ds_read_b128 v[190:193], v144 offset:35840
	ds_read_b128 v[194:197], v144 offset:36864
	ds_read_b128 v[198:201], v144 offset:37888
	ds_read_b128 v[202:205], v144 offset:38912
	ds_read_b128 v[206:209], v144 offset:39936
	global_load_lds_dwordx4 v[220:221], off
	v_lshl_add_u64 v[220:221], s[6:7], 0, v[134:135]
	s_mov_b32 m0, s15
	s_nop 0
	global_load_lds_dwordx4 v[220:221], off
	s_waitcnt vmcnt(8)
	s_waitcnt lgkmcnt(0)
	s_barrier
	s_setprio 1
	s_waitcnt lgkmcnt(0)
	v_mfma_f32_16x16x32_bf16 v[126:129], v[146:149], v[178:181], v[126:129]
	v_mfma_f32_16x16x32_bf16 v[122:125], v[154:157], v[178:181], v[122:125]
	v_mfma_f32_16x16x32_bf16 v[118:121], v[146:149], v[186:189], v[118:121]
	v_mfma_f32_16x16x32_bf16 v[114:117], v[154:157], v[186:189], v[114:117]
	v_mfma_f32_16x16x32_bf16 v[110:113], v[146:149], v[194:197], v[110:113]
	v_mfma_f32_16x16x32_bf16 v[106:109], v[154:157], v[194:197], v[106:109]
	v_mfma_f32_16x16x32_bf16 v[102:105], v[146:149], v[202:205], v[102:105]
	v_mfma_f32_16x16x32_bf16 v[98:101], v[154:157], v[202:205], v[98:101]
	v_mfma_f32_16x16x32_bf16 v[126:129], v[150:153], v[182:185], v[126:129]
	v_mfma_f32_16x16x32_bf16 v[122:125], v[158:161], v[182:185], v[122:125]
	v_mfma_f32_16x16x32_bf16 v[118:121], v[150:153], v[190:193], v[118:121]
	v_mfma_f32_16x16x32_bf16 v[114:117], v[158:161], v[190:193], v[114:117]
	v_mfma_f32_16x16x32_bf16 v[110:113], v[150:153], v[198:201], v[110:113]
	v_mfma_f32_16x16x32_bf16 v[106:109], v[158:161], v[198:201], v[106:109]
	v_mfma_f32_16x16x32_bf16 v[102:105], v[150:153], v[206:209], v[102:105]
	v_mfma_f32_16x16x32_bf16 v[98:101], v[158:161], v[206:209], v[98:101]
	s_setprio 0
	s_setprio 1
	v_mfma_f32_16x16x32_bf16 v[62:65], v[162:165], v[178:181], v[62:65]
	v_mfma_f32_16x16x32_bf16 v[58:61], v[170:173], v[178:181], v[58:61]
	v_mfma_f32_16x16x32_bf16 v[54:57], v[162:165], v[186:189], v[54:57]
	v_mfma_f32_16x16x32_bf16 v[50:53], v[170:173], v[186:189], v[50:53]
	v_mfma_f32_16x16x32_bf16 v[46:49], v[162:165], v[194:197], v[46:49]
	v_mfma_f32_16x16x32_bf16 v[42:45], v[170:173], v[194:197], v[42:45]
	v_mfma_f32_16x16x32_bf16 v[38:41], v[162:165], v[202:205], v[38:41]
	v_mfma_f32_16x16x32_bf16 v[34:37], v[170:173], v[202:205], v[34:37]
	v_mfma_f32_16x16x32_bf16 v[62:65], v[166:169], v[182:185], v[62:65]
	v_mfma_f32_16x16x32_bf16 v[58:61], v[174:177], v[182:185], v[58:61]
	v_mfma_f32_16x16x32_bf16 v[54:57], v[166:169], v[190:193], v[54:57]
	v_mfma_f32_16x16x32_bf16 v[50:53], v[174:177], v[190:193], v[50:53]
	v_mfma_f32_16x16x32_bf16 v[46:49], v[166:169], v[198:201], v[46:49]
	v_mfma_f32_16x16x32_bf16 v[42:45], v[174:177], v[198:201], v[42:45]
	v_mfma_f32_16x16x32_bf16 v[38:41], v[166:169], v[206:209], v[38:41]
	v_mfma_f32_16x16x32_bf16 v[34:37], v[174:177], v[206:209], v[34:37]
	s_setprio 0
	s_barrier
; #define PG8_STAGE(bufoff, gbase, voff) do { _Pragma("unroll") for (int _i = 0; _i < 2; ++_i) \
;         __builtin_amdgcn_global_load_lds((const unsigned*)((const char*)(gbase) + (voff)[_i]), (PG8_LAS unsigned*)(lds + (bufoff) + ldsw + _i * 8192), 16, 0, 0); } while (0)
; #define PG8_LDA(dst, b, h) do { _Pragma("unroll") for (int m = 0; m < 4; ++m) _Pragma("unroll") for (int k = 0; k < 2; ++k) dst[m][k] = *(const PG8_LAS bf16x8*)(lds + PG8_SA(b, h) + aoff + m * 2048 + k * 1024); } while (0)
; #define PG8_MMA(ai, bj, At, Bt) do { __builtin_amdgcn_s_setprio(1); _Pragma("unroll") for (int m = 0; m < 4; ++m) _Pragma("unroll") for (int n = 0; n < 2; ++n) _Pragma("unroll") for (int k = 0; k < 2; ++k) \
;         acc[ai][bj][m][n] = __builtin_amdgcn_mfma_f32_16x16x32_bf16(Bt[n][k], At[m][k], acc[ai][bj][m][n], 0, 0, 0); __builtin_amdgcn_s_setprio(0); } while (0)
; #define PG8_WAIT_V(n) asm volatile("s_waitcnt vmcnt(" #n ")" ::: "memory")
; #define PG8_WAIT_L(n) asm volatile("s_waitcnt lgkmcnt(" #n ")" ::: "memory")
; #define PG8_BAR __builtin_amdgcn_s_barrier()
; #define PG8_SCHED __builtin_amdgcn_sched_barrier(0)
; template <class Epi, class Sched>
; __device__ __forceinline__ void gemm_phase(PG8_LAS unsigned char* lds, const Gemm g, const Sched& S, const Epi& E) {
;     ...
;             PG8_LDA(At, 1, 1); PG8_STAGE(PG8_SB(1, 0), b3, voffB); PG8_STAGE(PG8_SB(1, 1), b3 + hstepB, voffB); PG8_STAGE(PG8_SA(1, 0), a3, voffA);
;             PG8_WAIT_V(8); PG8_WAIT_L(0); PG8_BAR; PG8_MMA(1, 0, At, B0); PG8_MMA(1, 1, At, B1); PG8_BAR; PG8_SCHED;
;         }
	s_add_i32 s6, s18, s11
	v_lshl_add_u64 v[210:211], v[210:211], 0, s[78:79]
	s_mov_b32 m0, s6
	ds_read_b128 v[178:181], v144 offset:49152
	ds_read_b128 v[182:185], v144 offset:50176
	ds_read_b128 v[186:189], v144 offset:51200
	ds_read_b128 v[190:193], v144 offset:52224
	ds_read_b128 v[194:197], v144 offset:53248
	ds_read_b128 v[198:201], v144 offset:54272
	ds_read_b128 v[202:205], v144 offset:55296
	ds_read_b128 v[206:209], v144 offset:56320
	global_load_lds_dwordx4 v[210:211], off
	s_add_i32 m0, s6, 0x2000
	s_add_u32 s4, s4, 0x20080
	v_lshl_add_u64 v[210:211], v[214:215], 0, s[78:79]
	s_addc_u32 s5, s5, 0
	s_add_i32 s6, s19, s11
	global_load_lds_dwordx4 v[210:211], off
	v_lshl_add_u64 v[210:211], s[4:5], 0, v[132:133]
	s_mov_b32 m0, s6
	s_nop 0
	global_load_lds_dwordx4 v[210:211], off
	v_lshl_add_u64 v[210:211], s[4:5], 0, v[136:137]
	s_add_i32 m0, s6, 0x2000
	s_nop 0
	global_load_lds_dwordx4 v[210:211], off
	v_lshl_add_u64 v[210:211], v[216:217], 0, s[78:79]
	s_mov_b32 m0, s33
	s_nop 0
	global_load_lds_dwordx4 v[210:211], off
	v_lshl_add_u64 v[210:211], v[218:219], 0, s[78:79]
	s_mov_b32 m0, s47
	s_nop 0
	global_load_lds_dwordx4 v[210:211], off
	s_waitcnt vmcnt(8)
	s_waitcnt lgkmcnt(0)
	s_barrier
	s_setprio 1
	s_waitcnt lgkmcnt(0)
	v_mfma_f32_16x16x32_bf16 v[94:97], v[146:149], v[178:181], v[94:97]
	v_mfma_f32_16x16x32_bf16 v[90:93], v[154:157], v[178:181], v[90:93]
	v_mfma_f32_16x16x32_bf16 v[86:89], v[146:149], v[186:189], v[86:89]
	v_mfma_f32_16x16x32_bf16 v[82:85], v[154:157], v[186:189], v[82:85]
	v_mfma_f32_16x16x32_bf16 v[78:81], v[146:149], v[194:197], v[78:81]
	v_mfma_f32_16x16x32_bf16 v[74:77], v[154:157], v[194:197], v[74:77]
	v_mfma_f32_16x16x32_bf16 v[70:73], v[146:149], v[202:205], v[70:73]
	v_mfma_f32_16x16x32_bf16 v[66:69], v[154:157], v[202:205], v[66:69]
	v_mfma_f32_16x16x32_bf16 v[94:97], v[150:153], v[182:185], v[94:97]
	v_mfma_f32_16x16x32_bf16 v[90:93], v[158:161], v[182:185], v[90:93]
	v_mfma_f32_16x16x32_bf16 v[86:89], v[150:153], v[190:193], v[86:89]
	v_mfma_f32_16x16x32_bf16 v[82:85], v[158:161], v[190:193], v[82:85]
	v_mfma_f32_16x16x32_bf16 v[78:81], v[150:153], v[198:201], v[78:81]
	v_mfma_f32_16x16x32_bf16 v[74:77], v[158:161], v[198:201], v[74:77]
	v_mfma_f32_16x16x32_bf16 v[70:73], v[150:153], v[206:209], v[70:73]
	v_mfma_f32_16x16x32_bf16 v[66:69], v[158:161], v[206:209], v[66:69]
	s_setprio 0
	s_setprio 1
	v_mfma_f32_16x16x32_bf16 v[30:33], v[162:165], v[178:181], v[30:33]
	v_mfma_f32_16x16x32_bf16 v[26:29], v[170:173], v[178:181], v[26:29]
	v_mfma_f32_16x16x32_bf16 v[22:25], v[162:165], v[186:189], v[22:25]
	v_mfma_f32_16x16x32_bf16 v[18:21], v[170:173], v[186:189], v[18:21]
	v_mfma_f32_16x16x32_bf16 v[14:17], v[162:165], v[194:197], v[14:17]
	v_mfma_f32_16x16x32_bf16 v[10:13], v[170:173], v[194:197], v[10:13]
	v_mfma_f32_16x16x32_bf16 v[6:9], v[162:165], v[202:205], v[6:9]
	v_mfma_f32_16x16x32_bf16 v[2:5], v[170:173], v[202:205], v[2:5]
	v_mfma_f32_16x16x32_bf16 v[30:33], v[166:169], v[182:185], v[30:33]
	v_mfma_f32_16x16x32_bf16 v[26:29], v[174:177], v[182:185], v[26:29]
	v_mfma_f32_16x16x32_bf16 v[22:25], v[166:169], v[190:193], v[22:25]
	v_mfma_f32_16x16x32_bf16 v[18:21], v[174:177], v[190:193], v[18:21]
	v_mfma_f32_16x16x32_bf16 v[14:17], v[166:169], v[198:201], v[14:17]
	v_mfma_f32_16x16x32_bf16 v[10:13], v[174:177], v[198:201], v[10:13]
	v_mfma_f32_16x16x32_bf16 v[6:9], v[166:169], v[206:209], v[6:9]
	v_mfma_f32_16x16x32_bf16 v[2:5], v[174:177], v[206:209], v[2:5]
	s_setprio 0
	s_barrier
	s_add_i32 s48, s48, 2
	s_add_u32 s0, s0, 0x100
	s_addc_u32 s1, s1, 0
	s_cmp_gt_u32 s48, 5
	s_cbranch_scc0 .LBB0_241
	s_cmpk_lt_u32 s10, 0x100
	s_cbranch_scc0 .LBB0_244
	s_barrier

; #define PG8_STAGE(bufoff, gbase, voff) do { _Pragma("unroll") for (int _i = 0; _i < 2; ++_i) \
;         __builtin_amdgcn_global_load_lds((const unsigned*)((const char*)(gbase) + (voff)[_i]), (PG8_LAS unsigned*)(lds + (bufoff) + ldsw + _i * 8192), 16, 0, 0); } while (0)
; #define PG8_LDA(dst, b, h) do { _Pragma("unroll") for (int m = 0; m < 4; ++m) _Pragma("unroll") for (int k = 0; k < 2; ++k) dst[m][k] = *(const PG8_LAS bf16x8*)(lds + PG8_SA(b, h) + aoff + m * 2048 + k * 1024); } while (0)
; #define PG8_LDB(dst, b, h) do { _Pragma("unroll") for (int n = 0; n < 2; ++n) _Pragma("unroll") for (int k = 0; k < 2; ++k) dst[n][k] = *(const PG8_LAS bf16x8*)(lds + PG8_SB(b, h) + boff + n * 2048 + k * 1024); } while (0)
; #define PG8_MMA(ai, bj, At, Bt) do { __builtin_amdgcn_s_setprio(1); _Pragma("unroll") for (int m = 0; m < 4; ++m) _Pragma("unroll") for (int n = 0; n < 2; ++n) _Pragma("unroll") for (int k = 0; k < 2; ++k) \
;         acc[ai][bj][m][n] = __builtin_amdgcn_mfma_f32_16x16x32_bf16(Bt[n][k], At[m][k], acc[ai][bj][m][n], 0, 0, 0); __builtin_amdgcn_s_setprio(0); } while (0)
; #define PG8_WAIT_V(n) asm volatile("s_waitcnt vmcnt(" #n ")" ::: "memory")
; #define PG8_WAIT_L(n) asm volatile("s_waitcnt lgkmcnt(" #n ")" ::: "memory")
; #define PG8_BAR __builtin_amdgcn_s_barrier()
; #define PG8_SCHED __builtin_amdgcn_sched_barrier(0)
; template <class Epi, class Sched>
; __device__ __forceinline__ void gemm_phase(PG8_LAS unsigned char* lds, const Gemm g, const Sched& S, const Epi& E) {
;     ...
;         const bool has_next = S.next(ui + 1, nxt);
;         const char* nA = has_next ? (const char*)g.A + (size_t)nxt.pm * tstepA : cA; const char* nB = has_next ? (const char*)g.Bt + (size_t)nxt.pn * tstepB : cB;
;         for (int t = 0; t < nt; t += 2) {
;             const bool last = (t == nt - 2);
;             const char* a1 = cA + (size_t)(t + 1) * kstep;
;             const char* a2 = last ? nA : cA + (size_t)(t + 2) * kstep; const char* b2 = last ? nB : cB + (size_t)(t + 2) * kstep;
;             const char* a3 = a2 + kstep; const char* b3 = b2 + kstep;
;             PG8_LDB(B0, 0, 0); PG8_LDB(B1, 0, 1); PG8_SCHED; PG8_LDA(At, 0, 0); PG8_STAGE(PG8_SA(1, 1), a1 + hstepA, voffA);
;             PG8_WAIT_V(8); PG8_WAIT_L(0); PG8_BAR; PG8_MMA(0, 0, At, B0); PG8_MMA(0, 1, At, B1); PG8_BAR; PG8_SCHED;
.LBB0_255:
	s_and_b64 s[12:13], s[6:7], exec
	s_cselect_b32 vcc_lo, s43, s11
	s_cselect_b32 vcc_hi, s42, s10
	s_add_u32 s74, s10, 0x100
	v_mov_b32_e32 v2, 0
	s_addc_u32 s64, s11, 0
	s_mov_b32 s65, -2
	s_mov_b64 s[10:11], 0
	v_add_u32_e32 v144, s16, v1
	ds_read_b128 v[148:151], v144
	ds_read_b128 v[152:155], v144 offset:1024
	ds_read_b128 v[156:159], v144 offset:2048
	ds_read_b128 v[160:163], v144 offset:3072
	v_add_u32_e32 v144, s17, v1
	s_add_u32 s12, s76, s10
	ds_read_b128 v[164:167], v144
	ds_read_b128 v[168:171], v144 offset:1024
	ds_read_b128 v[172:175], v144 offset:2048
	ds_read_b128 v[176:179], v144 offset:3072
	s_addc_u32 s13, s77, s11
	s_add_u32 s12, s12, 0x2e000100
	s_addc_u32 s13, s13, 0
	s_add_u32 s66, s74, s10
	s_addc_u32 s67, s64, s11
	s_cmpk_eq_i32 s10, 0x500
	s_cselect_b32 s15, s53, s13
	s_cselect_b32 s14, s52, s12
	s_cselect_b32 s13, vcc_lo, s67
	s_cselect_b32 s12, vcc_hi, s66
	v_lshl_add_u64 v[144:145], v[140:141], 0, s[10:11]
	s_add_i32 m0, s48, 0xc000
	ds_read_b128 v[180:183], v147
	ds_read_b128 v[184:187], v147 offset:1024
	ds_read_b128 v[188:191], v147 offset:2048
	ds_read_b128 v[192:195], v147 offset:3072
	ds_read_b128 v[196:199], v147 offset:4096
	ds_read_b128 v[200:203], v147 offset:5120
	ds_read_b128 v[204:207], v147 offset:6144
	ds_read_b128 v[214:217], v147 offset:7168
	global_load_lds_dwordx4 v[144:145], off
	v_lshl_add_u64 v[144:145], v[142:143], 0, s[10:11]
	s_add_i32 m0, s48, 0xe000
	s_nop 0
	global_load_lds_dwordx4 v[144:145], off
	s_waitcnt vmcnt(8)
	s_waitcnt lgkmcnt(0)
	s_barrier
	s_setprio 1
	s_waitcnt lgkmcnt(0)
	v_mfma_f32_16x16x32_bf16 v[126:129], v[148:151], v[180:183], 0
	v_mfma_f32_16x16x32_bf16 v[122:125], v[156:159], v[180:183], 0
	v_mfma_f32_16x16x32_bf16 v[110:113], v[148:151], v[188:191], 0
	v_mfma_f32_16x16x32_bf16 v[106:109], v[156:159], v[188:191], 0
	v_mfma_f32_16x16x32_bf16 v[94:97], v[148:151], v[196:199], 0
	v_mfma_f32_16x16x32_bf16 v[90:93], v[156:159], v[196:199], 0
	v_mfma_f32_16x16x32_bf16 v[78:81], v[148:151], v[204:207], 0
	v_mfma_f32_16x16x32_bf16 v[74:77], v[156:159], v[204:207], 0
	v_mfma_f32_16x16x32_bf16 v[126:129], v[152:155], v[184:187], v[126:129]
	v_mfma_f32_16x16x32_bf16 v[122:125], v[160:163], v[184:187], v[122:125]
	v_mfma_f32_16x16x32_bf16 v[110:113], v[152:155], v[192:195], v[110:113]
	v_mfma_f32_16x16x32_bf16 v[106:109], v[160:163], v[192:195], v[106:109]
	v_mfma_f32_16x16x32_bf16 v[94:97], v[152:155], v[200:203], v[94:97]
	v_mfma_f32_16x16x32_bf16 v[90:93], v[160:163], v[200:203], v[90:93]
	v_mfma_f32_16x16x32_bf16 v[78:81], v[152:155], v[214:217], v[78:81]
	v_mfma_f32_16x16x32_bf16 v[74:77], v[160:163], v[214:217], v[74:77]
	s_setprio 0
	s_setprio 1
	v_mfma_f32_16x16x32_bf16 v[118:121], v[164:167], v[180:183], 0
	v_mfma_f32_16x16x32_bf16 v[114:117], v[172:175], v[180:183], 0
	v_mfma_f32_16x16x32_bf16 v[102:105], v[164:167], v[188:191], 0
	v_mfma_f32_16x16x32_bf16 v[98:101], v[172:175], v[188:191], 0
	v_mfma_f32_16x16x32_bf16 v[86:89], v[164:167], v[196:199], 0
	v_mfma_f32_16x16x32_bf16 v[82:85], v[172:175], v[196:199], 0
	v_mfma_f32_16x16x32_bf16 v[70:73], v[164:167], v[204:207], 0
	v_mfma_f32_16x16x32_bf16 v[66:69], v[172:175], v[204:207], 0
	v_mfma_f32_16x16x32_bf16 v[118:121], v[168:171], v[184:187], v[118:121]
	v_mfma_f32_16x16x32_bf16 v[114:117], v[176:179], v[184:187], v[114:117]
	v_mfma_f32_16x16x32_bf16 v[102:105], v[168:171], v[192:195], v[102:105]
	v_mfma_f32_16x16x32_bf16 v[98:101], v[176:179], v[192:195], v[98:101]
	v_mfma_f32_16x16x32_bf16 v[86:89], v[168:171], v[200:203], v[86:89]
	v_mfma_f32_16x16x32_bf16 v[82:85], v[176:179], v[200:203], v[82:85]
	v_mfma_f32_16x16x32_bf16 v[70:73], v[168:171], v[214:217], v[70:73]
	v_mfma_f32_16x16x32_bf16 v[66:69], v[176:179], v[214:217], v[66:69]
	s_setprio 0
	s_barrier
; #define PG8_STAGE(bufoff, gbase, voff) do { _Pragma("unroll") for (int _i = 0; _i < 2; ++_i) \
;         __builtin_amdgcn_global_load_lds((const unsigned*)((const char*)(gbase) + (voff)[_i]), (PG8_LAS unsigned*)(lds + (bufoff) + ldsw + _i * 8192), 16, 0, 0); } while (0)
; #define PG8_LDA(dst, b, h) do { _Pragma("unroll") for (int m = 0; m < 4; ++m) _Pragma("unroll") for (int k = 0; k < 2; ++k) dst[m][k] = *(const PG8_LAS bf16x8*)(lds + PG8_SA(b, h) + aoff + m * 2048 + k * 1024); } while (0)
; #define PG8_MMA(ai, bj, At, Bt) do { __builtin_amdgcn_s_setprio(1); _Pragma("unroll") for (int m = 0; m < 4; ++m) _Pragma("unroll") for (int n = 0; n < 2; ++n) _Pragma("unroll") for (int k = 0; k < 2; ++k) \
;         acc[ai][bj][m][n] = __builtin_amdgcn_mfma_f32_16x16x32_bf16(Bt[n][k], At[m][k], acc[ai][bj][m][n], 0, 0, 0); __builtin_amdgcn_s_setprio(0); } while (0)
; #define PG8_WAIT_V(n) asm volatile("s_waitcnt vmcnt(" #n ")" ::: "memory")
; #define PG8_WAIT_L(n) asm volatile("s_waitcnt lgkmcnt(" #n ")" ::: "memory")
; #define PG8_BAR __builtin_amdgcn_s_barrier()
; #define PG8_SCHED __builtin_amdgcn_sched_barrier(0)
; template <class Epi, class Sched>
; __device__ __forceinline__ void gemm_phase(PG8_LAS unsigned char* lds, const Gemm g, const Sched& S, const Epi& E) {
;     ...
;             PG8_LDA(At, 0, 1); PG8_STAGE(PG8_SB(0, 0), b2, voffB); PG8_STAGE(PG8_SB(0, 1), b2 + hstepB, voffB); PG8_STAGE(PG8_SA(0, 0), a2, voffA);
;             PG8_WAIT_V(8); PG8_WAIT_L(0); PG8_BAR; PG8_MMA(1, 0, At, B0); PG8_MMA(1, 1, At, B1); PG8_BAR; PG8_SCHED;
	s_add_i32 s66, s16, s59
	v_lshl_add_u64 v[144:145], s[12:13], 0, v[132:133]
	s_mov_b32 m0, s66
	ds_read_b128 v[180:183], v147 offset:16384
	ds_read_b128 v[184:187], v147 offset:17408
	ds_read_b128 v[188:191], v147 offset:18432
	ds_read_b128 v[192:195], v147 offset:19456
	ds_read_b128 v[196:199], v147 offset:20480
	ds_read_b128 v[200:203], v147 offset:21504
	ds_read_b128 v[204:207], v147 offset:22528
	ds_read_b128 v[214:217], v147 offset:23552
	global_load_lds_dwordx4 v[144:145], off
	s_add_i32 m0, s66, 0x2000
	s_add_u32 s66, s12, 0x30000
	v_lshl_add_u64 v[208:209], s[12:13], 0, v[136:137]
	s_addc_u32 s67, s13, 0
	s_add_i32 s82, s17, s59
	global_load_lds_dwordx4 v[208:209], off
	v_lshl_add_u64 v[210:211], s[66:67], 0, v[132:133]
	s_mov_b32 m0, s82
	v_lshl_add_u64 v[218:219], s[14:15], 0, v[134:135]
	global_load_lds_dwordx4 v[210:211], off
	v_lshl_add_u64 v[210:211], s[66:67], 0, v[136:137]
	s_add_i32 m0, s82, 0x2000
	s_nop 0
	global_load_lds_dwordx4 v[210:211], off
	v_lshl_add_u64 v[210:211], s[14:15], 0, v[130:131]
	s_mov_b32 m0, s48
	s_nop 0
	global_load_lds_dwordx4 v[210:211], off
	s_mov_b32 m0, s49
	s_nop 0
	global_load_lds_dwordx4 v[218:219], off
	s_waitcnt vmcnt(8)
	s_waitcnt lgkmcnt(0)
	s_barrier
	s_setprio 1
	s_waitcnt lgkmcnt(0)
	v_mfma_f32_16x16x32_bf16 v[62:65], v[148:151], v[180:183], 0
	v_mfma_f32_16x16x32_bf16 v[58:61], v[156:159], v[180:183], 0
	v_mfma_f32_16x16x32_bf16 v[46:49], v[148:151], v[188:191], 0
	v_mfma_f32_16x16x32_bf16 v[42:45], v[156:159], v[188:191], 0
	v_mfma_f32_16x16x32_bf16 v[30:33], v[148:151], v[196:199], 0
	v_mfma_f32_16x16x32_bf16 v[26:29], v[156:159], v[196:199], 0
	v_mfma_f32_16x16x32_bf16 v[14:17], v[148:151], v[204:207], 0
	v_mfma_f32_16x16x32_bf16 v[10:13], v[156:159], v[204:207], 0
	v_mfma_f32_16x16x32_bf16 v[62:65], v[152:155], v[184:187], v[62:65]
	v_mfma_f32_16x16x32_bf16 v[58:61], v[160:163], v[184:187], v[58:61]
	v_mfma_f32_16x16x32_bf16 v[46:49], v[152:155], v[192:195], v[46:49]
	v_mfma_f32_16x16x32_bf16 v[42:45], v[160:163], v[192:195], v[42:45]
	v_mfma_f32_16x16x32_bf16 v[30:33], v[152:155], v[200:203], v[30:33]
	v_mfma_f32_16x16x32_bf16 v[26:29], v[160:163], v[200:203], v[26:29]
	v_mfma_f32_16x16x32_bf16 v[14:17], v[152:155], v[214:217], v[14:17]
	v_mfma_f32_16x16x32_bf16 v[10:13], v[160:163], v[214:217], v[10:13]
	s_setprio 0
	s_setprio 1
	v_mfma_f32_16x16x32_bf16 v[54:57], v[164:167], v[180:183], 0
	v_mfma_f32_16x16x32_bf16 v[50:53], v[172:175], v[180:183], 0
	v_mfma_f32_16x16x32_bf16 v[38:41], v[164:167], v[188:191], 0
	v_mfma_f32_16x16x32_bf16 v[34:37], v[172:175], v[188:191], 0
	v_mfma_f32_16x16x32_bf16 v[22:25], v[164:167], v[196:199], 0
	v_mfma_f32_16x16x32_bf16 v[18:21], v[172:175], v[196:199], 0
	v_mfma_f32_16x16x32_bf16 v[6:9], v[164:167], v[204:207], 0
	v_mfma_f32_16x16x32_bf16 v[2:5], v[172:175], v[204:207], 0
	v_mfma_f32_16x16x32_bf16 v[54:57], v[168:171], v[184:187], v[54:57]
	v_mfma_f32_16x16x32_bf16 v[50:53], v[176:179], v[184:187], v[50:53]
	v_mfma_f32_16x16x32_bf16 v[38:41], v[168:171], v[192:195], v[38:41]
	v_mfma_f32_16x16x32_bf16 v[34:37], v[176:179], v[192:195], v[34:37]
	v_mfma_f32_16x16x32_bf16 v[22:25], v[168:171], v[200:203], v[22:25]
	v_mfma_f32_16x16x32_bf16 v[18:21], v[176:179], v[200:203], v[18:21]
	v_mfma_f32_16x16x32_bf16 v[6:9], v[168:171], v[214:217], v[6:9]
	v_mfma_f32_16x16x32_bf16 v[2:5], v[176:179], v[214:217], v[2:5]
	s_setprio 0
	s_barrier
	s_branch .Lpeel_mid_256

; #define PG8_STAGE(bufoff, gbase, voff) do { _Pragma("unroll") for (int _i = 0; _i < 2; ++_i) \
;         __builtin_amdgcn_global_load_lds((const unsigned*)((const char*)(gbase) + (voff)[_i]), (PG8_LAS unsigned*)(lds + (bufoff) + ldsw + _i * 8192), 16, 0, 0); } while (0)
; #define PG8_LDA(dst, b, h) do { _Pragma("unroll") for (int m = 0; m < 4; ++m) _Pragma("unroll") for (int k = 0; k < 2; ++k) dst[m][k] = *(const PG8_LAS bf16x8*)(lds + PG8_SA(b, h) + aoff + m * 2048 + k * 1024); } while (0)
; #define PG8_LDB(dst, b, h) do { _Pragma("unroll") for (int n = 0; n < 2; ++n) _Pragma("unroll") for (int k = 0; k < 2; ++k) dst[n][k] = *(const PG8_LAS bf16x8*)(lds + PG8_SB(b, h) + boff + n * 2048 + k * 1024); } while (0)
; #define PG8_MMA(ai, bj, At, Bt) do { __builtin_amdgcn_s_setprio(1); _Pragma("unroll") for (int m = 0; m < 4; ++m) _Pragma("unroll") for (int n = 0; n < 2; ++n) _Pragma("unroll") for (int k = 0; k < 2; ++k) \
;         acc[ai][bj][m][n] = __builtin_amdgcn_mfma_f32_16x16x32_bf16(Bt[n][k], At[m][k], acc[ai][bj][m][n], 0, 0, 0); __builtin_amdgcn_s_setprio(0); } while (0)
; #define PG8_WAIT_V(n) asm volatile("s_waitcnt vmcnt(" #n ")" ::: "memory")
; #define PG8_WAIT_L(n) asm volatile("s_waitcnt lgkmcnt(" #n ")" ::: "memory")
; #define PG8_BAR __builtin_amdgcn_s_barrier()
; #define PG8_SCHED __builtin_amdgcn_sched_barrier(0)
; template <class Epi, class Sched>
; __device__ __forceinline__ void gemm_phase(PG8_LAS unsigned char* lds, const Gemm g, const Sched& S, const Epi& E) {
;     ...
;             PG8_LDB(B0, 1, 0); PG8_LDB(B1, 1, 1); PG8_SCHED; PG8_LDA(At, 1, 0); PG8_STAGE(PG8_SA(0, 1), a2 + hstepA, voffA);
;             PG8_WAIT_V(8); PG8_WAIT_L(0); PG8_BAR; PG8_MMA(0, 0, At, B0); PG8_MMA(0, 1, At, B1); PG8_BAR; PG8_SCHED;
.Lpeel_mid_256:
	v_add_u32_e32 v160, s18, v1
	v_add_u32_e32 v176, s19, v1
	ds_read_b128 v[148:151], v160
	ds_read_b128 v[152:155], v160 offset:1024
	ds_read_b128 v[156:159], v160 offset:2048
	ds_read_b128 v[160:163], v160 offset:3072
	ds_read_b128 v[164:167], v176
	ds_read_b128 v[168:171], v176 offset:1024
	ds_read_b128 v[172:175], v176 offset:2048
	ds_read_b128 v[176:179], v176 offset:3072
	s_add_u32 s14, s14, 0x30000
	s_addc_u32 s15, s15, 0
	s_mov_b32 m0, s57
	v_lshl_add_u64 v[220:221], s[14:15], 0, v[130:131]
	ds_read_b128 v[180:183], v147 offset:32768
	ds_read_b128 v[184:187], v147 offset:33792
	ds_read_b128 v[188:191], v147 offset:34816
	ds_read_b128 v[192:195], v147 offset:35840
	ds_read_b128 v[196:199], v147 offset:36864
	ds_read_b128 v[200:203], v147 offset:37888
	ds_read_b128 v[204:207], v147 offset:38912
	ds_read_b128 v[214:217], v147 offset:39936
	global_load_lds_dwordx4 v[220:221], off
	v_lshl_add_u64 v[220:221], s[14:15], 0, v[134:135]
	s_mov_b32 m0, s58
	s_nop 0
	global_load_lds_dwordx4 v[220:221], off
	s_waitcnt vmcnt(8)
	s_waitcnt lgkmcnt(0)
	s_barrier
	s_setprio 1
	s_waitcnt lgkmcnt(0)
	v_mfma_f32_16x16x32_bf16 v[126:129], v[148:151], v[180:183], v[126:129]
	v_mfma_f32_16x16x32_bf16 v[122:125], v[156:159], v[180:183], v[122:125]
	v_mfma_f32_16x16x32_bf16 v[110:113], v[148:151], v[188:191], v[110:113]
	v_mfma_f32_16x16x32_bf16 v[106:109], v[156:159], v[188:191], v[106:109]
	v_mfma_f32_16x16x32_bf16 v[94:97], v[148:151], v[196:199], v[94:97]
	v_mfma_f32_16x16x32_bf16 v[90:93], v[156:159], v[196:199], v[90:93]
	v_mfma_f32_16x16x32_bf16 v[78:81], v[148:151], v[204:207], v[78:81]
	v_mfma_f32_16x16x32_bf16 v[74:77], v[156:159], v[204:207], v[74:77]
	v_mfma_f32_16x16x32_bf16 v[126:129], v[152:155], v[184:187], v[126:129]
	v_mfma_f32_16x16x32_bf16 v[122:125], v[160:163], v[184:187], v[122:125]
	v_mfma_f32_16x16x32_bf16 v[110:113], v[152:155], v[192:195], v[110:113]
	v_mfma_f32_16x16x32_bf16 v[106:109], v[160:163], v[192:195], v[106:109]
	v_mfma_f32_16x16x32_bf16 v[94:97], v[152:155], v[200:203], v[94:97]
	v_mfma_f32_16x16x32_bf16 v[90:93], v[160:163], v[200:203], v[90:93]
	v_mfma_f32_16x16x32_bf16 v[78:81], v[152:155], v[214:217], v[78:81]
	v_mfma_f32_16x16x32_bf16 v[74:77], v[160:163], v[214:217], v[74:77]
	s_setprio 0
	s_setprio 1
	v_mfma_f32_16x16x32_bf16 v[118:121], v[164:167], v[180:183], v[118:121]
	v_mfma_f32_16x16x32_bf16 v[114:117], v[172:175], v[180:183], v[114:117]
	v_mfma_f32_16x16x32_bf16 v[102:105], v[164:167], v[188:191], v[102:105]
	v_mfma_f32_16x16x32_bf16 v[98:101], v[172:175], v[188:191], v[98:101]
	v_mfma_f32_16x16x32_bf16 v[86:89], v[164:167], v[196:199], v[86:89]
	v_mfma_f32_16x16x32_bf16 v[82:85], v[172:175], v[196:199], v[82:85]
	v_mfma_f32_16x16x32_bf16 v[70:73], v[164:167], v[204:207], v[70:73]
	v_mfma_f32_16x16x32_bf16 v[66:69], v[172:175], v[204:207], v[66:69]
	v_mfma_f32_16x16x32_bf16 v[118:121], v[168:171], v[184:187], v[118:121]
	v_mfma_f32_16x16x32_bf16 v[114:117], v[176:179], v[184:187], v[114:117]
	v_mfma_f32_16x16x32_bf16 v[102:105], v[168:171], v[192:195], v[102:105]
	v_mfma_f32_16x16x32_bf16 v[98:101], v[176:179], v[192:195], v[98:101]
	v_mfma_f32_16x16x32_bf16 v[86:89], v[168:171], v[200:203], v[86:89]
	v_mfma_f32_16x16x32_bf16 v[82:85], v[176:179], v[200:203], v[82:85]
	v_mfma_f32_16x16x32_bf16 v[70:73], v[168:171], v[214:217], v[70:73]
	v_mfma_f32_16x16x32_bf16 v[66:69], v[176:179], v[214:217], v[66:69]
	s_setprio 0
	s_barrier
; #define PG8_STAGE(bufoff, gbase, voff) do { _Pragma("unroll") for (int _i = 0; _i < 2; ++_i) \
;         __builtin_amdgcn_global_load_lds((const unsigned*)((const char*)(gbase) + (voff)[_i]), (PG8_LAS unsigned*)(lds + (bufoff) + ldsw + _i * 8192), 16, 0, 0); } while (0)
; #define PG8_LDA(dst, b, h) do { _Pragma("unroll") for (int m = 0; m < 4; ++m) _Pragma("unroll") for (int k = 0; k < 2; ++k) dst[m][k] = *(const PG8_LAS bf16x8*)(lds + PG8_SA(b, h) + aoff + m * 2048 + k * 1024); } while (0)
; #define PG8_MMA(ai, bj, At, Bt) do { __builtin_amdgcn_s_setprio(1); _Pragma("unroll") for (int m = 0; m < 4; ++m) _Pragma("unroll") for (int n = 0; n < 2; ++n) _Pragma("unroll") for (int k = 0; k < 2; ++k) \
;         acc[ai][bj][m][n] = __builtin_amdgcn_mfma_f32_16x16x32_bf16(Bt[n][k], At[m][k], acc[ai][bj][m][n], 0, 0, 0); __builtin_amdgcn_s_setprio(0); } while (0)
; #define PG8_WAIT_V(n) asm volatile("s_waitcnt vmcnt(" #n ")" ::: "memory")
; #define PG8_WAIT_L(n) asm volatile("s_waitcnt lgkmcnt(" #n ")" ::: "memory")
; #define PG8_BAR __builtin_amdgcn_s_barrier()
; #define PG8_SCHED __builtin_amdgcn_sched_barrier(0)
; template <class Epi, class Sched>
; __device__ __forceinline__ void gemm_phase(PG8_LAS unsigned char* lds, const Gemm g, const Sched& S, const Epi& E) {
;     ...
;             PG8_LDA(At, 1, 1); PG8_STAGE(PG8_SB(1, 0), b3, voffB); PG8_STAGE(PG8_SB(1, 1), b3 + hstepB, voffB); PG8_STAGE(PG8_SA(1, 0), a3, voffA);
;             PG8_WAIT_V(8); PG8_WAIT_L(0); PG8_BAR; PG8_MMA(1, 0, At, B0); PG8_MMA(1, 1, At, B1); PG8_BAR; PG8_SCHED;
;         }
	s_add_i32 s14, s18, s59
	v_lshl_add_u64 v[144:145], v[144:145], 0, s[78:79]
	s_mov_b32 m0, s14
	ds_read_b128 v[180:183], v147 offset:49152
	ds_read_b128 v[184:187], v147 offset:50176
	ds_read_b128 v[188:191], v147 offset:51200
	ds_read_b128 v[192:195], v147 offset:52224
	ds_read_b128 v[196:199], v147 offset:53248
	ds_read_b128 v[200:203], v147 offset:54272
	ds_read_b128 v[204:207], v147 offset:55296
	ds_read_b128 v[214:217], v147 offset:56320
	global_load_lds_dwordx4 v[144:145], off
	s_add_i32 m0, s14, 0x2000
	s_add_u32 s12, s12, 0x30080
	v_lshl_add_u64 v[144:145], v[208:209], 0, s[78:79]
	s_addc_u32 s13, s13, 0
	s_add_i32 s14, s19, s59
	global_load_lds_dwordx4 v[144:145], off
	v_lshl_add_u64 v[144:145], s[12:13], 0, v[132:133]
	s_mov_b32 m0, s14
	s_nop 0
	global_load_lds_dwordx4 v[144:145], off
	v_lshl_add_u64 v[144:145], s[12:13], 0, v[136:137]
	s_add_i32 m0, s14, 0x2000
	s_nop 0
	global_load_lds_dwordx4 v[144:145], off
	v_lshl_add_u64 v[144:145], v[210:211], 0, s[78:79]
	s_mov_b32 m0, s46
	s_nop 0
	global_load_lds_dwordx4 v[144:145], off
	v_lshl_add_u64 v[144:145], v[218:219], 0, s[78:79]
	s_mov_b32 m0, s47
	s_nop 0
	global_load_lds_dwordx4 v[144:145], off
	s_waitcnt vmcnt(8)
	s_waitcnt lgkmcnt(0)
	s_barrier
	s_setprio 1
	s_waitcnt lgkmcnt(0)
	v_mfma_f32_16x16x32_bf16 v[62:65], v[148:151], v[180:183], v[62:65]
	v_mfma_f32_16x16x32_bf16 v[58:61], v[156:159], v[180:183], v[58:61]
	v_mfma_f32_16x16x32_bf16 v[46:49], v[148:151], v[188:191], v[46:49]
	v_mfma_f32_16x16x32_bf16 v[42:45], v[156:159], v[188:191], v[42:45]
	v_mfma_f32_16x16x32_bf16 v[30:33], v[148:151], v[196:199], v[30:33]
	v_mfma_f32_16x16x32_bf16 v[26:29], v[156:159], v[196:199], v[26:29]
	v_mfma_f32_16x16x32_bf16 v[14:17], v[148:151], v[204:207], v[14:17]
	v_mfma_f32_16x16x32_bf16 v[10:13], v[156:159], v[204:207], v[10:13]
	v_mfma_f32_16x16x32_bf16 v[62:65], v[152:155], v[184:187], v[62:65]
	v_mfma_f32_16x16x32_bf16 v[58:61], v[160:163], v[184:187], v[58:61]
	v_mfma_f32_16x16x32_bf16 v[46:49], v[152:155], v[192:195], v[46:49]
	v_mfma_f32_16x16x32_bf16 v[42:45], v[160:163], v[192:195], v[42:45]
	v_mfma_f32_16x16x32_bf16 v[30:33], v[152:155], v[200:203], v[30:33]
	v_mfma_f32_16x16x32_bf16 v[26:29], v[160:163], v[200:203], v[26:29]
	v_mfma_f32_16x16x32_bf16 v[14:17], v[152:155], v[214:217], v[14:17]
	v_mfma_f32_16x16x32_bf16 v[10:13], v[160:163], v[214:217], v[10:13]
	s_setprio 0
	s_setprio 1
	v_mfma_f32_16x16x32_bf16 v[54:57], v[164:167], v[180:183], v[54:57]
	v_mfma_f32_16x16x32_bf16 v[50:53], v[172:175], v[180:183], v[50:53]
	v_mfma_f32_16x16x32_bf16 v[38:41], v[164:167], v[188:191], v[38:41]
	v_mfma_f32_16x16x32_bf16 v[34:37], v[172:175], v[188:191], v[34:37]
	v_mfma_f32_16x16x32_bf16 v[22:25], v[164:167], v[196:199], v[22:25]
	v_mfma_f32_16x16x32_bf16 v[18:21], v[172:175], v[196:199], v[18:21]
	v_mfma_f32_16x16x32_bf16 v[6:9], v[164:167], v[204:207], v[6:9]
	v_mfma_f32_16x16x32_bf16 v[2:5], v[172:175], v[204:207], v[2:5]
	v_mfma_f32_16x16x32_bf16 v[54:57], v[168:171], v[184:187], v[54:57]
	v_mfma_f32_16x16x32_bf16 v[50:53], v[176:179], v[184:187], v[50:53]
	v_mfma_f32_16x16x32_bf16 v[38:41], v[168:171], v[192:195], v[38:41]
	v_mfma_f32_16x16x32_bf16 v[34:37], v[176:179], v[192:195], v[34:37]
	v_mfma_f32_16x16x32_bf16 v[22:25], v[168:171], v[200:203], v[22:25]
	v_mfma_f32_16x16x32_bf16 v[18:21], v[176:179], v[200:203], v[18:21]
	v_mfma_f32_16x16x32_bf16 v[6:9], v[168:171], v[214:217], v[6:9]
	v_mfma_f32_16x16x32_bf16 v[2:5], v[176:179], v[214:217], v[2:5]
	s_setprio 0
	s_barrier
	s_add_i32 s65, s65, 2
	s_add_u32 s10, s10, 0x100
	s_addc_u32 s11, s11, 0
	s_cmp_gt_u32 s65, 9
	s_cbranch_scc0 .LBB0_256
	s_and_b64 vcc, exec, s[4:5]
	s_cbranch_vccz .LBB0_259
	s_barrier

; #define PG8_STAGE(bufoff, gbase, voff) do { _Pragma("unroll") for (int _i = 0; _i < 2; ++_i) \
;         __builtin_amdgcn_global_load_lds((const unsigned*)((const char*)(gbase) + (voff)[_i]), (PG8_LAS unsigned*)(lds + (bufoff) + ldsw + _i * 8192), 16, 0, 0); } while (0)
; #define PG8_LDA(dst, b, h) do { _Pragma("unroll") for (int m = 0; m < 4; ++m) _Pragma("unroll") for (int k = 0; k < 2; ++k) dst[m][k] = *(const PG8_LAS bf16x8*)(lds + PG8_SA(b, h) + aoff + m * 2048 + k * 1024); } while (0)
; #define PG8_LDB(dst, b, h) do { _Pragma("unroll") for (int n = 0; n < 2; ++n) _Pragma("unroll") for (int k = 0; k < 2; ++k) dst[n][k] = *(const PG8_LAS bf16x8*)(lds + PG8_SB(b, h) + boff + n * 2048 + k * 1024); } while (0)
; #define PG8_MMA(ai, bj, At, Bt) do { __builtin_amdgcn_s_setprio(1); _Pragma("unroll") for (int m = 0; m < 4; ++m) _Pragma("unroll") for (int n = 0; n < 2; ++n) _Pragma("unroll") for (int k = 0; k < 2; ++k) \
;         acc[ai][bj][m][n] = __builtin_amdgcn_mfma_f32_16x16x32_bf16(Bt[n][k], At[m][k], acc[ai][bj][m][n], 0, 0, 0); __builtin_amdgcn_s_setprio(0); } while (0)
; #define PG8_WAIT_V(n) asm volatile("s_waitcnt vmcnt(" #n ")" ::: "memory")
; #define PG8_WAIT_L(n) asm volatile("s_waitcnt lgkmcnt(" #n ")" ::: "memory")
; #define PG8_BAR __builtin_amdgcn_s_barrier()
; #define PG8_SCHED __builtin_amdgcn_sched_barrier(0)
; template <class Epi, class Sched>
; __device__ __forceinline__ void gemm_phase(PG8_LAS unsigned char* lds, const Gemm g, const Sched& S, const Epi& E) {
;     ...
;         const bool has_next = S.next(ui + 1, nxt);
;         const char* nA = has_next ? (const char*)g.A + (size_t)nxt.pm * tstepA : cA; const char* nB = has_next ? (const char*)g.Bt + (size_t)nxt.pn * tstepB : cB;
;         for (int t = 0; t < nt; t += 2) {
;             const bool last = (t == nt - 2);
;             const char* a1 = cA + (size_t)(t + 1) * kstep;
;             const char* a2 = last ? nA : cA + (size_t)(t + 2) * kstep; const char* b2 = last ? nB : cB + (size_t)(t + 2) * kstep;
;             const char* a3 = a2 + kstep; const char* b3 = b2 + kstep;
;             PG8_LDB(B0, 0, 0); PG8_LDB(B1, 0, 1); PG8_SCHED; PG8_LDA(At, 0, 0); PG8_STAGE(PG8_SA(1, 1), a1 + hstepA, voffA);
;             PG8_WAIT_V(8); PG8_WAIT_L(0); PG8_BAR; PG8_MMA(0, 0, At, B0); PG8_MMA(0, 1, At, B1); PG8_BAR; PG8_SCHED;
.LBB0_463:
	s_ashr_i32 s25, s24, 31
	s_lshl_b64 s[26:27], s[24:25], 19
	s_add_u32 s26, s50, s26
	s_addc_u32 s27, s51, s27
	s_and_b64 s[28:29], s[6:7], exec
	s_cselect_b32 s11, s27, s31
	s_cselect_b32 s13, s26, s30
	s_ashr_i32 s23, s22, 31
	s_lshl_b64 s[28:29], s[22:23], 19
	s_add_u32 s28, s61, s28
	s_addc_u32 s29, s85, s29
	s_and_b64 s[46:47], s[6:7], exec
	s_cselect_b32 s21, s29, s71
	s_cselect_b32 s23, s28, s70
	s_add_u32 s30, s30, 0x40080
	s_addc_u32 s31, s31, 0
	s_add_u32 s25, s70, 0x100
	v_mov_b32_e32 v2, 0
	s_addc_u32 s33, s71, 0
	s_mov_b32 s46, -2
	s_add_u32 s47, s30, 0xfffc0080
	s_addc_u32 s48, s31, -1
	s_add_i32 s49, 0, 0x10000
	s_cmp_eq_u32 s46, 12
	s_cselect_b32 s75, s11, s48
	s_cselect_b32 s74, s13, s47
	s_cselect_b32 s71, s21, s33
	s_cselect_b32 s70, s23, s25
	s_add_i32 s47, 0, 0x14000
	v_add_u32_e32 v106, s49, v1
	v_add_u32_e32 v158, s47, v1
	ds_read_b128 v[90:93], v106
	ds_read_b128 v[94:97], v106 offset:1024
	ds_read_b128 v[98:101], v106 offset:2048
	ds_read_b128 v[106:109], v106 offset:3072
	ds_read_b128 v[146:149], v158
	ds_read_b128 v[150:153], v158 offset:1024
	ds_read_b128 v[154:157], v158 offset:2048
	ds_read_b128 v[158:161], v158 offset:3072
	v_lshl_add_u64 v[226:227], s[30:31], 0, v[204:205]
	s_add_i32 m0, s86, 0xc000
	ds_read_b128 v[162:165], v232
	ds_read_b128 v[166:169], v232 offset:1024
	ds_read_b128 v[170:173], v232 offset:2048
	ds_read_b128 v[174:177], v232 offset:3072
	ds_read_b128 v[214:217], v232 offset:4096
	ds_read_b128 v[218:221], v232 offset:5120
	ds_read_b128 v[222:225], v232 offset:6144
	ds_read_b128 v[208:211], v232 offset:7168
	global_load_lds_dwordx4 v[226:227], off
	v_lshl_add_u64 v[226:227], s[30:31], 0, v[206:207]
	s_add_i32 m0, s86, 0xe000
	s_nop 0
	global_load_lds_dwordx4 v[226:227], off
	s_waitcnt vmcnt(8)
	s_waitcnt lgkmcnt(0)
	s_barrier
	s_setprio 1
	s_waitcnt lgkmcnt(0)
	v_mfma_f32_16x16x32_bf16 v[142:145], v[90:93], v[162:165], 0
	v_mfma_f32_16x16x32_bf16 v[138:141], v[98:101], v[162:165], 0
	v_mfma_f32_16x16x32_bf16 v[126:129], v[90:93], v[170:173], 0
	v_mfma_f32_16x16x32_bf16 v[122:125], v[98:101], v[170:173], 0
	v_mfma_f32_16x16x32_bf16 v[110:113], v[90:93], v[214:217], 0
	v_mfma_f32_16x16x32_bf16 v[102:105], v[98:101], v[214:217], 0
	v_mfma_f32_16x16x32_bf16 v[78:81], v[90:93], v[222:225], 0
	v_mfma_f32_16x16x32_bf16 v[74:77], v[98:101], v[222:225], 0
	v_mfma_f32_16x16x32_bf16 v[142:145], v[94:97], v[166:169], v[142:145]
	v_mfma_f32_16x16x32_bf16 v[138:141], v[106:109], v[166:169], v[138:141]
	v_mfma_f32_16x16x32_bf16 v[126:129], v[94:97], v[174:177], v[126:129]
	v_mfma_f32_16x16x32_bf16 v[122:125], v[106:109], v[174:177], v[122:125]
	v_mfma_f32_16x16x32_bf16 v[110:113], v[94:97], v[218:221], v[110:113]
	v_mfma_f32_16x16x32_bf16 v[102:105], v[106:109], v[218:221], v[102:105]
	v_mfma_f32_16x16x32_bf16 v[78:81], v[94:97], v[208:211], v[78:81]
	v_mfma_f32_16x16x32_bf16 v[74:77], v[106:109], v[208:211], v[74:77]
	s_setprio 0
	s_setprio 1
	v_mfma_f32_16x16x32_bf16 v[134:137], v[146:149], v[162:165], 0
	v_mfma_f32_16x16x32_bf16 v[130:133], v[154:157], v[162:165], 0
	v_mfma_f32_16x16x32_bf16 v[118:121], v[146:149], v[170:173], 0
	v_mfma_f32_16x16x32_bf16 v[114:117], v[154:157], v[170:173], 0
	v_mfma_f32_16x16x32_bf16 v[86:89], v[146:149], v[214:217], 0
	v_mfma_f32_16x16x32_bf16 v[82:85], v[154:157], v[214:217], 0
	v_mfma_f32_16x16x32_bf16 v[70:73], v[146:149], v[222:225], 0
	v_mfma_f32_16x16x32_bf16 v[66:69], v[154:157], v[222:225], 0
	v_mfma_f32_16x16x32_bf16 v[134:137], v[150:153], v[166:169], v[134:137]
	v_mfma_f32_16x16x32_bf16 v[130:133], v[158:161], v[166:169], v[130:133]
	v_mfma_f32_16x16x32_bf16 v[118:121], v[150:153], v[174:177], v[118:121]
	v_mfma_f32_16x16x32_bf16 v[114:117], v[158:161], v[174:177], v[114:117]
	v_mfma_f32_16x16x32_bf16 v[86:89], v[150:153], v[218:221], v[86:89]
	v_mfma_f32_16x16x32_bf16 v[82:85], v[158:161], v[218:221], v[82:85]
	v_mfma_f32_16x16x32_bf16 v[70:73], v[150:153], v[208:211], v[70:73]
	v_mfma_f32_16x16x32_bf16 v[66:69], v[158:161], v[208:211], v[66:69]
	s_setprio 0
	s_barrier
; #define PG8_STAGE(bufoff, gbase, voff) do { _Pragma("unroll") for (int _i = 0; _i < 2; ++_i) \
;         __builtin_amdgcn_global_load_lds((const unsigned*)((const char*)(gbase) + (voff)[_i]), (PG8_LAS unsigned*)(lds + (bufoff) + ldsw + _i * 8192), 16, 0, 0); } while (0)
; #define PG8_LDA(dst, b, h) do { _Pragma("unroll") for (int m = 0; m < 4; ++m) _Pragma("unroll") for (int k = 0; k < 2; ++k) dst[m][k] = *(const PG8_LAS bf16x8*)(lds + PG8_SA(b, h) + aoff + m * 2048 + k * 1024); } while (0)
; #define PG8_MMA(ai, bj, At, Bt) do { __builtin_amdgcn_s_setprio(1); _Pragma("unroll") for (int m = 0; m < 4; ++m) _Pragma("unroll") for (int n = 0; n < 2; ++n) _Pragma("unroll") for (int k = 0; k < 2; ++k) \
;         acc[ai][bj][m][n] = __builtin_amdgcn_mfma_f32_16x16x32_bf16(Bt[n][k], At[m][k], acc[ai][bj][m][n], 0, 0, 0); __builtin_amdgcn_s_setprio(0); } while (0)
; #define PG8_WAIT_V(n) asm volatile("s_waitcnt vmcnt(" #n ")" ::: "memory")
; #define PG8_WAIT_L(n) asm volatile("s_waitcnt lgkmcnt(" #n ")" ::: "memory")
; #define PG8_BAR __builtin_amdgcn_s_barrier()
; #define PG8_SCHED __builtin_amdgcn_sched_barrier(0)
; template <class Epi, class Sched>
; __device__ __forceinline__ void gemm_phase(PG8_LAS unsigned char* lds, const Gemm g, const Sched& S, const Epi& E) {
;     ...
;             PG8_LDA(At, 0, 1); PG8_STAGE(PG8_SB(0, 0), b2, voffB); PG8_STAGE(PG8_SB(0, 1), b2 + hstepB, voffB); PG8_STAGE(PG8_SA(0, 0), a2, voffA);
;             PG8_WAIT_V(8); PG8_WAIT_L(0); PG8_BAR; PG8_MMA(1, 0, At, B0); PG8_MMA(1, 1, At, B1); PG8_BAR; PG8_SCHED;
	s_add_i32 s48, s49, s60
	v_lshl_add_u64 v[226:227], s[70:71], 0, v[182:183]
	s_mov_b32 m0, s48
	ds_read_b128 v[162:165], v232 offset:16384
	ds_read_b128 v[166:169], v232 offset:17408
	ds_read_b128 v[170:173], v232 offset:18432
	ds_read_b128 v[174:177], v232 offset:19456
	ds_read_b128 v[208:211], v232 offset:20480
	ds_read_b128 v[214:217], v232 offset:21504
	ds_read_b128 v[218:221], v232 offset:22528
	ds_read_b128 v[222:225], v232 offset:23552
	global_load_lds_dwordx4 v[226:227], off
	s_add_i32 m0, s48, 0x2000
	s_add_u32 s48, s70, 0x40000
	v_lshl_add_u64 v[242:243], s[70:71], 0, v[178:179]
	s_addc_u32 s49, s71, 0
	s_add_i32 s47, s47, s60
	global_load_lds_dwordx4 v[242:243], off
	v_lshl_add_u64 v[250:251], s[48:49], 0, v[182:183]
	s_mov_b32 m0, s47
	v_lshl_add_u64 v[246:247], s[74:75], 0, v[180:181]
	global_load_lds_dwordx4 v[250:251], off
	v_lshl_add_u64 v[250:251], s[48:49], 0, v[178:179]
	s_add_i32 m0, s47, 0x2000
	s_nop 0
	global_load_lds_dwordx4 v[250:251], off
	v_lshl_add_u64 v[250:251], s[74:75], 0, v[184:185]
	s_mov_b32 m0, s86
	s_nop 0
	global_load_lds_dwordx4 v[250:251], off
	s_mov_b32 m0, s87
	s_nop 0
	global_load_lds_dwordx4 v[246:247], off
	s_waitcnt vmcnt(8)
	s_waitcnt lgkmcnt(0)
	s_barrier
	s_setprio 1
	s_waitcnt lgkmcnt(0)
	v_mfma_f32_16x16x32_bf16 v[62:65], v[90:93], v[162:165], 0
	v_mfma_f32_16x16x32_bf16 v[58:61], v[98:101], v[162:165], 0
	v_mfma_f32_16x16x32_bf16 v[46:49], v[90:93], v[170:173], 0
	v_mfma_f32_16x16x32_bf16 v[42:45], v[98:101], v[170:173], 0
	v_mfma_f32_16x16x32_bf16 v[30:33], v[90:93], v[208:211], 0
	v_mfma_f32_16x16x32_bf16 v[26:29], v[98:101], v[208:211], 0
	v_mfma_f32_16x16x32_bf16 v[14:17], v[90:93], v[218:221], 0
	v_mfma_f32_16x16x32_bf16 v[10:13], v[98:101], v[218:221], 0
	v_mfma_f32_16x16x32_bf16 v[62:65], v[94:97], v[166:169], v[62:65]
	v_mfma_f32_16x16x32_bf16 v[58:61], v[106:109], v[166:169], v[58:61]
	v_mfma_f32_16x16x32_bf16 v[46:49], v[94:97], v[174:177], v[46:49]
	v_mfma_f32_16x16x32_bf16 v[42:45], v[106:109], v[174:177], v[42:45]
	v_mfma_f32_16x16x32_bf16 v[30:33], v[94:97], v[214:217], v[30:33]
	v_mfma_f32_16x16x32_bf16 v[26:29], v[106:109], v[214:217], v[26:29]
	v_mfma_f32_16x16x32_bf16 v[14:17], v[94:97], v[222:225], v[14:17]
	v_mfma_f32_16x16x32_bf16 v[10:13], v[106:109], v[222:225], v[10:13]
	s_setprio 0
	s_setprio 1
	v_mfma_f32_16x16x32_bf16 v[54:57], v[146:149], v[162:165], 0
	v_mfma_f32_16x16x32_bf16 v[50:53], v[154:157], v[162:165], 0
	v_mfma_f32_16x16x32_bf16 v[38:41], v[146:149], v[170:173], 0
	v_mfma_f32_16x16x32_bf16 v[34:37], v[154:157], v[170:173], 0
	v_mfma_f32_16x16x32_bf16 v[22:25], v[146:149], v[208:211], 0
	v_mfma_f32_16x16x32_bf16 v[18:21], v[154:157], v[208:211], 0
	v_mfma_f32_16x16x32_bf16 v[6:9], v[146:149], v[218:221], 0
	v_mfma_f32_16x16x32_bf16 v[2:5], v[154:157], v[218:221], 0
	v_mfma_f32_16x16x32_bf16 v[54:57], v[150:153], v[166:169], v[54:57]
	v_mfma_f32_16x16x32_bf16 v[50:53], v[158:161], v[166:169], v[50:53]
	v_mfma_f32_16x16x32_bf16 v[38:41], v[150:153], v[174:177], v[38:41]
	v_mfma_f32_16x16x32_bf16 v[34:37], v[158:161], v[174:177], v[34:37]
	v_mfma_f32_16x16x32_bf16 v[22:25], v[150:153], v[214:217], v[22:25]
	v_mfma_f32_16x16x32_bf16 v[18:21], v[158:161], v[214:217], v[18:21]
	v_mfma_f32_16x16x32_bf16 v[6:9], v[150:153], v[222:225], v[6:9]
	v_mfma_f32_16x16x32_bf16 v[2:5], v[158:161], v[222:225], v[2:5]
	s_setprio 0
	s_barrier
	s_branch .Lpeel_mid_464

; #define PG8_STAGE(bufoff, gbase, voff) do { _Pragma("unroll") for (int _i = 0; _i < 2; ++_i) \
;         __builtin_amdgcn_global_load_lds((const unsigned*)((const char*)(gbase) + (voff)[_i]), (PG8_LAS unsigned*)(lds + (bufoff) + ldsw + _i * 8192), 16, 0, 0); } while (0)
; #define PG8_LDA(dst, b, h) do { _Pragma("unroll") for (int m = 0; m < 4; ++m) _Pragma("unroll") for (int k = 0; k < 2; ++k) dst[m][k] = *(const PG8_LAS bf16x8*)(lds + PG8_SA(b, h) + aoff + m * 2048 + k * 1024); } while (0)
; #define PG8_LDB(dst, b, h) do { _Pragma("unroll") for (int n = 0; n < 2; ++n) _Pragma("unroll") for (int k = 0; k < 2; ++k) dst[n][k] = *(const PG8_LAS bf16x8*)(lds + PG8_SB(b, h) + boff + n * 2048 + k * 1024); } while (0)
; #define PG8_MMA(ai, bj, At, Bt) do { __builtin_amdgcn_s_setprio(1); _Pragma("unroll") for (int m = 0; m < 4; ++m) _Pragma("unroll") for (int n = 0; n < 2; ++n) _Pragma("unroll") for (int k = 0; k < 2; ++k) \
;         acc[ai][bj][m][n] = __builtin_amdgcn_mfma_f32_16x16x32_bf16(Bt[n][k], At[m][k], acc[ai][bj][m][n], 0, 0, 0); __builtin_amdgcn_s_setprio(0); } while (0)
; #define PG8_WAIT_V(n) asm volatile("s_waitcnt vmcnt(" #n ")" ::: "memory")
; #define PG8_WAIT_L(n) asm volatile("s_waitcnt lgkmcnt(" #n ")" ::: "memory")
; #define PG8_BAR __builtin_amdgcn_s_barrier()
; #define PG8_SCHED __builtin_amdgcn_sched_barrier(0)
; template <class Epi, class Sched>
; __device__ __forceinline__ void gemm_phase(PG8_LAS unsigned char* lds, const Gemm g, const Sched& S, const Epi& E) {
;     ...
;             PG8_LDB(B0, 1, 0); PG8_LDB(B1, 1, 1); PG8_SCHED; PG8_LDA(At, 1, 0); PG8_STAGE(PG8_SA(0, 1), a2 + hstepA, voffA);
;             PG8_WAIT_V(8); PG8_WAIT_L(0); PG8_BAR; PG8_MMA(0, 0, At, B0); PG8_MMA(0, 1, At, B1); PG8_BAR; PG8_SCHED;
.Lpeel_mid_464:
	s_add_i32 s47, 0, 0x18000
	s_add_i32 s57, 0, 0x1c000
	v_add_u32_e32 v106, s47, v1
	v_add_u32_e32 v158, s57, v1
	ds_read_b128 v[90:93], v106
	ds_read_b128 v[94:97], v106 offset:1024
	ds_read_b128 v[98:101], v106 offset:2048
	ds_read_b128 v[106:109], v106 offset:3072
	ds_read_b128 v[146:149], v158
	ds_read_b128 v[150:153], v158 offset:1024
	ds_read_b128 v[154:157], v158 offset:2048
	ds_read_b128 v[158:161], v158 offset:3072
	s_add_u32 s48, s74, 0x40000
	s_addc_u32 s49, s75, 0
	s_mov_b32 m0, s90
	v_lshl_add_u64 v[212:213], s[48:49], 0, v[184:185]
	ds_read_b128 v[162:165], v232 offset:32768
	ds_read_b128 v[166:169], v232 offset:33792
	ds_read_b128 v[170:173], v232 offset:34816
	ds_read_b128 v[174:177], v232 offset:35840
	ds_read_b128 v[208:211], v232 offset:36864
	ds_read_b128 v[214:217], v232 offset:37888
	ds_read_b128 v[218:221], v232 offset:38912
	ds_read_b128 v[222:225], v232 offset:39936
	global_load_lds_dwordx4 v[212:213], off
	v_lshl_add_u64 v[212:213], s[48:49], 0, v[180:181]
	s_mov_b32 m0, s91
	s_nop 0
	global_load_lds_dwordx4 v[212:213], off
	s_waitcnt vmcnt(8)
	s_waitcnt lgkmcnt(0)
	s_barrier
	s_setprio 1
	s_waitcnt lgkmcnt(0)
	v_mfma_f32_16x16x32_bf16 v[142:145], v[90:93], v[162:165], v[142:145]
	v_mfma_f32_16x16x32_bf16 v[138:141], v[98:101], v[162:165], v[138:141]
	v_mfma_f32_16x16x32_bf16 v[126:129], v[90:93], v[170:173], v[126:129]
	v_mfma_f32_16x16x32_bf16 v[122:125], v[98:101], v[170:173], v[122:125]
	v_mfma_f32_16x16x32_bf16 v[110:113], v[90:93], v[208:211], v[110:113]
	v_mfma_f32_16x16x32_bf16 v[102:105], v[98:101], v[208:211], v[102:105]
	v_mfma_f32_16x16x32_bf16 v[78:81], v[90:93], v[218:221], v[78:81]
	v_mfma_f32_16x16x32_bf16 v[74:77], v[98:101], v[218:221], v[74:77]
	v_mfma_f32_16x16x32_bf16 v[142:145], v[94:97], v[166:169], v[142:145]
	v_mfma_f32_16x16x32_bf16 v[138:141], v[106:109], v[166:169], v[138:141]
	v_mfma_f32_16x16x32_bf16 v[126:129], v[94:97], v[174:177], v[126:129]
	v_mfma_f32_16x16x32_bf16 v[122:125], v[106:109], v[174:177], v[122:125]
	v_mfma_f32_16x16x32_bf16 v[110:113], v[94:97], v[214:217], v[110:113]
	v_mfma_f32_16x16x32_bf16 v[102:105], v[106:109], v[214:217], v[102:105]
	v_mfma_f32_16x16x32_bf16 v[78:81], v[94:97], v[222:225], v[78:81]
	v_mfma_f32_16x16x32_bf16 v[74:77], v[106:109], v[222:225], v[74:77]
	s_setprio 0
	s_setprio 1
	v_mfma_f32_16x16x32_bf16 v[134:137], v[146:149], v[162:165], v[134:137]
	v_mfma_f32_16x16x32_bf16 v[130:133], v[154:157], v[162:165], v[130:133]
	v_mfma_f32_16x16x32_bf16 v[118:121], v[146:149], v[170:173], v[118:121]
	v_mfma_f32_16x16x32_bf16 v[114:117], v[154:157], v[170:173], v[114:117]
	v_mfma_f32_16x16x32_bf16 v[86:89], v[146:149], v[208:211], v[86:89]
	v_mfma_f32_16x16x32_bf16 v[82:85], v[154:157], v[208:211], v[82:85]
	v_mfma_f32_16x16x32_bf16 v[70:73], v[146:149], v[218:221], v[70:73]
	v_mfma_f32_16x16x32_bf16 v[66:69], v[154:157], v[218:221], v[66:69]
	v_mfma_f32_16x16x32_bf16 v[134:137], v[150:153], v[166:169], v[134:137]
	v_mfma_f32_16x16x32_bf16 v[130:133], v[158:161], v[166:169], v[130:133]
	v_mfma_f32_16x16x32_bf16 v[118:121], v[150:153], v[174:177], v[118:121]
	v_mfma_f32_16x16x32_bf16 v[114:117], v[158:161], v[174:177], v[114:117]
	v_mfma_f32_16x16x32_bf16 v[86:89], v[150:153], v[214:217], v[86:89]
	v_mfma_f32_16x16x32_bf16 v[82:85], v[158:161], v[214:217], v[82:85]
	v_mfma_f32_16x16x32_bf16 v[70:73], v[150:153], v[222:225], v[70:73]
	v_mfma_f32_16x16x32_bf16 v[66:69], v[158:161], v[222:225], v[66:69]
	s_setprio 0
	s_barrier
; #define PG8_STAGE(bufoff, gbase, voff) do { _Pragma("unroll") for (int _i = 0; _i < 2; ++_i) \
;         __builtin_amdgcn_global_load_lds((const unsigned*)((const char*)(gbase) + (voff)[_i]), (PG8_LAS unsigned*)(lds + (bufoff) + ldsw + _i * 8192), 16, 0, 0); } while (0)
; #define PG8_LDA(dst, b, h) do { _Pragma("unroll") for (int m = 0; m < 4; ++m) _Pragma("unroll") for (int k = 0; k < 2; ++k) dst[m][k] = *(const PG8_LAS bf16x8*)(lds + PG8_SA(b, h) + aoff + m * 2048 + k * 1024); } while (0)
; #define PG8_MMA(ai, bj, At, Bt) do { __builtin_amdgcn_s_setprio(1); _Pragma("unroll") for (int m = 0; m < 4; ++m) _Pragma("unroll") for (int n = 0; n < 2; ++n) _Pragma("unroll") for (int k = 0; k < 2; ++k) \
;         acc[ai][bj][m][n] = __builtin_amdgcn_mfma_f32_16x16x32_bf16(Bt[n][k], At[m][k], acc[ai][bj][m][n], 0, 0, 0); __builtin_amdgcn_s_setprio(0); } while (0)
; #define PG8_WAIT_V(n) asm volatile("s_waitcnt vmcnt(" #n ")" ::: "memory")
; #define PG8_WAIT_L(n) asm volatile("s_waitcnt lgkmcnt(" #n ")" ::: "memory")
; #define PG8_BAR __builtin_amdgcn_s_barrier()
; #define PG8_SCHED __builtin_amdgcn_sched_barrier(0)
; template <class Epi, class Sched>
; __device__ __forceinline__ void gemm_phase(PG8_LAS unsigned char* lds, const Gemm g, const Sched& S, const Epi& E) {
;     ...
;             PG8_LDA(At, 1, 1); PG8_STAGE(PG8_SB(1, 0), b3, voffB); PG8_STAGE(PG8_SB(1, 1), b3 + hstepB, voffB); PG8_STAGE(PG8_SA(1, 0), a3, voffA);
;             PG8_WAIT_V(8); PG8_WAIT_L(0); PG8_BAR; PG8_MMA(1, 0, At, B0); PG8_MMA(1, 1, At, B1); PG8_BAR; PG8_SCHED;
;         }
	s_add_i32 s47, s47, s60
	v_lshl_add_u64 v[212:213], v[226:227], 0, s[78:79]
	s_mov_b32 m0, s47
	ds_read_b128 v[162:165], v232 offset:49152
	ds_read_b128 v[166:169], v232 offset:50176
	ds_read_b128 v[170:173], v232 offset:51200
	ds_read_b128 v[174:177], v232 offset:52224
	ds_read_b128 v[208:211], v232 offset:53248
	ds_read_b128 v[214:217], v232 offset:54272
	ds_read_b128 v[218:221], v232 offset:55296
	ds_read_b128 v[222:225], v232 offset:56320
	global_load_lds_dwordx4 v[212:213], off
	s_add_i32 m0, s47, 0x2000
	s_add_u32 s48, s70, 0x40080
	v_lshl_add_u64 v[212:213], v[242:243], 0, s[78:79]
	s_addc_u32 s49, s71, 0
	s_add_i32 s47, s57, s60
	global_load_lds_dwordx4 v[212:213], off
	v_lshl_add_u64 v[212:213], s[48:49], 0, v[182:183]
	s_mov_b32 m0, s47
	s_nop 0
	global_load_lds_dwordx4 v[212:213], off
	v_lshl_add_u64 v[212:213], s[48:49], 0, v[178:179]
	s_add_i32 m0, s47, 0x2000
	s_nop 0
	global_load_lds_dwordx4 v[212:213], off
	v_lshl_add_u64 v[212:213], v[250:251], 0, s[78:79]
	s_mov_b32 m0, s93
	s_nop 0
	global_load_lds_dwordx4 v[212:213], off
	v_lshl_add_u64 v[212:213], v[246:247], 0, s[78:79]
	s_mov_b32 m0, s94
	s_nop 0
	global_load_lds_dwordx4 v[212:213], off
	s_waitcnt vmcnt(8)
	s_waitcnt lgkmcnt(0)
	s_barrier
	s_setprio 1
	s_waitcnt lgkmcnt(0)
	v_mfma_f32_16x16x32_bf16 v[62:65], v[90:93], v[162:165], v[62:65]
	v_mfma_f32_16x16x32_bf16 v[58:61], v[98:101], v[162:165], v[58:61]
	v_mfma_f32_16x16x32_bf16 v[46:49], v[90:93], v[170:173], v[46:49]
	v_mfma_f32_16x16x32_bf16 v[42:45], v[98:101], v[170:173], v[42:45]
	v_mfma_f32_16x16x32_bf16 v[30:33], v[90:93], v[208:211], v[30:33]
	v_mfma_f32_16x16x32_bf16 v[26:29], v[98:101], v[208:211], v[26:29]
	v_mfma_f32_16x16x32_bf16 v[14:17], v[90:93], v[218:221], v[14:17]
	v_mfma_f32_16x16x32_bf16 v[10:13], v[98:101], v[218:221], v[10:13]
	v_mfma_f32_16x16x32_bf16 v[62:65], v[94:97], v[166:169], v[62:65]
	v_mfma_f32_16x16x32_bf16 v[58:61], v[106:109], v[166:169], v[58:61]
	v_mfma_f32_16x16x32_bf16 v[46:49], v[94:97], v[174:177], v[46:49]
	v_mfma_f32_16x16x32_bf16 v[42:45], v[106:109], v[174:177], v[42:45]
	v_mfma_f32_16x16x32_bf16 v[30:33], v[94:97], v[214:217], v[30:33]
	v_mfma_f32_16x16x32_bf16 v[26:29], v[106:109], v[214:217], v[26:29]
	v_mfma_f32_16x16x32_bf16 v[14:17], v[94:97], v[222:225], v[14:17]
	v_mfma_f32_16x16x32_bf16 v[10:13], v[106:109], v[222:225], v[10:13]
	s_setprio 0
	s_setprio 1
	v_mfma_f32_16x16x32_bf16 v[54:57], v[146:149], v[162:165], v[54:57]
	v_mfma_f32_16x16x32_bf16 v[50:53], v[154:157], v[162:165], v[50:53]
	v_mfma_f32_16x16x32_bf16 v[38:41], v[146:149], v[170:173], v[38:41]
	v_mfma_f32_16x16x32_bf16 v[34:37], v[154:157], v[170:173], v[34:37]
	v_mfma_f32_16x16x32_bf16 v[22:25], v[146:149], v[208:211], v[22:25]
	v_mfma_f32_16x16x32_bf16 v[18:21], v[154:157], v[208:211], v[18:21]
	v_mfma_f32_16x16x32_bf16 v[6:9], v[146:149], v[218:221], v[6:9]
	v_mfma_f32_16x16x32_bf16 v[2:5], v[154:157], v[218:221], v[2:5]
	v_mfma_f32_16x16x32_bf16 v[54:57], v[150:153], v[166:169], v[54:57]
	v_mfma_f32_16x16x32_bf16 v[50:53], v[158:161], v[166:169], v[50:53]
	v_mfma_f32_16x16x32_bf16 v[38:41], v[150:153], v[174:177], v[38:41]
	v_mfma_f32_16x16x32_bf16 v[34:37], v[158:161], v[174:177], v[34:37]
	v_mfma_f32_16x16x32_bf16 v[22:25], v[150:153], v[214:217], v[22:25]
	v_mfma_f32_16x16x32_bf16 v[18:21], v[158:161], v[214:217], v[18:21]
	v_mfma_f32_16x16x32_bf16 v[6:9], v[150:153], v[222:225], v[6:9]
	v_mfma_f32_16x16x32_bf16 v[2:5], v[158:161], v[222:225], v[2:5]
	s_setprio 0
	s_barrier
	s_add_i32 s46, s46, 2
	s_add_u32 s30, s30, 0x100
	s_addc_u32 s31, s31, 0
	s_add_u32 s25, s25, 0x100
	s_addc_u32 s33, s33, 0
	s_cmp_gt_u32 s46, 13
	s_cbranch_scc0 .LBB0_464
	s_and_b64 vcc, exec, s[18:19]
	s_cbranch_vccz .LBB0_467
	s_barrier

; #define PG8_STAGE(bufoff, gbase, voff) do { _Pragma("unroll") for (int _i = 0; _i < 2; ++_i) \
;         __builtin_amdgcn_global_load_lds((const unsigned*)((const char*)(gbase) + (voff)[_i]), (PG8_LAS unsigned*)(lds + (bufoff) + ldsw + _i * 8192), 16, 0, 0); } while (0)
; #define PG8_LDA(dst, b, h) do { _Pragma("unroll") for (int m = 0; m < 4; ++m) _Pragma("unroll") for (int k = 0; k < 2; ++k) dst[m][k] = *(const PG8_LAS bf16x8*)(lds + PG8_SA(b, h) + aoff + m * 2048 + k * 1024); } while (0)
; #define PG8_LDB(dst, b, h) do { _Pragma("unroll") for (int n = 0; n < 2; ++n) _Pragma("unroll") for (int k = 0; k < 2; ++k) dst[n][k] = *(const PG8_LAS bf16x8*)(lds + PG8_SB(b, h) + boff + n * 2048 + k * 1024); } while (0)
; #define PG8_MMA(ai, bj, At, Bt) do { __builtin_amdgcn_s_setprio(1); _Pragma("unroll") for (int m = 0; m < 4; ++m) _Pragma("unroll") for (int n = 0; n < 2; ++n) _Pragma("unroll") for (int k = 0; k < 2; ++k) \
;         acc[ai][bj][m][n] = __builtin_amdgcn_mfma_f32_16x16x32_bf16(Bt[n][k], At[m][k], acc[ai][bj][m][n], 0, 0, 0); __builtin_amdgcn_s_setprio(0); } while (0)
; #define PG8_WAIT_V(n) asm volatile("s_waitcnt vmcnt(" #n ")" ::: "memory")
; #define PG8_WAIT_L(n) asm volatile("s_waitcnt lgkmcnt(" #n ")" ::: "memory")
; #define PG8_BAR __builtin_amdgcn_s_barrier()
; #define PG8_SCHED __builtin_amdgcn_sched_barrier(0)
; template <class Epi, class Sched>
; __device__ __forceinline__ void gemm_phase(PG8_LAS unsigned char* lds, const Gemm g, const Sched& S, const Epi& E) {
;     ...
;         const bool has_next = S.next(ui + 1, nxt);
;         const char* nA = has_next ? (const char*)g.A + (size_t)nxt.pm * tstepA : cA; const char* nB = has_next ? (const char*)g.Bt + (size_t)nxt.pn * tstepB : cB;
;         for (int t = 0; t < nt; t += 2) {
;             const bool last = (t == nt - 2);
;             const char* a1 = cA + (size_t)(t + 1) * kstep;
;             const char* a2 = last ? nA : cA + (size_t)(t + 2) * kstep; const char* b2 = last ? nB : cB + (size_t)(t + 2) * kstep;
;             const char* a3 = a2 + kstep; const char* b3 = b2 + kstep;
;             PG8_LDB(B0, 0, 0); PG8_LDB(B1, 0, 1); PG8_SCHED; PG8_LDA(At, 0, 0); PG8_STAGE(PG8_SA(1, 1), a1 + hstepA, voffA);
;             PG8_WAIT_V(8); PG8_WAIT_L(0); PG8_BAR; PG8_MMA(0, 0, At, B0); PG8_MMA(0, 1, At, B1); PG8_BAR; PG8_SCHED;
.LBB0_580:
	s_ashr_i32 s11, s10, 31
	s_lshl_b64 s[16:17], s[10:11], 19
	s_add_u32 s16, s36, s16
	s_addc_u32 s17, s37, s17
	s_and_b64 s[18:19], s[20:21], exec
	s_cselect_b32 s33, s17, s23
	s_cselect_b32 s46, s16, s22
	s_ashr_i32 s15, s14, 31
	s_lshl_b64 s[18:19], s[14:15], 19
	s_add_u32 s18, s29, s18
	s_addc_u32 s19, s30, s19
	s_and_b64 s[26:27], s[20:21], exec
	s_cselect_b32 s15, s19, s25
	s_cselect_b32 s47, s18, s24
	s_add_u32 s22, s22, 0x40080
	s_addc_u32 s23, s23, 0
	s_add_u32 s48, s24, 0x100
	v_mov_b32_e32 v2, 0
	s_addc_u32 s49, s25, 0
	s_mov_b32 s57, -2
	s_add_u32 s24, s22, 0xfffc0080
	s_addc_u32 s25, s23, -1
	s_add_i32 s58, 0, 0x10000
	s_cmp_eq_u32 s57, 12
	s_cselect_b32 s27, s33, s25
	s_cselect_b32 s26, s46, s24
	v_add_u32_e32 v148, s58, v150
	s_cselect_b32 s25, s15, s49
	s_cselect_b32 s24, s47, s48
	s_add_i32 s64, 0, 0x14000
	ds_read_b128 v[98:101], v148
	ds_read_b128 v[156:159], v148 offset:1024
	ds_read_b128 v[160:163], v148 offset:2048
	ds_read_b128 v[164:167], v148 offset:3072
	v_add_u32_e32 v148, s64, v150
	ds_read_b128 v[168:171], v148
	ds_read_b128 v[172:175], v148 offset:1024
	ds_read_b128 v[176:179], v148 offset:2048
	ds_read_b128 v[180:183], v148 offset:3072
	v_lshl_add_u64 v[148:149], s[22:23], 0, v[144:145]
	s_add_i32 m0, s31, 0xc000
	ds_read_b128 v[184:187], v154
	ds_read_b128 v[188:191], v154 offset:1024
	ds_read_b128 v[192:195], v154 offset:2048
	ds_read_b128 v[196:199], v154 offset:3072
	ds_read_b128 v[200:203], v154 offset:4096
	ds_read_b128 v[204:207], v154 offset:5120
	ds_read_b128 v[208:211], v154 offset:6144
	ds_read_b128 v[214:217], v154 offset:7168
	global_load_lds_dwordx4 v[148:149], off
	v_lshl_add_u64 v[148:149], s[22:23], 0, v[146:147]
	s_add_i32 m0, s31, 0xe000
	s_nop 0
	global_load_lds_dwordx4 v[148:149], off
	s_waitcnt vmcnt(8)
	s_waitcnt lgkmcnt(0)
	s_barrier
	s_setprio 1
	s_waitcnt lgkmcnt(0)
	v_mfma_f32_16x16x32_bf16 v[130:133], v[98:101], v[184:187], 0
	v_mfma_f32_16x16x32_bf16 v[126:129], v[160:163], v[184:187], 0
	v_mfma_f32_16x16x32_bf16 v[114:117], v[98:101], v[192:195], 0
	v_mfma_f32_16x16x32_bf16 v[110:113], v[160:163], v[192:195], 0
	v_mfma_f32_16x16x32_bf16 v[94:97], v[98:101], v[200:203], 0
	v_mfma_f32_16x16x32_bf16 v[90:93], v[160:163], v[200:203], 0
	v_mfma_f32_16x16x32_bf16 v[78:81], v[98:101], v[208:211], 0
	v_mfma_f32_16x16x32_bf16 v[74:77], v[160:163], v[208:211], 0
	v_mfma_f32_16x16x32_bf16 v[130:133], v[156:159], v[188:191], v[130:133]
	v_mfma_f32_16x16x32_bf16 v[126:129], v[164:167], v[188:191], v[126:129]
	v_mfma_f32_16x16x32_bf16 v[114:117], v[156:159], v[196:199], v[114:117]
	v_mfma_f32_16x16x32_bf16 v[110:113], v[164:167], v[196:199], v[110:113]
	v_mfma_f32_16x16x32_bf16 v[94:97], v[156:159], v[204:207], v[94:97]
	v_mfma_f32_16x16x32_bf16 v[90:93], v[164:167], v[204:207], v[90:93]
	v_mfma_f32_16x16x32_bf16 v[78:81], v[156:159], v[214:217], v[78:81]
	v_mfma_f32_16x16x32_bf16 v[74:77], v[164:167], v[214:217], v[74:77]
	s_setprio 0
	s_setprio 1
	v_mfma_f32_16x16x32_bf16 v[122:125], v[168:171], v[184:187], 0
	v_mfma_f32_16x16x32_bf16 v[118:121], v[176:179], v[184:187], 0
	v_mfma_f32_16x16x32_bf16 v[106:109], v[168:171], v[192:195], 0
	v_mfma_f32_16x16x32_bf16 v[102:105], v[176:179], v[192:195], 0
	v_mfma_f32_16x16x32_bf16 v[86:89], v[168:171], v[200:203], 0
	v_mfma_f32_16x16x32_bf16 v[82:85], v[176:179], v[200:203], 0
	v_mfma_f32_16x16x32_bf16 v[70:73], v[168:171], v[208:211], 0
	v_mfma_f32_16x16x32_bf16 v[66:69], v[176:179], v[208:211], 0
	v_mfma_f32_16x16x32_bf16 v[122:125], v[172:175], v[188:191], v[122:125]
	v_mfma_f32_16x16x32_bf16 v[118:121], v[180:183], v[188:191], v[118:121]
	v_mfma_f32_16x16x32_bf16 v[106:109], v[172:175], v[196:199], v[106:109]
	v_mfma_f32_16x16x32_bf16 v[102:105], v[180:183], v[196:199], v[102:105]
	v_mfma_f32_16x16x32_bf16 v[86:89], v[172:175], v[204:207], v[86:89]
	v_mfma_f32_16x16x32_bf16 v[82:85], v[180:183], v[204:207], v[82:85]
	v_mfma_f32_16x16x32_bf16 v[70:73], v[172:175], v[214:217], v[70:73]
	v_mfma_f32_16x16x32_bf16 v[66:69], v[180:183], v[214:217], v[66:69]
	s_setprio 0
	s_barrier
; #define PG8_STAGE(bufoff, gbase, voff) do { _Pragma("unroll") for (int _i = 0; _i < 2; ++_i) \
;         __builtin_amdgcn_global_load_lds((const unsigned*)((const char*)(gbase) + (voff)[_i]), (PG8_LAS unsigned*)(lds + (bufoff) + ldsw + _i * 8192), 16, 0, 0); } while (0)
; #define PG8_LDA(dst, b, h) do { _Pragma("unroll") for (int m = 0; m < 4; ++m) _Pragma("unroll") for (int k = 0; k < 2; ++k) dst[m][k] = *(const PG8_LAS bf16x8*)(lds + PG8_SA(b, h) + aoff + m * 2048 + k * 1024); } while (0)
; #define PG8_MMA(ai, bj, At, Bt) do { __builtin_amdgcn_s_setprio(1); _Pragma("unroll") for (int m = 0; m < 4; ++m) _Pragma("unroll") for (int n = 0; n < 2; ++n) _Pragma("unroll") for (int k = 0; k < 2; ++k) \
;         acc[ai][bj][m][n] = __builtin_amdgcn_mfma_f32_16x16x32_bf16(Bt[n][k], At[m][k], acc[ai][bj][m][n], 0, 0, 0); __builtin_amdgcn_s_setprio(0); } while (0)
; #define PG8_WAIT_V(n) asm volatile("s_waitcnt vmcnt(" #n ")" ::: "memory")
; #define PG8_WAIT_L(n) asm volatile("s_waitcnt lgkmcnt(" #n ")" ::: "memory")
; #define PG8_BAR __builtin_amdgcn_s_barrier()
; #define PG8_SCHED __builtin_amdgcn_sched_barrier(0)
; template <class Epi, class Sched>
; __device__ __forceinline__ void gemm_phase(PG8_LAS unsigned char* lds, const Gemm g, const Sched& S, const Epi& E) {
;     ...
;             PG8_LDA(At, 0, 1); PG8_STAGE(PG8_SB(0, 0), b2, voffB); PG8_STAGE(PG8_SB(0, 1), b2 + hstepB, voffB); PG8_STAGE(PG8_SA(0, 0), a2, voffA);
;             PG8_WAIT_V(8); PG8_WAIT_L(0); PG8_BAR; PG8_MMA(1, 0, At, B0); PG8_MMA(1, 1, At, B1); PG8_BAR; PG8_SCHED;
	s_add_i32 s58, s58, s28
	v_lshl_add_u64 v[148:149], s[24:25], 0, v[136:137]
	s_mov_b32 m0, s58
	ds_read_b128 v[184:187], v154 offset:16384
	ds_read_b128 v[188:191], v154 offset:17408
	ds_read_b128 v[192:195], v154 offset:18432
	ds_read_b128 v[196:199], v154 offset:19456
	ds_read_b128 v[200:203], v154 offset:20480
	ds_read_b128 v[204:207], v154 offset:21504
	ds_read_b128 v[208:211], v154 offset:22528
	ds_read_b128 v[214:217], v154 offset:23552
	global_load_lds_dwordx4 v[148:149], off
	s_add_i32 m0, s58, 0x2000
	s_add_u32 s58, s24, 0x40000
	v_lshl_add_u64 v[212:213], s[24:25], 0, v[140:141]
	s_addc_u32 s59, s25, 0
	s_add_i32 s64, s64, s28
	global_load_lds_dwordx4 v[212:213], off
	v_lshl_add_u64 v[218:219], s[58:59], 0, v[136:137]
	s_mov_b32 m0, s64
	v_lshl_add_u64 v[220:221], s[26:27], 0, v[138:139]
	global_load_lds_dwordx4 v[218:219], off
	v_lshl_add_u64 v[218:219], s[58:59], 0, v[140:141]
	s_add_i32 m0, s64, 0x2000
	s_nop 0
	global_load_lds_dwordx4 v[218:219], off
	v_lshl_add_u64 v[218:219], s[26:27], 0, v[134:135]
	s_mov_b32 m0, s31
	s_nop 0
	global_load_lds_dwordx4 v[218:219], off
	s_mov_b32 m0, s60
	s_nop 0
	global_load_lds_dwordx4 v[220:221], off
	s_waitcnt vmcnt(8)
	s_waitcnt lgkmcnt(0)
	s_barrier
	s_setprio 1
	s_waitcnt lgkmcnt(0)
	v_mfma_f32_16x16x32_bf16 v[62:65], v[98:101], v[184:187], 0
	v_mfma_f32_16x16x32_bf16 v[58:61], v[160:163], v[184:187], 0
	v_mfma_f32_16x16x32_bf16 v[46:49], v[98:101], v[192:195], 0
	v_mfma_f32_16x16x32_bf16 v[42:45], v[160:163], v[192:195], 0
	v_mfma_f32_16x16x32_bf16 v[30:33], v[98:101], v[200:203], 0
	v_mfma_f32_16x16x32_bf16 v[26:29], v[160:163], v[200:203], 0
	v_mfma_f32_16x16x32_bf16 v[14:17], v[98:101], v[208:211], 0
	v_mfma_f32_16x16x32_bf16 v[10:13], v[160:163], v[208:211], 0
	v_mfma_f32_16x16x32_bf16 v[62:65], v[156:159], v[188:191], v[62:65]
	v_mfma_f32_16x16x32_bf16 v[58:61], v[164:167], v[188:191], v[58:61]
	v_mfma_f32_16x16x32_bf16 v[46:49], v[156:159], v[196:199], v[46:49]
	v_mfma_f32_16x16x32_bf16 v[42:45], v[164:167], v[196:199], v[42:45]
	v_mfma_f32_16x16x32_bf16 v[30:33], v[156:159], v[204:207], v[30:33]
	v_mfma_f32_16x16x32_bf16 v[26:29], v[164:167], v[204:207], v[26:29]
	v_mfma_f32_16x16x32_bf16 v[14:17], v[156:159], v[214:217], v[14:17]
	v_mfma_f32_16x16x32_bf16 v[10:13], v[164:167], v[214:217], v[10:13]
	s_setprio 0
	s_setprio 1
	v_mfma_f32_16x16x32_bf16 v[54:57], v[168:171], v[184:187], 0
	v_mfma_f32_16x16x32_bf16 v[50:53], v[176:179], v[184:187], 0
	v_mfma_f32_16x16x32_bf16 v[38:41], v[168:171], v[192:195], 0
	v_mfma_f32_16x16x32_bf16 v[34:37], v[176:179], v[192:195], 0
	v_mfma_f32_16x16x32_bf16 v[22:25], v[168:171], v[200:203], 0
	v_mfma_f32_16x16x32_bf16 v[18:21], v[176:179], v[200:203], 0
	v_mfma_f32_16x16x32_bf16 v[6:9], v[168:171], v[208:211], 0
	v_mfma_f32_16x16x32_bf16 v[2:5], v[176:179], v[208:211], 0
	v_mfma_f32_16x16x32_bf16 v[54:57], v[172:175], v[188:191], v[54:57]
	v_mfma_f32_16x16x32_bf16 v[50:53], v[180:183], v[188:191], v[50:53]
	v_mfma_f32_16x16x32_bf16 v[38:41], v[172:175], v[196:199], v[38:41]
	v_mfma_f32_16x16x32_bf16 v[34:37], v[180:183], v[196:199], v[34:37]
	v_mfma_f32_16x16x32_bf16 v[22:25], v[172:175], v[204:207], v[22:25]
	v_mfma_f32_16x16x32_bf16 v[18:21], v[180:183], v[204:207], v[18:21]
	v_mfma_f32_16x16x32_bf16 v[6:9], v[172:175], v[214:217], v[6:9]
	v_mfma_f32_16x16x32_bf16 v[2:5], v[180:183], v[214:217], v[2:5]
	s_setprio 0
	s_barrier
	s_branch .Lpeel_mid_581

; #define PG8_STAGE(bufoff, gbase, voff) do { _Pragma("unroll") for (int _i = 0; _i < 2; ++_i) \
;         __builtin_amdgcn_global_load_lds((const unsigned*)((const char*)(gbase) + (voff)[_i]), (PG8_LAS unsigned*)(lds + (bufoff) + ldsw + _i * 8192), 16, 0, 0); } while (0)
; #define PG8_LDA(dst, b, h) do { _Pragma("unroll") for (int m = 0; m < 4; ++m) _Pragma("unroll") for (int k = 0; k < 2; ++k) dst[m][k] = *(const PG8_LAS bf16x8*)(lds + PG8_SA(b, h) + aoff + m * 2048 + k * 1024); } while (0)
; #define PG8_LDB(dst, b, h) do { _Pragma("unroll") for (int n = 0; n < 2; ++n) _Pragma("unroll") for (int k = 0; k < 2; ++k) dst[n][k] = *(const PG8_LAS bf16x8*)(lds + PG8_SB(b, h) + boff + n * 2048 + k * 1024); } while (0)
; #define PG8_MMA(ai, bj, At, Bt) do { __builtin_amdgcn_s_setprio(1); _Pragma("unroll") for (int m = 0; m < 4; ++m) _Pragma("unroll") for (int n = 0; n < 2; ++n) _Pragma("unroll") for (int k = 0; k < 2; ++k) \
;         acc[ai][bj][m][n] = __builtin_amdgcn_mfma_f32_16x16x32_bf16(Bt[n][k], At[m][k], acc[ai][bj][m][n], 0, 0, 0); __builtin_amdgcn_s_setprio(0); } while (0)
; #define PG8_WAIT_V(n) asm volatile("s_waitcnt vmcnt(" #n ")" ::: "memory")
; #define PG8_WAIT_L(n) asm volatile("s_waitcnt lgkmcnt(" #n ")" ::: "memory")
; #define PG8_BAR __builtin_amdgcn_s_barrier()
; #define PG8_SCHED __builtin_amdgcn_sched_barrier(0)
; template <class Epi, class Sched>
; __device__ __forceinline__ void gemm_phase(PG8_LAS unsigned char* lds, const Gemm g, const Sched& S, const Epi& E) {
;     ...
;             PG8_LDB(B0, 1, 0); PG8_LDB(B1, 1, 1); PG8_SCHED; PG8_LDA(At, 1, 0); PG8_STAGE(PG8_SA(0, 1), a2 + hstepA, voffA);
;             PG8_WAIT_V(8); PG8_WAIT_L(0); PG8_BAR; PG8_MMA(0, 0, At, B0); PG8_MMA(0, 1, At, B1); PG8_BAR; PG8_SCHED;
.Lpeel_mid_581:
	s_add_i32 s58, 0, 0x18000
	v_add_u32_e32 v155, s58, v150
	s_add_i32 s59, 0, 0x1c000
	ds_read_b128 v[98:101], v155
	ds_read_b128 v[156:159], v155 offset:1024
	ds_read_b128 v[160:163], v155 offset:2048
	ds_read_b128 v[164:167], v155 offset:3072
	v_add_u32_e32 v155, s59, v150
	ds_read_b128 v[168:171], v155
	ds_read_b128 v[172:175], v155 offset:1024
	ds_read_b128 v[176:179], v155 offset:2048
	ds_read_b128 v[180:183], v155 offset:3072
	s_add_u32 s26, s26, 0x40000
	s_addc_u32 s27, s27, 0
	s_mov_b32 m0, s61
	v_lshl_add_u64 v[222:223], s[26:27], 0, v[134:135]
	ds_read_b128 v[184:187], v154 offset:32768
	ds_read_b128 v[188:191], v154 offset:33792
	ds_read_b128 v[192:195], v154 offset:34816
	ds_read_b128 v[196:199], v154 offset:35840
	ds_read_b128 v[200:203], v154 offset:36864
	ds_read_b128 v[204:207], v154 offset:37888
	ds_read_b128 v[208:211], v154 offset:38912
	ds_read_b128 v[214:217], v154 offset:39936
	global_load_lds_dwordx4 v[222:223], off
	v_lshl_add_u64 v[222:223], s[26:27], 0, v[138:139]
	s_mov_b32 m0, s70
	s_nop 0
	global_load_lds_dwordx4 v[222:223], off
	s_waitcnt vmcnt(8)
	s_waitcnt lgkmcnt(0)
	s_barrier
	s_setprio 1
	s_waitcnt lgkmcnt(0)
	v_mfma_f32_16x16x32_bf16 v[130:133], v[98:101], v[184:187], v[130:133]
	v_mfma_f32_16x16x32_bf16 v[126:129], v[160:163], v[184:187], v[126:129]
	v_mfma_f32_16x16x32_bf16 v[114:117], v[98:101], v[192:195], v[114:117]
	v_mfma_f32_16x16x32_bf16 v[110:113], v[160:163], v[192:195], v[110:113]
	v_mfma_f32_16x16x32_bf16 v[94:97], v[98:101], v[200:203], v[94:97]
	v_mfma_f32_16x16x32_bf16 v[90:93], v[160:163], v[200:203], v[90:93]
	v_mfma_f32_16x16x32_bf16 v[78:81], v[98:101], v[208:211], v[78:81]
	v_mfma_f32_16x16x32_bf16 v[74:77], v[160:163], v[208:211], v[74:77]
	v_mfma_f32_16x16x32_bf16 v[130:133], v[156:159], v[188:191], v[130:133]
	v_mfma_f32_16x16x32_bf16 v[126:129], v[164:167], v[188:191], v[126:129]
	v_mfma_f32_16x16x32_bf16 v[114:117], v[156:159], v[196:199], v[114:117]
	v_mfma_f32_16x16x32_bf16 v[110:113], v[164:167], v[196:199], v[110:113]
	v_mfma_f32_16x16x32_bf16 v[94:97], v[156:159], v[204:207], v[94:97]
	v_mfma_f32_16x16x32_bf16 v[90:93], v[164:167], v[204:207], v[90:93]
	v_mfma_f32_16x16x32_bf16 v[78:81], v[156:159], v[214:217], v[78:81]
	v_mfma_f32_16x16x32_bf16 v[74:77], v[164:167], v[214:217], v[74:77]
	s_setprio 0
	s_setprio 1
	v_mfma_f32_16x16x32_bf16 v[122:125], v[168:171], v[184:187], v[122:125]
	v_mfma_f32_16x16x32_bf16 v[118:121], v[176:179], v[184:187], v[118:121]
	v_mfma_f32_16x16x32_bf16 v[106:109], v[168:171], v[192:195], v[106:109]
	v_mfma_f32_16x16x32_bf16 v[102:105], v[176:179], v[192:195], v[102:105]
	v_mfma_f32_16x16x32_bf16 v[86:89], v[168:171], v[200:203], v[86:89]
	v_mfma_f32_16x16x32_bf16 v[82:85], v[176:179], v[200:203], v[82:85]
	v_mfma_f32_16x16x32_bf16 v[70:73], v[168:171], v[208:211], v[70:73]
	v_mfma_f32_16x16x32_bf16 v[66:69], v[176:179], v[208:211], v[66:69]
	v_mfma_f32_16x16x32_bf16 v[122:125], v[172:175], v[188:191], v[122:125]
	v_mfma_f32_16x16x32_bf16 v[118:121], v[180:183], v[188:191], v[118:121]
	v_mfma_f32_16x16x32_bf16 v[106:109], v[172:175], v[196:199], v[106:109]
	v_mfma_f32_16x16x32_bf16 v[102:105], v[180:183], v[196:199], v[102:105]
	v_mfma_f32_16x16x32_bf16 v[86:89], v[172:175], v[204:207], v[86:89]
	v_mfma_f32_16x16x32_bf16 v[82:85], v[180:183], v[204:207], v[82:85]
	v_mfma_f32_16x16x32_bf16 v[70:73], v[172:175], v[214:217], v[70:73]
	v_mfma_f32_16x16x32_bf16 v[66:69], v[180:183], v[214:217], v[66:69]
	s_setprio 0
	s_barrier
; #define PG8_STAGE(bufoff, gbase, voff) do { _Pragma("unroll") for (int _i = 0; _i < 2; ++_i) \
;         __builtin_amdgcn_global_load_lds((const unsigned*)((const char*)(gbase) + (voff)[_i]), (PG8_LAS unsigned*)(lds + (bufoff) + ldsw + _i * 8192), 16, 0, 0); } while (0)
; #define PG8_LDA(dst, b, h) do { _Pragma("unroll") for (int m = 0; m < 4; ++m) _Pragma("unroll") for (int k = 0; k < 2; ++k) dst[m][k] = *(const PG8_LAS bf16x8*)(lds + PG8_SA(b, h) + aoff + m * 2048 + k * 1024); } while (0)
; #define PG8_MMA(ai, bj, At, Bt) do { __builtin_amdgcn_s_setprio(1); _Pragma("unroll") for (int m = 0; m < 4; ++m) _Pragma("unroll") for (int n = 0; n < 2; ++n) _Pragma("unroll") for (int k = 0; k < 2; ++k) \
;         acc[ai][bj][m][n] = __builtin_amdgcn_mfma_f32_16x16x32_bf16(Bt[n][k], At[m][k], acc[ai][bj][m][n], 0, 0, 0); __builtin_amdgcn_s_setprio(0); } while (0)
; #define PG8_WAIT_V(n) asm volatile("s_waitcnt vmcnt(" #n ")" ::: "memory")
; #define PG8_WAIT_L(n) asm volatile("s_waitcnt lgkmcnt(" #n ")" ::: "memory")
; #define PG8_BAR __builtin_amdgcn_s_barrier()
; #define PG8_SCHED __builtin_amdgcn_sched_barrier(0)
; template <class Epi, class Sched>
; __device__ __forceinline__ void gemm_phase(PG8_LAS unsigned char* lds, const Gemm g, const Sched& S, const Epi& E) {
;     ...
;             PG8_LDA(At, 1, 1); PG8_STAGE(PG8_SB(1, 0), b3, voffB); PG8_STAGE(PG8_SB(1, 1), b3 + hstepB, voffB); PG8_STAGE(PG8_SA(1, 0), a3, voffA);
;             PG8_WAIT_V(8); PG8_WAIT_L(0); PG8_BAR; PG8_MMA(1, 0, At, B0); PG8_MMA(1, 1, At, B1); PG8_BAR; PG8_SCHED;
;         }
;         if (wr == 0) PG8_BAR;
	s_add_i32 s26, s58, s28
	v_lshl_add_u64 v[148:149], v[148:149], 0, s[78:79]
	s_mov_b32 m0, s26
	ds_read_b128 v[184:187], v154 offset:49152
	ds_read_b128 v[188:191], v154 offset:50176
	ds_read_b128 v[192:195], v154 offset:51200
	ds_read_b128 v[196:199], v154 offset:52224
	ds_read_b128 v[200:203], v154 offset:53248
	ds_read_b128 v[204:207], v154 offset:54272
	ds_read_b128 v[208:211], v154 offset:55296
	ds_read_b128 v[214:217], v154 offset:56320
	global_load_lds_dwordx4 v[148:149], off
	s_add_i32 m0, s26, 0x2000
	s_add_u32 s24, s24, 0x40080
	v_lshl_add_u64 v[148:149], v[212:213], 0, s[78:79]
	s_addc_u32 s25, s25, 0
	s_add_i32 s26, s59, s28
	global_load_lds_dwordx4 v[148:149], off
	v_lshl_add_u64 v[148:149], s[24:25], 0, v[136:137]
	s_mov_b32 m0, s26
	s_nop 0
	global_load_lds_dwordx4 v[148:149], off
	v_lshl_add_u64 v[148:149], s[24:25], 0, v[140:141]
	s_add_i32 m0, s26, 0x2000
	s_nop 0
	global_load_lds_dwordx4 v[148:149], off
	v_lshl_add_u64 v[148:149], v[218:219], 0, s[78:79]
	s_mov_b32 m0, s71
	s_nop 0
	global_load_lds_dwordx4 v[148:149], off
	v_lshl_add_u64 v[148:149], v[220:221], 0, s[78:79]
	s_mov_b32 m0, s74
	s_nop 0
	global_load_lds_dwordx4 v[148:149], off
	s_waitcnt vmcnt(8)
	s_waitcnt lgkmcnt(0)
	s_barrier
	s_setprio 1
	s_waitcnt lgkmcnt(0)
	v_mfma_f32_16x16x32_bf16 v[62:65], v[98:101], v[184:187], v[62:65]
	v_mfma_f32_16x16x32_bf16 v[58:61], v[160:163], v[184:187], v[58:61]
	v_mfma_f32_16x16x32_bf16 v[46:49], v[98:101], v[192:195], v[46:49]
	v_mfma_f32_16x16x32_bf16 v[42:45], v[160:163], v[192:195], v[42:45]
	v_mfma_f32_16x16x32_bf16 v[30:33], v[98:101], v[200:203], v[30:33]
	v_mfma_f32_16x16x32_bf16 v[26:29], v[160:163], v[200:203], v[26:29]
	v_mfma_f32_16x16x32_bf16 v[14:17], v[98:101], v[208:211], v[14:17]
	v_mfma_f32_16x16x32_bf16 v[10:13], v[160:163], v[208:211], v[10:13]
	v_mfma_f32_16x16x32_bf16 v[62:65], v[156:159], v[188:191], v[62:65]
	v_mfma_f32_16x16x32_bf16 v[58:61], v[164:167], v[188:191], v[58:61]
	v_mfma_f32_16x16x32_bf16 v[46:49], v[156:159], v[196:199], v[46:49]
	v_mfma_f32_16x16x32_bf16 v[42:45], v[164:167], v[196:199], v[42:45]
	v_mfma_f32_16x16x32_bf16 v[30:33], v[156:159], v[204:207], v[30:33]
	v_mfma_f32_16x16x32_bf16 v[26:29], v[164:167], v[204:207], v[26:29]
	v_mfma_f32_16x16x32_bf16 v[14:17], v[156:159], v[214:217], v[14:17]
	v_mfma_f32_16x16x32_bf16 v[10:13], v[164:167], v[214:217], v[10:13]
	s_setprio 0
	s_setprio 1
	v_mfma_f32_16x16x32_bf16 v[54:57], v[168:171], v[184:187], v[54:57]
	v_mfma_f32_16x16x32_bf16 v[50:53], v[176:179], v[184:187], v[50:53]
	v_mfma_f32_16x16x32_bf16 v[38:41], v[168:171], v[192:195], v[38:41]
	v_mfma_f32_16x16x32_bf16 v[34:37], v[176:179], v[192:195], v[34:37]
	v_mfma_f32_16x16x32_bf16 v[22:25], v[168:171], v[200:203], v[22:25]
	v_mfma_f32_16x16x32_bf16 v[18:21], v[176:179], v[200:203], v[18:21]
	v_mfma_f32_16x16x32_bf16 v[6:9], v[168:171], v[208:211], v[6:9]
	v_mfma_f32_16x16x32_bf16 v[2:5], v[176:179], v[208:211], v[2:5]
	v_mfma_f32_16x16x32_bf16 v[54:57], v[172:175], v[188:191], v[54:57]
	v_mfma_f32_16x16x32_bf16 v[50:53], v[180:183], v[188:191], v[50:53]
	v_mfma_f32_16x16x32_bf16 v[38:41], v[172:175], v[196:199], v[38:41]
	v_mfma_f32_16x16x32_bf16 v[34:37], v[180:183], v[196:199], v[34:37]
	v_mfma_f32_16x16x32_bf16 v[22:25], v[172:175], v[204:207], v[22:25]
	v_mfma_f32_16x16x32_bf16 v[18:21], v[180:183], v[204:207], v[18:21]
	v_mfma_f32_16x16x32_bf16 v[6:9], v[172:175], v[214:217], v[6:9]
	v_mfma_f32_16x16x32_bf16 v[2:5], v[180:183], v[214:217], v[2:5]
	s_setprio 0
	s_barrier
	s_add_i32 s57, s57, 2
	s_add_u32 s22, s22, 0x100
	s_addc_u32 s23, s23, 0
	s_add_u32 s48, s48, 0x100
	s_addc_u32 s49, s49, 0
	s_cmp_gt_u32 s57, 13
	s_cbranch_scc0 .LBB0_581
	s_and_b64 vcc, exec, s[8:9]
	s_cbranch_vccz .LBB0_584
	s_barrier

; __device__ __forceinline__ unsigned cvt_pk_bf16(float lo, float hi) { unsigned r; asm volatile("v_cvt_pk_bf16_f32 %0, %1, %2" : "=v"(r) : "v"(lo), "v"(hi)); return r; }
; #define LAS __attribute__((address_space(3)))
; __device__ __forceinline__ float sigmoid_f(float x) { return __builtin_amdgcn_rcpf(1.0f + __builtin_amdgcn_exp2f(-1.4426950408889634f * x)); }
;     __device__ __forceinline__ void operator()(const f32x4 (&acc)[2][2][4][2], const pg8::Unit& u, int wr, int wc, int fr, int fq, LAS unsigned char* lds, int wid, int lane, const pg8::Unit& nxt, bool has_next, int ui) const {
;         const int row0 = u.pm * 256 + wr * 64 + fr, col = u.pn * 128 + wc * 32 + fq * 8, tid = wid * 64 + lane;
;         const LAS float* R = (const LAS float*)(lds + RS_OFF) + (ui & 1) * 256;
;         const bool pre = has_next && tid < 256; f32x4 qn = (f32x4){1.f, 1.f, 1.f, 1.f};
;         if (pre) qn = *(const f32x4*)(rss + ((size_t)nxt.pm * 256 + tid) * 4);
; #pragma unroll
;         for (int ai = 0; ai < 2; ++ai) {
; #pragma unroll
;             for (int m = 0; m < 4; ++m) {
;                 const int row = row0 + ai * 128 + m * 16; const float r_ = R[wr * 64 + fr + ai * 128 + m * 16];
;                 const f32x4 g0 = acc[ai][0][m][0] * r_, g1 = acc[ai][0][m][1] * r_, u0 = acc[ai][1][m][0] * r_, u1 = acc[ai][1][m][1] * r_;
;                 v4u w;
;                 w.x = cvt_pk_bf16(g0[0] * sigmoid_f(g0[0]) * u0[0], g0[1] * sigmoid_f(g0[1]) * u0[1]); w.y = cvt_pk_bf16(g0[2] * sigmoid_f(g0[2]) * u0[2], g0[3] * sigmoid_f(g0[3]) * u0[3]);
;                 w.z = cvt_pk_bf16(g1[0] * sigmoid_f(g1[0]) * u1[0], g1[1] * sigmoid_f(g1[1]) * u1[1]); w.w = cvt_pk_bf16(g1[2] * sigmoid_f(g1[2]) * u1[2], g1[3] * sigmoid_f(g1[3]) * u1[3]);
;                 *(v4u*)(ACT + (size_t)row * FF + col) = w;
.LBB0_586:
	s_or_b64 exec, exec, s[22:23]
	s_lshl_b32 s11, s82, 8
	s_and_b32 s11, s11, 0x100
	v_lshl_add_u32 v155, s11, 2, v151
	ds_read_b32 v227, v155
	v_lshl_or_b32 v148, s12, 7, v153
	v_lshl_add_u32 v156, s13, 8, v1
	v_ashrrev_i32_e32 v149, 31, v148
	v_lshlrev_b64 v[224:225], 1, v[148:149]
	v_lshl_add_u64 v[224:225], v[224:225], 0, s[40:41]
	s_waitcnt lgkmcnt(0)
	ds_read_b32 v232, v155 offset:64
	v_mul_f32_e32 v230, 0xbfb8aa3b, v227
	v_mul_f32_e32 v231, v227, v227
	v_rcp_f32_e32 v231, v231
	v_mul_f32_e32 v122, v130, v122
	v_mul_f32_e32 v123, v131, v123
	v_mul_f32_e32 v124, v132, v124
	v_mul_f32_e32 v125, v133, v125
	v_mul_f32_e32 v118, v126, v118
	v_mul_f32_e32 v119, v127, v119
	v_mul_f32_e32 v120, v128, v120
	v_mul_f32_e32 v121, v129, v121
	v_mul_f32_e32 v130, v230, v130
	v_mul_f32_e32 v131, v230, v131
	v_mul_f32_e32 v132, v230, v132
	v_mul_f32_e32 v133, v230, v133
	v_mul_f32_e32 v126, v230, v126
	v_mul_f32_e32 v127, v230, v127
	v_mul_f32_e32 v128, v230, v128
	v_mul_f32_e32 v129, v230, v129
	v_exp_f32_e32 v130, v130
	v_exp_f32_e32 v131, v131
	v_exp_f32_e32 v132, v132
	v_exp_f32_e32 v133, v133
	v_exp_f32_e32 v126, v126
	v_exp_f32_e32 v127, v127
	v_exp_f32_e32 v128, v128
	v_exp_f32_e32 v129, v129
	v_fma_f32 v130, v130, v231, v231
	v_fma_f32 v131, v131, v231, v231
	v_fma_f32 v132, v132, v231, v231
	v_fma_f32 v133, v133, v231, v231
	v_fma_f32 v126, v126, v231, v231
	v_fma_f32 v127, v127, v231, v231
	v_fma_f32 v128, v128, v231, v231
	v_fma_f32 v129, v129, v231, v231
	v_rcp_f32_e32 v130, v130
	v_rcp_f32_e32 v131, v131
	v_rcp_f32_e32 v132, v132
	v_rcp_f32_e32 v133, v133
	v_rcp_f32_e32 v126, v126
	v_rcp_f32_e32 v127, v127
	v_rcp_f32_e32 v128, v128
	v_rcp_f32_e32 v129, v129
	v_mul_f32_e32 v122, v122, v130
	v_mul_f32_e32 v123, v123, v131
	v_mul_f32_e32 v124, v124, v132
	v_mul_f32_e32 v125, v125, v133
	v_mul_f32_e32 v118, v118, v126
	v_mul_f32_e32 v119, v119, v127
	v_mul_f32_e32 v120, v120, v128
	v_mul_f32_e32 v121, v121, v129
	v_cvt_pk_bf16_f32 v122, v122, v123
	v_cvt_pk_bf16_f32 v123, v124, v125
	v_cvt_pk_bf16_f32 v124, v118, v119
	v_cvt_pk_bf16_f32 v125, v120, v121
	v_mov_b32_e32 v226, v156
	v_mad_i64_i32 v[228:229], s[12:13], v226, s55, v[224:225]
	global_store_dwordx4 v[228:229], v[122:125], off
	s_waitcnt lgkmcnt(0)
	ds_read_b32 v227, v155 offset:128
	v_mul_f32_e32 v230, 0xbfb8aa3b, v232
	v_mul_f32_e32 v231, v232, v232
	v_rcp_f32_e32 v231, v231
	v_mul_f32_e32 v106, v114, v106
	v_mul_f32_e32 v107, v115, v107
	v_mul_f32_e32 v108, v116, v108
	v_mul_f32_e32 v109, v117, v109
	v_mul_f32_e32 v102, v110, v102
	v_mul_f32_e32 v103, v111, v103
	v_mul_f32_e32 v104, v112, v104
	v_mul_f32_e32 v105, v113, v105
	v_mul_f32_e32 v114, v230, v114
	v_mul_f32_e32 v115, v230, v115
	v_mul_f32_e32 v116, v230, v116
	v_mul_f32_e32 v117, v230, v117
	v_mul_f32_e32 v110, v230, v110
	v_mul_f32_e32 v111, v230, v111
	v_mul_f32_e32 v112, v230, v112
	v_mul_f32_e32 v113, v230, v113
	v_exp_f32_e32 v114, v114
	v_exp_f32_e32 v115, v115
	v_exp_f32_e32 v116, v116
	v_exp_f32_e32 v117, v117
	v_exp_f32_e32 v110, v110
	v_exp_f32_e32 v111, v111
	v_exp_f32_e32 v112, v112
	v_exp_f32_e32 v113, v113
	v_fma_f32 v114, v114, v231, v231
	v_fma_f32 v115, v115, v231, v231
	v_fma_f32 v116, v116, v231, v231
	v_fma_f32 v117, v117, v231, v231
	v_fma_f32 v110, v110, v231, v231
	v_fma_f32 v111, v111, v231, v231
	v_fma_f32 v112, v112, v231, v231
	v_fma_f32 v113, v113, v231, v231
	v_rcp_f32_e32 v114, v114
	v_rcp_f32_e32 v115, v115
	v_rcp_f32_e32 v116, v116
	v_rcp_f32_e32 v117, v117
	v_rcp_f32_e32 v110, v110
	v_rcp_f32_e32 v111, v111
	v_rcp_f32_e32 v112, v112
	v_rcp_f32_e32 v113, v113
	v_mul_f32_e32 v106, v106, v114
	v_mul_f32_e32 v107, v107, v115
	v_mul_f32_e32 v108, v108, v116
	v_mul_f32_e32 v109, v109, v117
	v_mul_f32_e32 v102, v102, v110
	v_mul_f32_e32 v103, v103, v111
	v_mul_f32_e32 v104, v104, v112
	v_mul_f32_e32 v105, v105, v113
	v_cvt_pk_bf16_f32 v106, v106, v107
	v_cvt_pk_bf16_f32 v107, v108, v109
	v_cvt_pk_bf16_f32 v108, v102, v103
	v_cvt_pk_bf16_f32 v109, v104, v105
	v_or_b32_e32 v226, 16, v156
	v_mad_i64_i32 v[228:229], s[12:13], v226, s55, v[224:225]
	global_store_dwordx4 v[228:229], v[106:109], off
	s_waitcnt lgkmcnt(0)
	ds_read_b32 v232, v155 offset:192
	v_mul_f32_e32 v230, 0xbfb8aa3b, v227
	v_mul_f32_e32 v231, v227, v227
	v_rcp_f32_e32 v231, v231
	v_mul_f32_e32 v86, v94, v86
	v_mul_f32_e32 v87, v95, v87
	v_mul_f32_e32 v88, v96, v88
	v_mul_f32_e32 v89, v97, v89
	v_mul_f32_e32 v82, v90, v82
	v_mul_f32_e32 v83, v91, v83
	v_mul_f32_e32 v84, v92, v84
	v_mul_f32_e32 v85, v93, v85
	v_mul_f32_e32 v94, v230, v94
	v_mul_f32_e32 v95, v230, v95
	v_mul_f32_e32 v96, v230, v96
	v_mul_f32_e32 v97, v230, v97
	v_mul_f32_e32 v90, v230, v90
	v_mul_f32_e32 v91, v230, v91
	v_mul_f32_e32 v92, v230, v92
	v_mul_f32_e32 v93, v230, v93
	v_exp_f32_e32 v94, v94
	v_exp_f32_e32 v95, v95
	v_exp_f32_e32 v96, v96
	v_exp_f32_e32 v97, v97
	v_exp_f32_e32 v90, v90
	v_exp_f32_e32 v91, v91
	v_exp_f32_e32 v92, v92
	v_exp_f32_e32 v93, v93
	v_fma_f32 v94, v94, v231, v231
	v_fma_f32 v95, v95, v231, v231
	v_fma_f32 v96, v96, v231, v231
	v_fma_f32 v97, v97, v231, v231
	v_fma_f32 v90, v90, v231, v231
	v_fma_f32 v91, v91, v231, v231
	v_fma_f32 v92, v92, v231, v231
	v_fma_f32 v93, v93, v231, v231
	v_rcp_f32_e32 v94, v94
	v_rcp_f32_e32 v95, v95
	v_rcp_f32_e32 v96, v96
	v_rcp_f32_e32 v97, v97
	v_rcp_f32_e32 v90, v90
	v_rcp_f32_e32 v91, v91
	v_rcp_f32_e32 v92, v92
	v_rcp_f32_e32 v93, v93
	v_mul_f32_e32 v86, v86, v94
	v_mul_f32_e32 v87, v87, v95
	v_mul_f32_e32 v88, v88, v96
	v_mul_f32_e32 v89, v89, v97
	v_mul_f32_e32 v82, v82, v90
	v_mul_f32_e32 v83, v83, v91
	v_mul_f32_e32 v84, v84, v92
	v_mul_f32_e32 v85, v85, v93
	v_cvt_pk_bf16_f32 v86, v86, v87
	v_cvt_pk_bf16_f32 v87, v88, v89
	v_cvt_pk_bf16_f32 v88, v82, v83
	v_cvt_pk_bf16_f32 v89, v84, v85
	v_or_b32_e32 v226, 32, v156
	v_mad_i64_i32 v[228:229], s[12:13], v226, s55, v[224:225]
	global_store_dwordx4 v[228:229], v[86:89], off
	s_waitcnt lgkmcnt(0)
; __device__ __forceinline__ unsigned cvt_pk_bf16(float lo, float hi) { unsigned r; asm volatile("v_cvt_pk_bf16_f32 %0, %1, %2" : "=v"(r) : "v"(lo), "v"(hi)); return r; }
; #define LAS __attribute__((address_space(3)))
; __device__ __forceinline__ float sigmoid_f(float x) { return __builtin_amdgcn_rcpf(1.0f + __builtin_amdgcn_exp2f(-1.4426950408889634f * x)); }
; __device__ __forceinline__ float rstd4(const f32x4 q) { return __builtin_amdgcn_rsqf(((q[0] + q[1]) + (q[2] + q[3])) * (1.0f / DM) + EPS); }
;     __device__ __forceinline__ void operator()(const f32x4 (&acc)[2][2][4][2], const pg8::Unit& u, int wr, int wc, int fr, int fq, LAS unsigned char* lds, int wid, int lane, const pg8::Unit& nxt, bool has_next, int ui) const {
;     ...
;             for (int m = 0; m < 4; ++m) {
;                 const int row = row0 + ai * 128 + m * 16; const float r_ = R[wr * 64 + fr + ai * 128 + m * 16];
;                 const f32x4 g0 = acc[ai][0][m][0] * r_, g1 = acc[ai][0][m][1] * r_, u0 = acc[ai][1][m][0] * r_, u1 = acc[ai][1][m][1] * r_;
;                 v4u w;
;                 w.x = cvt_pk_bf16(g0[0] * sigmoid_f(g0[0]) * u0[0], g0[1] * sigmoid_f(g0[1]) * u0[1]); w.y = cvt_pk_bf16(g0[2] * sigmoid_f(g0[2]) * u0[2], g0[3] * sigmoid_f(g0[3]) * u0[3]);
;                 w.z = cvt_pk_bf16(g1[0] * sigmoid_f(g1[0]) * u1[0], g1[1] * sigmoid_f(g1[1]) * u1[1]); w.w = cvt_pk_bf16(g1[2] * sigmoid_f(g1[2]) * u1[2], g1[3] * sigmoid_f(g1[3]) * u1[3]);
;                 *(v4u*)(ACT + (size_t)row * FF + col) = w;
;             }
;             if (ai == 0) {
;                 __builtin_amdgcn_sched_barrier(0);
;                 float rn = rstd4(qn); asm volatile("" : "+v"(rn));
;                 if (pre) ((LAS float*)(lds + RS_OFF))[((ui + 1) & 1) * 256 + tid] = rn;
;                 __builtin_amdgcn_sched_barrier(0);
	ds_read_b32 v227, v155 offset:512
	v_mul_f32_e32 v230, 0xbfb8aa3b, v232
	v_mul_f32_e32 v231, v232, v232
	v_rcp_f32_e32 v231, v231
	v_mul_f32_e32 v70, v78, v70
	v_mul_f32_e32 v71, v79, v71
	v_mul_f32_e32 v72, v80, v72
	v_mul_f32_e32 v73, v81, v73
	v_mul_f32_e32 v66, v74, v66
	v_mul_f32_e32 v67, v75, v67
	v_mul_f32_e32 v68, v76, v68
	v_mul_f32_e32 v69, v77, v69
	v_mul_f32_e32 v78, v230, v78
	v_mul_f32_e32 v79, v230, v79
	v_mul_f32_e32 v80, v230, v80
	v_mul_f32_e32 v81, v230, v81
	v_mul_f32_e32 v74, v230, v74
	v_mul_f32_e32 v75, v230, v75
	v_mul_f32_e32 v76, v230, v76
	v_mul_f32_e32 v77, v230, v77
	v_exp_f32_e32 v78, v78
	v_exp_f32_e32 v79, v79
	v_exp_f32_e32 v80, v80
	v_exp_f32_e32 v81, v81
	v_exp_f32_e32 v74, v74
	v_exp_f32_e32 v75, v75
	v_exp_f32_e32 v76, v76
	v_exp_f32_e32 v77, v77
	v_fma_f32 v78, v78, v231, v231
	v_fma_f32 v79, v79, v231, v231
	v_fma_f32 v80, v80, v231, v231
	v_fma_f32 v81, v81, v231, v231
	v_fma_f32 v74, v74, v231, v231
	v_fma_f32 v75, v75, v231, v231
	v_fma_f32 v76, v76, v231, v231
	v_fma_f32 v77, v77, v231, v231
	v_rcp_f32_e32 v78, v78
	v_rcp_f32_e32 v79, v79
	v_rcp_f32_e32 v80, v80
	v_rcp_f32_e32 v81, v81
	v_rcp_f32_e32 v74, v74
	v_rcp_f32_e32 v75, v75
	v_rcp_f32_e32 v76, v76
	v_rcp_f32_e32 v77, v77
	v_mul_f32_e32 v70, v70, v78
	v_mul_f32_e32 v71, v71, v79
	v_mul_f32_e32 v72, v72, v80
	v_mul_f32_e32 v73, v73, v81
	v_mul_f32_e32 v66, v66, v74
	v_mul_f32_e32 v67, v67, v75
	v_mul_f32_e32 v68, v68, v76
	v_mul_f32_e32 v69, v69, v77
	v_cvt_pk_bf16_f32 v70, v70, v71
	v_cvt_pk_bf16_f32 v71, v72, v73
	v_cvt_pk_bf16_f32 v72, v66, v67
	v_cvt_pk_bf16_f32 v73, v68, v69
	v_or_b32_e32 v226, 48, v156
	v_mad_i64_i32 v[228:229], s[12:13], v226, s55, v[224:225]
	global_store_dwordx4 v[228:229], v[70:73], off
	s_waitcnt vmcnt(4)
	s_nop 0
	v_add_f32_e32 v233, v98, v99
	v_add_f32_e32 v226, v100, v101
	v_add_f32_e32 v233, v233, v226
	v_fmamk_f32 v233, v233, 0x3a800000, v245
	v_rsq_f32_e32 v233, v233
	s_and_saveexec_b64 s[22:23], s[20:21]
	s_xor_b32 s11, s11, 0x100
	v_lshl_add_u32 v226, s11, 2, v152
	ds_write_b32 v226, v233
	s_or_b64 exec, exec, s[22:23]
	s_mov_b64 s[20:21], -1
	s_cmp_eq_u32 s82, 21
	s_waitcnt lgkmcnt(0)
	ds_read_b32 v232, v155 offset:576
	v_mul_f32_e32 v230, 0xbfb8aa3b, v227
	v_mul_f32_e32 v231, v227, v227
	v_rcp_f32_e32 v231, v231
	v_mul_f32_e32 v54, v62, v54
	v_mul_f32_e32 v55, v63, v55
	v_mul_f32_e32 v56, v64, v56
	v_mul_f32_e32 v57, v65, v57
	v_mul_f32_e32 v50, v58, v50
	v_mul_f32_e32 v51, v59, v51
	v_mul_f32_e32 v52, v60, v52
	v_mul_f32_e32 v53, v61, v53
	v_mul_f32_e32 v62, v230, v62
	v_mul_f32_e32 v63, v230, v63
	v_mul_f32_e32 v64, v230, v64
	v_mul_f32_e32 v65, v230, v65
	v_mul_f32_e32 v58, v230, v58
	v_mul_f32_e32 v59, v230, v59
	v_mul_f32_e32 v60, v230, v60
	v_mul_f32_e32 v61, v230, v61
	v_exp_f32_e32 v62, v62
	v_exp_f32_e32 v63, v63
	v_exp_f32_e32 v64, v64
	v_exp_f32_e32 v65, v65
	v_exp_f32_e32 v58, v58
	v_exp_f32_e32 v59, v59
	v_exp_f32_e32 v60, v60
	v_exp_f32_e32 v61, v61
	v_fma_f32 v62, v62, v231, v231
	v_fma_f32 v63, v63, v231, v231
	v_fma_f32 v64, v64, v231, v231
	v_fma_f32 v65, v65, v231, v231
	v_fma_f32 v58, v58, v231, v231
	v_fma_f32 v59, v59, v231, v231
	v_fma_f32 v60, v60, v231, v231
	v_fma_f32 v61, v61, v231, v231
	v_rcp_f32_e32 v62, v62
	v_rcp_f32_e32 v63, v63
	v_rcp_f32_e32 v64, v64
	v_rcp_f32_e32 v65, v65
	v_rcp_f32_e32 v58, v58
	v_rcp_f32_e32 v59, v59
	v_rcp_f32_e32 v60, v60
	v_rcp_f32_e32 v61, v61
	v_mul_f32_e32 v54, v54, v62
	v_mul_f32_e32 v55, v55, v63
	v_mul_f32_e32 v56, v56, v64
	v_mul_f32_e32 v57, v57, v65
	v_mul_f32_e32 v50, v50, v58
	v_mul_f32_e32 v51, v51, v59
	v_mul_f32_e32 v52, v52, v60
	v_mul_f32_e32 v53, v53, v61
	v_cvt_pk_bf16_f32 v54, v54, v55
	v_cvt_pk_bf16_f32 v55, v56, v57
	v_cvt_pk_bf16_f32 v56, v50, v51
	v_cvt_pk_bf16_f32 v57, v52, v53
	v_or_b32_e32 v226, 0x80, v156
	v_mad_i64_i32 v[228:229], s[12:13], v226, s55, v[224:225]
	global_store_dwordx4 v[228:229], v[54:57], off
	s_waitcnt lgkmcnt(0)
; __device__ __forceinline__ unsigned cvt_pk_bf16(float lo, float hi) { unsigned r; asm volatile("v_cvt_pk_bf16_f32 %0, %1, %2" : "=v"(r) : "v"(lo), "v"(hi)); return r; }
; __device__ __forceinline__ float sigmoid_f(float x) { return __builtin_amdgcn_rcpf(1.0f + __builtin_amdgcn_exp2f(-1.4426950408889634f * x)); }
;     __device__ __forceinline__ void operator()(const f32x4 (&acc)[2][2][4][2], const pg8::Unit& u, int wr, int wc, int fr, int fq, LAS unsigned char* lds, int wid, int lane, const pg8::Unit& nxt, bool has_next, int ui) const {
;     ...
;             for (int m = 0; m < 4; ++m) {
;                 const int row = row0 + ai * 128 + m * 16; const float r_ = R[wr * 64 + fr + ai * 128 + m * 16];
;                 const f32x4 g0 = acc[ai][0][m][0] * r_, g1 = acc[ai][0][m][1] * r_, u0 = acc[ai][1][m][0] * r_, u1 = acc[ai][1][m][1] * r_;
;                 v4u w;
;                 w.x = cvt_pk_bf16(g0[0] * sigmoid_f(g0[0]) * u0[0], g0[1] * sigmoid_f(g0[1]) * u0[1]); w.y = cvt_pk_bf16(g0[2] * sigmoid_f(g0[2]) * u0[2], g0[3] * sigmoid_f(g0[3]) * u0[3]);
;                 w.z = cvt_pk_bf16(g1[0] * sigmoid_f(g1[0]) * u1[0], g1[1] * sigmoid_f(g1[1]) * u1[1]); w.w = cvt_pk_bf16(g1[2] * sigmoid_f(g1[2]) * u1[2], g1[3] * sigmoid_f(g1[3]) * u1[3]);
;                 *(v4u*)(ACT + (size_t)row * FF + col) = w;
	ds_read_b32 v227, v155 offset:640
	v_mul_f32_e32 v230, 0xbfb8aa3b, v232
	v_mul_f32_e32 v231, v232, v232
	v_rcp_f32_e32 v231, v231
	v_mul_f32_e32 v38, v46, v38
	v_mul_f32_e32 v39, v47, v39
	v_mul_f32_e32 v40, v48, v40
	v_mul_f32_e32 v41, v49, v41
	v_mul_f32_e32 v34, v42, v34
	v_mul_f32_e32 v35, v43, v35
	v_mul_f32_e32 v36, v44, v36
	v_mul_f32_e32 v37, v45, v37
	v_mul_f32_e32 v46, v230, v46
	v_mul_f32_e32 v47, v230, v47
	v_mul_f32_e32 v48, v230, v48
	v_mul_f32_e32 v49, v230, v49
	v_mul_f32_e32 v42, v230, v42
	v_mul_f32_e32 v43, v230, v43
	v_mul_f32_e32 v44, v230, v44
	v_mul_f32_e32 v45, v230, v45
	v_exp_f32_e32 v46, v46
	v_exp_f32_e32 v47, v47
	v_exp_f32_e32 v48, v48
	v_exp_f32_e32 v49, v49
	v_exp_f32_e32 v42, v42
	v_exp_f32_e32 v43, v43
	v_exp_f32_e32 v44, v44
	v_exp_f32_e32 v45, v45
	v_fma_f32 v46, v46, v231, v231
	v_fma_f32 v47, v47, v231, v231
	v_fma_f32 v48, v48, v231, v231
	v_fma_f32 v49, v49, v231, v231
	v_fma_f32 v42, v42, v231, v231
	v_fma_f32 v43, v43, v231, v231
	v_fma_f32 v44, v44, v231, v231
	v_fma_f32 v45, v45, v231, v231
	v_rcp_f32_e32 v46, v46
	v_rcp_f32_e32 v47, v47
	v_rcp_f32_e32 v48, v48
	v_rcp_f32_e32 v49, v49
	v_rcp_f32_e32 v42, v42
	v_rcp_f32_e32 v43, v43
	v_rcp_f32_e32 v44, v44
	v_rcp_f32_e32 v45, v45
	v_mul_f32_e32 v38, v38, v46
	v_mul_f32_e32 v39, v39, v47
	v_mul_f32_e32 v40, v40, v48
	v_mul_f32_e32 v41, v41, v49
	v_mul_f32_e32 v34, v34, v42
	v_mul_f32_e32 v35, v35, v43
	v_mul_f32_e32 v36, v36, v44
	v_mul_f32_e32 v37, v37, v45
	v_cvt_pk_bf16_f32 v38, v38, v39
	v_cvt_pk_bf16_f32 v39, v40, v41
	v_cvt_pk_bf16_f32 v40, v34, v35
	v_cvt_pk_bf16_f32 v41, v36, v37
	v_or_b32_e32 v226, 0x90, v156
	v_mad_i64_i32 v[228:229], s[12:13], v226, s55, v[224:225]
	global_store_dwordx4 v[228:229], v[38:41], off
	s_waitcnt lgkmcnt(0)
	ds_read_b32 v232, v155 offset:704
	v_mul_f32_e32 v230, 0xbfb8aa3b, v227
	v_mul_f32_e32 v231, v227, v227
	v_rcp_f32_e32 v231, v231
	v_mul_f32_e32 v22, v30, v22
	v_mul_f32_e32 v23, v31, v23
	v_mul_f32_e32 v24, v32, v24
	v_mul_f32_e32 v25, v33, v25
	v_mul_f32_e32 v18, v26, v18
	v_mul_f32_e32 v19, v27, v19
	v_mul_f32_e32 v20, v28, v20
	v_mul_f32_e32 v21, v29, v21
	v_mul_f32_e32 v30, v230, v30
	v_mul_f32_e32 v31, v230, v31
	v_mul_f32_e32 v32, v230, v32
	v_mul_f32_e32 v33, v230, v33
	v_mul_f32_e32 v26, v230, v26
	v_mul_f32_e32 v27, v230, v27
	v_mul_f32_e32 v28, v230, v28
	v_mul_f32_e32 v29, v230, v29
	v_exp_f32_e32 v30, v30
	v_exp_f32_e32 v31, v31
	v_exp_f32_e32 v32, v32
	v_exp_f32_e32 v33, v33
	v_exp_f32_e32 v26, v26
	v_exp_f32_e32 v27, v27
	v_exp_f32_e32 v28, v28
	v_exp_f32_e32 v29, v29
	v_fma_f32 v30, v30, v231, v231
	v_fma_f32 v31, v31, v231, v231
	v_fma_f32 v32, v32, v231, v231
	v_fma_f32 v33, v33, v231, v231
	v_fma_f32 v26, v26, v231, v231
	v_fma_f32 v27, v27, v231, v231
	v_fma_f32 v28, v28, v231, v231
	v_fma_f32 v29, v29, v231, v231
	v_rcp_f32_e32 v30, v30
	v_rcp_f32_e32 v31, v31
	v_rcp_f32_e32 v32, v32
	v_rcp_f32_e32 v33, v33
	v_rcp_f32_e32 v26, v26
	v_rcp_f32_e32 v27, v27
	v_rcp_f32_e32 v28, v28
	v_rcp_f32_e32 v29, v29
	v_mul_f32_e32 v22, v22, v30
	v_mul_f32_e32 v23, v23, v31
	v_mul_f32_e32 v24, v24, v32
	v_mul_f32_e32 v25, v25, v33
	v_mul_f32_e32 v18, v18, v26
	v_mul_f32_e32 v19, v19, v27
	v_mul_f32_e32 v20, v20, v28
	v_mul_f32_e32 v21, v21, v29
	v_cvt_pk_bf16_f32 v22, v22, v23
	v_cvt_pk_bf16_f32 v23, v24, v25
	v_cvt_pk_bf16_f32 v24, v18, v19
	v_cvt_pk_bf16_f32 v25, v20, v21
	v_or_b32_e32 v226, 0xa0, v156
	v_mad_i64_i32 v[228:229], s[12:13], v226, s55, v[224:225]
	global_store_dwordx4 v[228:229], v[22:25], off
	s_waitcnt lgkmcnt(0)
	v_mul_f32_e32 v230, 0xbfb8aa3b, v232
	v_mul_f32_e32 v231, v232, v232
	v_rcp_f32_e32 v231, v231
	v_mul_f32_e32 v6, v14, v6
	v_mul_f32_e32 v7, v15, v7
	v_mul_f32_e32 v8, v16, v8
	v_mul_f32_e32 v9, v17, v9
	v_mul_f32_e32 v2, v10, v2
	v_mul_f32_e32 v3, v11, v3
	v_mul_f32_e32 v4, v12, v4
	v_mul_f32_e32 v5, v13, v5
	v_mul_f32_e32 v14, v230, v14
	v_mul_f32_e32 v15, v230, v15
	v_mul_f32_e32 v16, v230, v16
	v_mul_f32_e32 v17, v230, v17
	v_mul_f32_e32 v10, v230, v10
	v_mul_f32_e32 v11, v230, v11
	v_mul_f32_e32 v12, v230, v12
	v_mul_f32_e32 v13, v230, v13
	v_exp_f32_e32 v14, v14
	v_exp_f32_e32 v15, v15
	v_exp_f32_e32 v16, v16
	v_exp_f32_e32 v17, v17
	v_exp_f32_e32 v10, v10
	v_exp_f32_e32 v11, v11
	v_exp_f32_e32 v12, v12
	v_exp_f32_e32 v13, v13
	v_fma_f32 v14, v14, v231, v231
	v_fma_f32 v15, v15, v231, v231
	v_fma_f32 v16, v16, v231, v231
	v_fma_f32 v17, v17, v231, v231
	v_fma_f32 v10, v10, v231, v231
	v_fma_f32 v11, v11, v231, v231
	v_fma_f32 v12, v12, v231, v231
	v_fma_f32 v13, v13, v231, v231
	v_rcp_f32_e32 v14, v14
	v_rcp_f32_e32 v15, v15
	v_rcp_f32_e32 v16, v16
	v_rcp_f32_e32 v17, v17
	v_rcp_f32_e32 v10, v10
	v_rcp_f32_e32 v11, v11
	v_rcp_f32_e32 v12, v12
	v_rcp_f32_e32 v13, v13
	v_mul_f32_e32 v6, v6, v14
	v_mul_f32_e32 v7, v7, v15
	v_mul_f32_e32 v8, v8, v16
	v_mul_f32_e32 v9, v9, v17
	v_mul_f32_e32 v2, v2, v10
	v_mul_f32_e32 v3, v3, v11
	v_mul_f32_e32 v4, v4, v12
	v_mul_f32_e32 v5, v5, v13
	v_cvt_pk_bf16_f32 v6, v6, v7
	v_cvt_pk_bf16_f32 v7, v8, v9
	v_cvt_pk_bf16_f32 v8, v2, v3
	v_cvt_pk_bf16_f32 v9, v4, v5
	v_or_b32_e32 v226, 0xb0, v156
	v_mad_i64_i32 v[228:229], s[12:13], v226, s55, v[224:225]
	global_store_dwordx4 v[228:229], v[6:9], off
	s_cbranch_scc1 .LBB0_574
	s_andn2_b64 vcc, exec, s[6:7]
	s_cbranch_vccnz .LBB0_573
	s_barrier
	s_branch .LBB0_573

; #define PG8_STAGE(bufoff, gbase, voff) do { _Pragma("unroll") for (int _i = 0; _i < 2; ++_i) \
;         __builtin_amdgcn_global_load_lds((const unsigned*)((const char*)(gbase) + (voff)[_i]), (PG8_LAS unsigned*)(lds + (bufoff) + ldsw + _i * 8192), 16, 0, 0); } while (0)
; #define PG8_LDA(dst, b, h) do { _Pragma("unroll") for (int m = 0; m < 4; ++m) _Pragma("unroll") for (int k = 0; k < 2; ++k) dst[m][k] = *(const PG8_LAS bf16x8*)(lds + PG8_SA(b, h) + aoff + m * 2048 + k * 1024); } while (0)
; #define PG8_LDB(dst, b, h) do { _Pragma("unroll") for (int n = 0; n < 2; ++n) _Pragma("unroll") for (int k = 0; k < 2; ++k) dst[n][k] = *(const PG8_LAS bf16x8*)(lds + PG8_SB(b, h) + boff + n * 2048 + k * 1024); } while (0)
; #define PG8_MMA(ai, bj, At, Bt) do { __builtin_amdgcn_s_setprio(1); _Pragma("unroll") for (int m = 0; m < 4; ++m) _Pragma("unroll") for (int n = 0; n < 2; ++n) _Pragma("unroll") for (int k = 0; k < 2; ++k) \
;         acc[ai][bj][m][n] = __builtin_amdgcn_mfma_f32_16x16x32_bf16(Bt[n][k], At[m][k], acc[ai][bj][m][n], 0, 0, 0); __builtin_amdgcn_s_setprio(0); } while (0)
; #define PG8_WAIT_V(n) asm volatile("s_waitcnt vmcnt(" #n ")" ::: "memory")
; template <class Epi, class Sched>
; __device__ __forceinline__ void gemm_phase(PG8_LAS unsigned char* lds, const Gemm g, const Sched& S, const Epi& E) {
;     ...
;         const char* nA = has_next ? (const char*)g.A + (size_t)nxt.pm * tstepA : cA; const char* nB = has_next ? (const char*)g.Bt + (size_t)nxt.pn * tstepB : cB;
;         for (int t = 0; t < nt; t += 2) {
;             const bool last = (t == nt - 2);
;             const char* a1 = cA + (size_t)(t + 1) * kstep;
;             const char* a2 = last ? nA : cA + (size_t)(t + 2) * kstep; const char* b2 = last ? nB : cB + (size_t)(t + 2) * kstep;
;             const char* a3 = a2 + kstep; const char* b3 = b2 + kstep;
;             PG8_LDB(B0, 0, 0); PG8_LDB(B1, 0, 1); PG8_SCHED; PG8_LDA(At, 0, 0); PG8_STAGE(PG8_SA(1, 1), a1 + hstepA, voffA);
;             PG8_WAIT_V(8); PG8_WAIT_L(0); PG8_BAR; PG8_MMA(0, 0, At, B0); PG8_MMA(0, 1, At, B1); PG8_BAR; PG8_SCHED;
;             PG8_LDA(At, 0, 1); PG8_STAGE(PG8_SB(0, 0), b2, voffB); PG8_STAGE(PG8_SB(0, 1), b2 + hstepB, voffB); PG8_STAGE(PG8_SA(0, 0), a2, voffA);
;             PG8_WAIT_V(8); PG8_WAIT_L(0); PG8_BAR; PG8_MMA(1, 0, At, B0); PG8_MMA(1, 1, At, B1); PG8_BAR; PG8_SCHED;
.LBB0_666:
	s_add_u32 s19, s28, 0x100
	v_mov_b32_e32 v2, 0
	s_addc_u32 s25, s29, 0
	s_mov_b32 s33, -2
	s_add_u32 s10, s26, 0x100
	s_addc_u32 s11, s27, 0
	s_add_i32 s46, 0, 0x10000
	s_cmp_eq_u32 s33, 40
	s_cselect_b32 s31, s21, s11
	s_cselect_b32 s30, s20, s10
	s_cselect_b32 s29, s23, s25
	s_cselect_b32 s28, s22, s19
	s_add_i32 s47, 0, 0x14000
	v_add_u32_e32 v106, s46, v1
	v_add_u32_e32 v158, s47, v1
	ds_read_b128 v[90:93], v106
	ds_read_b128 v[94:97], v106 offset:1024
	ds_read_b128 v[98:101], v106 offset:2048
	ds_read_b128 v[106:109], v106 offset:3072
	ds_read_b128 v[146:149], v158
	ds_read_b128 v[150:153], v158 offset:1024
	ds_read_b128 v[154:157], v158 offset:2048
	ds_read_b128 v[158:161], v158 offset:3072
	v_lshl_add_u64 v[212:213], s[26:27], 0, v[204:205]
	s_add_i32 m0, s61, 0xc000
	ds_read_b128 v[162:165], v232
	ds_read_b128 v[166:169], v232 offset:1024
	ds_read_b128 v[170:173], v232 offset:2048
	ds_read_b128 v[174:177], v232 offset:3072
	ds_read_b128 v[208:211], v232 offset:4096
	ds_read_b128 v[214:217], v232 offset:5120
	ds_read_b128 v[218:221], v232 offset:6144
	ds_read_b128 v[222:225], v232 offset:7168
	global_load_lds_dwordx4 v[212:213], off
	v_lshl_add_u64 v[212:213], s[26:27], 0, v[206:207]
	s_add_i32 m0, s61, 0xe000
	s_nop 0
	global_load_lds_dwordx4 v[212:213], off
	s_waitcnt vmcnt(8)
	s_waitcnt lgkmcnt(0)
	s_barrier
	s_setprio 1
	s_waitcnt lgkmcnt(0)
	v_mfma_f32_16x16x32_bf16 v[142:145], v[90:93], v[162:165], 0
	v_mfma_f32_16x16x32_bf16 v[138:141], v[98:101], v[162:165], 0
	v_mfma_f32_16x16x32_bf16 v[126:129], v[90:93], v[170:173], 0
	v_mfma_f32_16x16x32_bf16 v[122:125], v[98:101], v[170:173], 0
	v_mfma_f32_16x16x32_bf16 v[110:113], v[90:93], v[208:211], 0
	v_mfma_f32_16x16x32_bf16 v[102:105], v[98:101], v[208:211], 0
	v_mfma_f32_16x16x32_bf16 v[78:81], v[90:93], v[218:221], 0
	v_mfma_f32_16x16x32_bf16 v[74:77], v[98:101], v[218:221], 0
	v_mfma_f32_16x16x32_bf16 v[142:145], v[94:97], v[166:169], v[142:145]
	v_mfma_f32_16x16x32_bf16 v[138:141], v[106:109], v[166:169], v[138:141]
	v_mfma_f32_16x16x32_bf16 v[126:129], v[94:97], v[174:177], v[126:129]
	v_mfma_f32_16x16x32_bf16 v[122:125], v[106:109], v[174:177], v[122:125]
	v_mfma_f32_16x16x32_bf16 v[110:113], v[94:97], v[214:217], v[110:113]
	v_mfma_f32_16x16x32_bf16 v[102:105], v[106:109], v[214:217], v[102:105]
	v_mfma_f32_16x16x32_bf16 v[78:81], v[94:97], v[222:225], v[78:81]
	v_mfma_f32_16x16x32_bf16 v[74:77], v[106:109], v[222:225], v[74:77]
	s_setprio 0
	s_setprio 1
	v_mfma_f32_16x16x32_bf16 v[134:137], v[146:149], v[162:165], 0
	v_mfma_f32_16x16x32_bf16 v[130:133], v[154:157], v[162:165], 0
	v_mfma_f32_16x16x32_bf16 v[118:121], v[146:149], v[170:173], 0
	v_mfma_f32_16x16x32_bf16 v[114:117], v[154:157], v[170:173], 0
	v_mfma_f32_16x16x32_bf16 v[86:89], v[146:149], v[208:211], 0
	v_mfma_f32_16x16x32_bf16 v[82:85], v[154:157], v[208:211], 0
	v_mfma_f32_16x16x32_bf16 v[70:73], v[146:149], v[218:221], 0
	v_mfma_f32_16x16x32_bf16 v[66:69], v[154:157], v[218:221], 0
	v_mfma_f32_16x16x32_bf16 v[134:137], v[150:153], v[166:169], v[134:137]
	v_mfma_f32_16x16x32_bf16 v[130:133], v[158:161], v[166:169], v[130:133]
	v_mfma_f32_16x16x32_bf16 v[118:121], v[150:153], v[174:177], v[118:121]
	v_mfma_f32_16x16x32_bf16 v[114:117], v[158:161], v[174:177], v[114:117]
	v_mfma_f32_16x16x32_bf16 v[86:89], v[150:153], v[214:217], v[86:89]
	v_mfma_f32_16x16x32_bf16 v[82:85], v[158:161], v[214:217], v[82:85]
	v_mfma_f32_16x16x32_bf16 v[70:73], v[150:153], v[222:225], v[70:73]
	v_mfma_f32_16x16x32_bf16 v[66:69], v[158:161], v[222:225], v[66:69]
	s_setprio 0
	s_barrier
	s_add_i32 s26, s46, s60
	v_lshl_add_u64 v[212:213], s[28:29], 0, v[182:183]
	s_mov_b32 m0, s26
	ds_read_b128 v[162:165], v232 offset:16384
	ds_read_b128 v[166:169], v232 offset:17408
	ds_read_b128 v[170:173], v232 offset:18432
	ds_read_b128 v[174:177], v232 offset:19456
	ds_read_b128 v[208:211], v232 offset:20480
	ds_read_b128 v[214:217], v232 offset:21504
	ds_read_b128 v[218:221], v232 offset:22528
	ds_read_b128 v[222:225], v232 offset:23552
	global_load_lds_dwordx4 v[212:213], off
	s_add_i32 m0, s26, 0x2000
	s_add_u32 s26, s28, 0xb0000
	v_lshl_add_u64 v[226:227], s[28:29], 0, v[178:179]
	s_addc_u32 s27, s29, 0
	s_add_i32 s46, s47, s60
	global_load_lds_dwordx4 v[226:227], off
	v_lshl_add_u64 v[242:243], s[26:27], 0, v[182:183]
	s_mov_b32 m0, s46
	v_lshl_add_u64 v[246:247], s[30:31], 0, v[180:181]
	global_load_lds_dwordx4 v[242:243], off
	v_lshl_add_u64 v[242:243], s[26:27], 0, v[178:179]
	s_add_i32 m0, s46, 0x2000
	s_nop 0
	global_load_lds_dwordx4 v[242:243], off
	v_lshl_add_u64 v[242:243], s[30:31], 0, v[184:185]
	s_mov_b32 m0, s61
	s_nop 0
	global_load_lds_dwordx4 v[242:243], off
	s_mov_b32 m0, s70
	s_nop 0
	global_load_lds_dwordx4 v[246:247], off
	s_waitcnt vmcnt(8)
	s_waitcnt lgkmcnt(0)
	s_barrier
	s_setprio 1
	s_waitcnt lgkmcnt(0)
	v_mfma_f32_16x16x32_bf16 v[62:65], v[90:93], v[162:165], 0
	v_mfma_f32_16x16x32_bf16 v[58:61], v[98:101], v[162:165], 0
	v_mfma_f32_16x16x32_bf16 v[46:49], v[90:93], v[170:173], 0
	v_mfma_f32_16x16x32_bf16 v[42:45], v[98:101], v[170:173], 0
	v_mfma_f32_16x16x32_bf16 v[30:33], v[90:93], v[208:211], 0
	v_mfma_f32_16x16x32_bf16 v[26:29], v[98:101], v[208:211], 0
	v_mfma_f32_16x16x32_bf16 v[14:17], v[90:93], v[218:221], 0
	v_mfma_f32_16x16x32_bf16 v[10:13], v[98:101], v[218:221], 0
	v_mfma_f32_16x16x32_bf16 v[62:65], v[94:97], v[166:169], v[62:65]
	v_mfma_f32_16x16x32_bf16 v[58:61], v[106:109], v[166:169], v[58:61]
	v_mfma_f32_16x16x32_bf16 v[46:49], v[94:97], v[174:177], v[46:49]
	v_mfma_f32_16x16x32_bf16 v[42:45], v[106:109], v[174:177], v[42:45]
	v_mfma_f32_16x16x32_bf16 v[30:33], v[94:97], v[214:217], v[30:33]
	v_mfma_f32_16x16x32_bf16 v[26:29], v[106:109], v[214:217], v[26:29]
	v_mfma_f32_16x16x32_bf16 v[14:17], v[94:97], v[222:225], v[14:17]
	v_mfma_f32_16x16x32_bf16 v[10:13], v[106:109], v[222:225], v[10:13]
	s_setprio 0
	s_setprio 1
	v_mfma_f32_16x16x32_bf16 v[54:57], v[146:149], v[162:165], 0
	v_mfma_f32_16x16x32_bf16 v[50:53], v[154:157], v[162:165], 0
	v_mfma_f32_16x16x32_bf16 v[38:41], v[146:149], v[170:173], 0
	v_mfma_f32_16x16x32_bf16 v[34:37], v[154:157], v[170:173], 0
	v_mfma_f32_16x16x32_bf16 v[22:25], v[146:149], v[208:211], 0
	v_mfma_f32_16x16x32_bf16 v[18:21], v[154:157], v[208:211], 0
	v_mfma_f32_16x16x32_bf16 v[6:9], v[146:149], v[218:221], 0
	v_mfma_f32_16x16x32_bf16 v[2:5], v[154:157], v[218:221], 0
	v_mfma_f32_16x16x32_bf16 v[54:57], v[150:153], v[166:169], v[54:57]
	v_mfma_f32_16x16x32_bf16 v[50:53], v[158:161], v[166:169], v[50:53]
	v_mfma_f32_16x16x32_bf16 v[38:41], v[150:153], v[174:177], v[38:41]
	v_mfma_f32_16x16x32_bf16 v[34:37], v[158:161], v[174:177], v[34:37]
	v_mfma_f32_16x16x32_bf16 v[22:25], v[150:153], v[214:217], v[22:25]
	v_mfma_f32_16x16x32_bf16 v[18:21], v[158:161], v[214:217], v[18:21]
	v_mfma_f32_16x16x32_bf16 v[6:9], v[150:153], v[222:225], v[6:9]
	v_mfma_f32_16x16x32_bf16 v[2:5], v[158:161], v[222:225], v[2:5]
	s_setprio 0
	s_barrier
	s_branch .Lpeel_mid_667

; #define PG8_STAGE(bufoff, gbase, voff) do { _Pragma("unroll") for (int _i = 0; _i < 2; ++_i) \
;         __builtin_amdgcn_global_load_lds((const unsigned*)((const char*)(gbase) + (voff)[_i]), (PG8_LAS unsigned*)(lds + (bufoff) + ldsw + _i * 8192), 16, 0, 0); } while (0)
; #define PG8_LDA(dst, b, h) do { _Pragma("unroll") for (int m = 0; m < 4; ++m) _Pragma("unroll") for (int k = 0; k < 2; ++k) dst[m][k] = *(const PG8_LAS bf16x8*)(lds + PG8_SA(b, h) + aoff + m * 2048 + k * 1024); } while (0)
; #define PG8_LDB(dst, b, h) do { _Pragma("unroll") for (int n = 0; n < 2; ++n) _Pragma("unroll") for (int k = 0; k < 2; ++k) dst[n][k] = *(const PG8_LAS bf16x8*)(lds + PG8_SB(b, h) + boff + n * 2048 + k * 1024); } while (0)
; #define PG8_MMA(ai, bj, At, Bt) do { __builtin_amdgcn_s_setprio(1); _Pragma("unroll") for (int m = 0; m < 4; ++m) _Pragma("unroll") for (int n = 0; n < 2; ++n) _Pragma("unroll") for (int k = 0; k < 2; ++k) \
;         acc[ai][bj][m][n] = __builtin_amdgcn_mfma_f32_16x16x32_bf16(Bt[n][k], At[m][k], acc[ai][bj][m][n], 0, 0, 0); __builtin_amdgcn_s_setprio(0); } while (0)
; #define PG8_WAIT_V(n) asm volatile("s_waitcnt vmcnt(" #n ")" ::: "memory")
; #define PG8_WAIT_L(n) asm volatile("s_waitcnt lgkmcnt(" #n ")" ::: "memory")
; #define PG8_BAR __builtin_amdgcn_s_barrier()
; #define PG8_SCHED __builtin_amdgcn_sched_barrier(0)
; template <class Epi, class Sched>
; __device__ __forceinline__ void gemm_phase(PG8_LAS unsigned char* lds, const Gemm g, const Sched& S, const Epi& E) {
;     ...
;             PG8_LDB(B0, 1, 0); PG8_LDB(B1, 1, 1); PG8_SCHED; PG8_LDA(At, 1, 0); PG8_STAGE(PG8_SA(0, 1), a2 + hstepA, voffA);
;             PG8_WAIT_V(8); PG8_WAIT_L(0); PG8_BAR; PG8_MMA(0, 0, At, B0); PG8_MMA(0, 1, At, B1); PG8_BAR; PG8_SCHED;
.Lpeel_mid_667:
	s_add_i32 s46, 0, 0x18000
	s_add_i32 s47, 0, 0x1c000
	v_add_u32_e32 v106, s46, v1
	v_add_u32_e32 v158, s47, v1
	ds_read_b128 v[90:93], v106
	ds_read_b128 v[94:97], v106 offset:1024
	ds_read_b128 v[98:101], v106 offset:2048
	ds_read_b128 v[106:109], v106 offset:3072
	ds_read_b128 v[146:149], v158
	ds_read_b128 v[150:153], v158 offset:1024
	ds_read_b128 v[154:157], v158 offset:2048
	ds_read_b128 v[158:161], v158 offset:3072
	s_add_u32 s26, s30, 0xb0000
	s_addc_u32 s27, s31, 0
	s_mov_b32 m0, s71
	v_lshl_add_u64 v[250:251], s[26:27], 0, v[184:185]
	ds_read_b128 v[162:165], v232 offset:32768
	ds_read_b128 v[166:169], v232 offset:33792
	ds_read_b128 v[170:173], v232 offset:34816
	ds_read_b128 v[174:177], v232 offset:35840
	ds_read_b128 v[208:211], v232 offset:36864
	ds_read_b128 v[214:217], v232 offset:37888
	ds_read_b128 v[218:221], v232 offset:38912
	ds_read_b128 v[222:225], v232 offset:39936
	global_load_lds_dwordx4 v[250:251], off
	v_lshl_add_u64 v[250:251], s[26:27], 0, v[180:181]
	s_mov_b32 m0, s74
	s_nop 0
	global_load_lds_dwordx4 v[250:251], off
	s_waitcnt vmcnt(8)
	s_waitcnt lgkmcnt(0)
	s_barrier
	s_setprio 1
	s_waitcnt lgkmcnt(0)
	v_mfma_f32_16x16x32_bf16 v[142:145], v[90:93], v[162:165], v[142:145]
	v_mfma_f32_16x16x32_bf16 v[138:141], v[98:101], v[162:165], v[138:141]
	v_mfma_f32_16x16x32_bf16 v[126:129], v[90:93], v[170:173], v[126:129]
	v_mfma_f32_16x16x32_bf16 v[122:125], v[98:101], v[170:173], v[122:125]
	v_mfma_f32_16x16x32_bf16 v[110:113], v[90:93], v[208:211], v[110:113]
	v_mfma_f32_16x16x32_bf16 v[102:105], v[98:101], v[208:211], v[102:105]
	v_mfma_f32_16x16x32_bf16 v[78:81], v[90:93], v[218:221], v[78:81]
	v_mfma_f32_16x16x32_bf16 v[74:77], v[98:101], v[218:221], v[74:77]
	v_mfma_f32_16x16x32_bf16 v[142:145], v[94:97], v[166:169], v[142:145]
	v_mfma_f32_16x16x32_bf16 v[138:141], v[106:109], v[166:169], v[138:141]
	v_mfma_f32_16x16x32_bf16 v[126:129], v[94:97], v[174:177], v[126:129]
	v_mfma_f32_16x16x32_bf16 v[122:125], v[106:109], v[174:177], v[122:125]
	v_mfma_f32_16x16x32_bf16 v[110:113], v[94:97], v[214:217], v[110:113]
	v_mfma_f32_16x16x32_bf16 v[102:105], v[106:109], v[214:217], v[102:105]
	v_mfma_f32_16x16x32_bf16 v[78:81], v[94:97], v[222:225], v[78:81]
	v_mfma_f32_16x16x32_bf16 v[74:77], v[106:109], v[222:225], v[74:77]
	s_setprio 0
	s_setprio 1
	v_mfma_f32_16x16x32_bf16 v[134:137], v[146:149], v[162:165], v[134:137]
	v_mfma_f32_16x16x32_bf16 v[130:133], v[154:157], v[162:165], v[130:133]
	v_mfma_f32_16x16x32_bf16 v[118:121], v[146:149], v[170:173], v[118:121]
	v_mfma_f32_16x16x32_bf16 v[114:117], v[154:157], v[170:173], v[114:117]
	v_mfma_f32_16x16x32_bf16 v[86:89], v[146:149], v[208:211], v[86:89]
	v_mfma_f32_16x16x32_bf16 v[82:85], v[154:157], v[208:211], v[82:85]
	v_mfma_f32_16x16x32_bf16 v[70:73], v[146:149], v[218:221], v[70:73]
	v_mfma_f32_16x16x32_bf16 v[66:69], v[154:157], v[218:221], v[66:69]
	v_mfma_f32_16x16x32_bf16 v[134:137], v[150:153], v[166:169], v[134:137]
	v_mfma_f32_16x16x32_bf16 v[130:133], v[158:161], v[166:169], v[130:133]
	v_mfma_f32_16x16x32_bf16 v[118:121], v[150:153], v[174:177], v[118:121]
	v_mfma_f32_16x16x32_bf16 v[114:117], v[158:161], v[174:177], v[114:117]
	v_mfma_f32_16x16x32_bf16 v[86:89], v[150:153], v[214:217], v[86:89]
	v_mfma_f32_16x16x32_bf16 v[82:85], v[158:161], v[214:217], v[82:85]
	v_mfma_f32_16x16x32_bf16 v[70:73], v[150:153], v[222:225], v[70:73]
	v_mfma_f32_16x16x32_bf16 v[66:69], v[158:161], v[222:225], v[66:69]
	s_setprio 0
	s_barrier
; #define PG8_STAGE(bufoff, gbase, voff) do { _Pragma("unroll") for (int _i = 0; _i < 2; ++_i) \
;         __builtin_amdgcn_global_load_lds((const unsigned*)((const char*)(gbase) + (voff)[_i]), (PG8_LAS unsigned*)(lds + (bufoff) + ldsw + _i * 8192), 16, 0, 0); } while (0)
; #define PG8_LDA(dst, b, h) do { _Pragma("unroll") for (int m = 0; m < 4; ++m) _Pragma("unroll") for (int k = 0; k < 2; ++k) dst[m][k] = *(const PG8_LAS bf16x8*)(lds + PG8_SA(b, h) + aoff + m * 2048 + k * 1024); } while (0)
; #define PG8_MMA(ai, bj, At, Bt) do { __builtin_amdgcn_s_setprio(1); _Pragma("unroll") for (int m = 0; m < 4; ++m) _Pragma("unroll") for (int n = 0; n < 2; ++n) _Pragma("unroll") for (int k = 0; k < 2; ++k) \
;         acc[ai][bj][m][n] = __builtin_amdgcn_mfma_f32_16x16x32_bf16(Bt[n][k], At[m][k], acc[ai][bj][m][n], 0, 0, 0); __builtin_amdgcn_s_setprio(0); } while (0)
; #define PG8_WAIT_V(n) asm volatile("s_waitcnt vmcnt(" #n ")" ::: "memory")
; #define PG8_WAIT_L(n) asm volatile("s_waitcnt lgkmcnt(" #n ")" ::: "memory")
; #define PG8_BAR __builtin_amdgcn_s_barrier()
; #define PG8_SCHED __builtin_amdgcn_sched_barrier(0)
; template <class Epi, class Sched>
; __device__ __forceinline__ void gemm_phase(PG8_LAS unsigned char* lds, const Gemm g, const Sched& S, const Epi& E) {
;     ...
;             PG8_LDA(At, 1, 1); PG8_STAGE(PG8_SB(1, 0), b3, voffB); PG8_STAGE(PG8_SB(1, 1), b3 + hstepB, voffB); PG8_STAGE(PG8_SA(1, 0), a3, voffA);
;             PG8_WAIT_V(8); PG8_WAIT_L(0); PG8_BAR; PG8_MMA(1, 0, At, B0); PG8_MMA(1, 1, At, B1); PG8_BAR; PG8_SCHED;
;         }
;         if (wr == 0) PG8_BAR;
	s_add_i32 s26, s46, s60
	v_lshl_add_u64 v[212:213], v[212:213], 0, s[78:79]
	s_mov_b32 m0, s26
	ds_read_b128 v[162:165], v232 offset:49152
	ds_read_b128 v[166:169], v232 offset:50176
	ds_read_b128 v[170:173], v232 offset:51200
	ds_read_b128 v[174:177], v232 offset:52224
	ds_read_b128 v[208:211], v232 offset:53248
	ds_read_b128 v[214:217], v232 offset:54272
	ds_read_b128 v[218:221], v232 offset:55296
	ds_read_b128 v[222:225], v232 offset:56320
	global_load_lds_dwordx4 v[212:213], off
	s_add_i32 m0, s26, 0x2000
	s_add_u32 s26, s28, 0xb0080
	v_lshl_add_u64 v[212:213], v[226:227], 0, s[78:79]
	s_addc_u32 s27, s29, 0
	s_add_i32 s28, s47, s60
	global_load_lds_dwordx4 v[212:213], off
	v_lshl_add_u64 v[212:213], s[26:27], 0, v[182:183]
	s_mov_b32 m0, s28
	s_nop 0
	global_load_lds_dwordx4 v[212:213], off
	v_lshl_add_u64 v[212:213], s[26:27], 0, v[178:179]
	s_add_i32 m0, s28, 0x2000
	s_nop 0
	global_load_lds_dwordx4 v[212:213], off
	v_lshl_add_u64 v[212:213], v[242:243], 0, s[78:79]
	s_mov_b32 m0, s75
	s_nop 0
	global_load_lds_dwordx4 v[212:213], off
	v_lshl_add_u64 v[212:213], v[246:247], 0, s[78:79]
	s_mov_b32 m0, s82
	s_nop 0
	global_load_lds_dwordx4 v[212:213], off
	s_waitcnt vmcnt(8)
	s_waitcnt lgkmcnt(0)
	s_barrier
	s_setprio 1
	s_waitcnt lgkmcnt(0)
	v_mfma_f32_16x16x32_bf16 v[62:65], v[90:93], v[162:165], v[62:65]
	v_mfma_f32_16x16x32_bf16 v[58:61], v[98:101], v[162:165], v[58:61]
	v_mfma_f32_16x16x32_bf16 v[46:49], v[90:93], v[170:173], v[46:49]
	v_mfma_f32_16x16x32_bf16 v[42:45], v[98:101], v[170:173], v[42:45]
	v_mfma_f32_16x16x32_bf16 v[30:33], v[90:93], v[208:211], v[30:33]
	v_mfma_f32_16x16x32_bf16 v[26:29], v[98:101], v[208:211], v[26:29]
	v_mfma_f32_16x16x32_bf16 v[14:17], v[90:93], v[218:221], v[14:17]
	v_mfma_f32_16x16x32_bf16 v[10:13], v[98:101], v[218:221], v[10:13]
	v_mfma_f32_16x16x32_bf16 v[62:65], v[94:97], v[166:169], v[62:65]
	v_mfma_f32_16x16x32_bf16 v[58:61], v[106:109], v[166:169], v[58:61]
	v_mfma_f32_16x16x32_bf16 v[46:49], v[94:97], v[174:177], v[46:49]
	v_mfma_f32_16x16x32_bf16 v[42:45], v[106:109], v[174:177], v[42:45]
	v_mfma_f32_16x16x32_bf16 v[30:33], v[94:97], v[214:217], v[30:33]
	v_mfma_f32_16x16x32_bf16 v[26:29], v[106:109], v[214:217], v[26:29]
	v_mfma_f32_16x16x32_bf16 v[14:17], v[94:97], v[222:225], v[14:17]
	v_mfma_f32_16x16x32_bf16 v[10:13], v[106:109], v[222:225], v[10:13]
	s_setprio 0
	s_setprio 1
	v_mfma_f32_16x16x32_bf16 v[54:57], v[146:149], v[162:165], v[54:57]
	v_mfma_f32_16x16x32_bf16 v[50:53], v[154:157], v[162:165], v[50:53]
	v_mfma_f32_16x16x32_bf16 v[38:41], v[146:149], v[170:173], v[38:41]
	v_mfma_f32_16x16x32_bf16 v[34:37], v[154:157], v[170:173], v[34:37]
	v_mfma_f32_16x16x32_bf16 v[22:25], v[146:149], v[208:211], v[22:25]
	v_mfma_f32_16x16x32_bf16 v[18:21], v[154:157], v[208:211], v[18:21]
	v_mfma_f32_16x16x32_bf16 v[6:9], v[146:149], v[218:221], v[6:9]
	v_mfma_f32_16x16x32_bf16 v[2:5], v[154:157], v[218:221], v[2:5]
	v_mfma_f32_16x16x32_bf16 v[54:57], v[150:153], v[166:169], v[54:57]
	v_mfma_f32_16x16x32_bf16 v[50:53], v[158:161], v[166:169], v[50:53]
	v_mfma_f32_16x16x32_bf16 v[38:41], v[150:153], v[174:177], v[38:41]
	v_mfma_f32_16x16x32_bf16 v[34:37], v[158:161], v[174:177], v[34:37]
	v_mfma_f32_16x16x32_bf16 v[22:25], v[150:153], v[214:217], v[22:25]
	v_mfma_f32_16x16x32_bf16 v[18:21], v[158:161], v[214:217], v[18:21]
	v_mfma_f32_16x16x32_bf16 v[6:9], v[150:153], v[222:225], v[6:9]
	v_mfma_f32_16x16x32_bf16 v[2:5], v[158:161], v[222:225], v[2:5]
	s_setprio 0
	s_barrier
	s_add_i32 s33, s33, 2
	s_add_u32 s19, s19, 0x100
	s_addc_u32 s25, s25, 0
	s_cmp_gt_u32 s33, 41
	s_mov_b64 s[26:27], s[10:11]
	s_cbranch_scc0 .LBB0_667
	s_and_b64 vcc, exec, s[16:17]
	s_cbranch_vccz .LBB0_670
	s_barrier
